# SSD / RG-LRU local items: causal-conv straight path (all taps in range) loads a tap's row segments and weight vectors together before its FMAs instead of 16 serialised load-wait-FMA blocks
# speedup vs baseline: 1.0061x; 1.0061x over previous
.LBB0_881:
	v_mov_b32_e32 v160, v185
	s_bfe_u32 s14, s34, 0x60002
	s_ashr_i32 s15, s34, 8
	s_lshl_b32 s0, s15, 13
	s_lshl_b32 s1, s14, 7
	v_ashrrev_i32_e32 v36, 1, v160
	s_or_b32 s52, s1, s0
	s_waitcnt vmcnt(63) expcnt(7) lgkmcnt(15)
	s_barrier
	v_add_u32_e32 v10, s1, v36
	s_load_dwordx4 s[0:3], s[54:55], 0x80
	s_and_b32 s4, s34, 3
	s_lshl_b32 s74, s4, 6
	v_lshlrev_b32_e32 v0, 5, v160
	v_and_b32_e32 v37, 32, v0
	s_waitcnt lgkmcnt(0)
	s_add_u32 s0, s0, s18
	s_addc_u32 s1, s1, s19
	v_or_b32_e32 v0, s74, v37
	s_add_u32 s2, s2, s60
	s_addc_u32 s3, s3, s61
	v_lshlrev_b32_e32 v168, 2, v0
	v_lshlrev_b32_e32 v0, 1, v0
	v_mov_b32_e32 v1, v169
	v_lshl_add_u64 v[34:35], s[82:83], 0, v[0:1]
	global_load_dwordx4 v[0:3], v168, s[2:3] offset:16
	global_load_dwordx4 v[4:7], v168, s[2:3]
	v_add_u32_e32 v38, s52, v36
	v_lshl_add_u64 v[32:33], s[0:1], 0, v[168:169]
	s_mov_b64 s[0:1], 0x6bb9a00
	v_add_u32_e32 v39, -3, v38
	v_lshl_add_u64 v[8:9], v[34:35], 0, s[0:1]
	v_cmp_lt_i32_e32 vcc, 2, v10
	s_cmp_eq_u64 vcc, -1
	s_cbranch_scc0 .Llru_slow
	v_mov_b32_e32 v48, v8
	v_mov_b32_e32 v49, v9
	global_load_dwordx4 v[12:15], v168, s[2:3] offset:32
	global_load_dwordx4 v[8:11], v168, s[2:3] offset:48
	global_load_dwordx4 v[20:23], v168, s[2:3] offset:64
	global_load_dwordx4 v[16:19], v168, s[2:3] offset:80
	global_load_dwordx4 v[28:31], v168, s[2:3] offset:96
	global_load_dwordx4 v[24:27], v168, s[2:3] offset:112
	v_add_u32_e32 v40, -2, v38
	v_add_u32_e32 v41, -1, v38
	v_mad_i64_i32 v[50:51], s[0:1], v39, s93, v[48:49]
	v_mad_i64_i32 v[52:53], s[0:1], v40, s93, v[48:49]
	v_mad_i64_i32 v[54:55], s[0:1], v41, s93, v[48:49]
	v_mad_i64_i32 v[56:57], s[0:1], v38, s93, v[48:49]
	global_load_dwordx4 v[58:61], v[50:51], off
	global_load_dwordx4 v[62:65], v[50:51], off offset:16
	global_load_dwordx4 v[66:69], v[50:51], off offset:32
	global_load_dwordx4 v[70:73], v[50:51], off offset:48
	global_load_dwordx4 v[90:93], v[32:33], off
	global_load_dwordx4 v[94:97], v[32:33], off offset:16
	global_load_dwordx4 v[98:101], v[32:33], off offset:32
	global_load_dwordx4 v[102:105], v[32:33], off offset:48
	global_load_dwordx4 v[106:109], v[32:33], off offset:64
	global_load_dwordx4 v[110:113], v[32:33], off offset:80
	global_load_dwordx4 v[114:117], v[32:33], off offset:96
	global_load_dwordx4 v[118:121], v[32:33], off offset:112
	global_load_dwordx4 v[74:77], v[52:53], off
	global_load_dwordx4 v[78:81], v[52:53], off offset:16
	global_load_dwordx4 v[82:85], v[52:53], off offset:32
	global_load_dwordx4 v[86:89], v[52:53], off offset:48
	global_load_dwordx4 v[122:125], v[32:33], off offset:1024
	global_load_dwordx4 v[126:129], v[32:33], off offset:1040
	global_load_dwordx4 v[130:133], v[32:33], off offset:1056
	global_load_dwordx4 v[134:137], v[32:33], off offset:1072
	global_load_dwordx4 v[138:141], v[32:33], off offset:1088
	global_load_dwordx4 v[142:145], v[32:33], off offset:1104
	global_load_dwordx4 v[146:149], v[32:33], off offset:1120
	global_load_dwordx4 v[150:153], v[32:33], off offset:1136
	s_waitcnt vmcnt(0)
	v_lshlrev_b32_e32 v154, 16, v58
	v_and_b32_e32 v155, 0xffff0000, v58
	v_pk_fma_f32 v[4:5], v[90:91], v[154:155], v[4:5]
	v_lshlrev_b32_e32 v154, 16, v59
	v_and_b32_e32 v155, 0xffff0000, v59
	v_pk_fma_f32 v[6:7], v[92:93], v[154:155], v[6:7]
	v_lshlrev_b32_e32 v154, 16, v60
	v_and_b32_e32 v155, 0xffff0000, v60
	v_pk_fma_f32 v[0:1], v[94:95], v[154:155], v[0:1]
	v_lshlrev_b32_e32 v154, 16, v61
	v_and_b32_e32 v155, 0xffff0000, v61
	v_pk_fma_f32 v[2:3], v[96:97], v[154:155], v[2:3]
	v_lshlrev_b32_e32 v154, 16, v74
	v_and_b32_e32 v155, 0xffff0000, v74
	v_pk_fma_f32 v[4:5], v[122:123], v[154:155], v[4:5]
	v_lshlrev_b32_e32 v154, 16, v75
	v_and_b32_e32 v155, 0xffff0000, v75
	v_pk_fma_f32 v[6:7], v[124:125], v[154:155], v[6:7]
	v_lshlrev_b32_e32 v154, 16, v76
	v_and_b32_e32 v155, 0xffff0000, v76
	v_pk_fma_f32 v[0:1], v[126:127], v[154:155], v[0:1]
	v_lshlrev_b32_e32 v154, 16, v77
	v_and_b32_e32 v155, 0xffff0000, v77
	v_pk_fma_f32 v[2:3], v[128:129], v[154:155], v[2:3]
	v_lshlrev_b32_e32 v154, 16, v62
	v_and_b32_e32 v155, 0xffff0000, v62
	v_pk_fma_f32 v[12:13], v[98:99], v[154:155], v[12:13]
	v_lshlrev_b32_e32 v154, 16, v63
	v_and_b32_e32 v155, 0xffff0000, v63
	v_pk_fma_f32 v[14:15], v[100:101], v[154:155], v[14:15]
	v_lshlrev_b32_e32 v154, 16, v64
	v_and_b32_e32 v155, 0xffff0000, v64
	v_pk_fma_f32 v[8:9], v[102:103], v[154:155], v[8:9]
	v_lshlrev_b32_e32 v154, 16, v65
	v_and_b32_e32 v155, 0xffff0000, v65
	v_pk_fma_f32 v[10:11], v[104:105], v[154:155], v[10:11]
	v_lshlrev_b32_e32 v154, 16, v78
	v_and_b32_e32 v155, 0xffff0000, v78
	v_pk_fma_f32 v[12:13], v[130:131], v[154:155], v[12:13]
	v_lshlrev_b32_e32 v154, 16, v79
	v_and_b32_e32 v155, 0xffff0000, v79
	v_pk_fma_f32 v[14:15], v[132:133], v[154:155], v[14:15]
	v_lshlrev_b32_e32 v154, 16, v80
	v_and_b32_e32 v155, 0xffff0000, v80
	v_pk_fma_f32 v[8:9], v[134:135], v[154:155], v[8:9]
	v_lshlrev_b32_e32 v154, 16, v81
	v_and_b32_e32 v155, 0xffff0000, v81
	v_pk_fma_f32 v[10:11], v[136:137], v[154:155], v[10:11]
	v_lshlrev_b32_e32 v154, 16, v66
	v_and_b32_e32 v155, 0xffff0000, v66
	v_pk_fma_f32 v[20:21], v[106:107], v[154:155], v[20:21]
	v_lshlrev_b32_e32 v154, 16, v67
	v_and_b32_e32 v155, 0xffff0000, v67
	v_pk_fma_f32 v[22:23], v[108:109], v[154:155], v[22:23]
	v_lshlrev_b32_e32 v154, 16, v68
	v_and_b32_e32 v155, 0xffff0000, v68
	v_pk_fma_f32 v[16:17], v[110:111], v[154:155], v[16:17]
	v_lshlrev_b32_e32 v154, 16, v69
	v_and_b32_e32 v155, 0xffff0000, v69
	v_pk_fma_f32 v[18:19], v[112:113], v[154:155], v[18:19]
	v_lshlrev_b32_e32 v154, 16, v82
	v_and_b32_e32 v155, 0xffff0000, v82
	v_pk_fma_f32 v[20:21], v[138:139], v[154:155], v[20:21]
	v_lshlrev_b32_e32 v154, 16, v83
	v_and_b32_e32 v155, 0xffff0000, v83
	v_pk_fma_f32 v[22:23], v[140:141], v[154:155], v[22:23]
	v_lshlrev_b32_e32 v154, 16, v84
	v_and_b32_e32 v155, 0xffff0000, v84
	v_pk_fma_f32 v[16:17], v[142:143], v[154:155], v[16:17]
	v_lshlrev_b32_e32 v154, 16, v85
	v_and_b32_e32 v155, 0xffff0000, v85
	v_pk_fma_f32 v[18:19], v[144:145], v[154:155], v[18:19]
	v_lshlrev_b32_e32 v154, 16, v70
	v_and_b32_e32 v155, 0xffff0000, v70
	v_pk_fma_f32 v[28:29], v[114:115], v[154:155], v[28:29]
	v_lshlrev_b32_e32 v154, 16, v71
	v_and_b32_e32 v155, 0xffff0000, v71
	v_pk_fma_f32 v[30:31], v[116:117], v[154:155], v[30:31]
	v_lshlrev_b32_e32 v154, 16, v72
	v_and_b32_e32 v155, 0xffff0000, v72
	v_pk_fma_f32 v[24:25], v[118:119], v[154:155], v[24:25]
	v_lshlrev_b32_e32 v154, 16, v73
	v_and_b32_e32 v155, 0xffff0000, v73
	v_pk_fma_f32 v[26:27], v[120:121], v[154:155], v[26:27]
	v_lshlrev_b32_e32 v154, 16, v86
	v_and_b32_e32 v155, 0xffff0000, v86
	v_pk_fma_f32 v[28:29], v[146:147], v[154:155], v[28:29]
	v_lshlrev_b32_e32 v154, 16, v87
	v_and_b32_e32 v155, 0xffff0000, v87
	v_pk_fma_f32 v[30:31], v[148:149], v[154:155], v[30:31]
	v_lshlrev_b32_e32 v154, 16, v88
	v_and_b32_e32 v155, 0xffff0000, v88
	v_pk_fma_f32 v[24:25], v[150:151], v[154:155], v[24:25]
	v_lshlrev_b32_e32 v154, 16, v89
	v_and_b32_e32 v155, 0xffff0000, v89
	v_pk_fma_f32 v[26:27], v[152:153], v[154:155], v[26:27]
	global_load_dwordx4 v[58:61], v[54:55], off
	global_load_dwordx4 v[62:65], v[54:55], off offset:16
	global_load_dwordx4 v[66:69], v[54:55], off offset:32
	global_load_dwordx4 v[70:73], v[54:55], off offset:48
	global_load_dwordx4 v[90:93], v[32:33], off offset:2048
	global_load_dwordx4 v[94:97], v[32:33], off offset:2064
	global_load_dwordx4 v[98:101], v[32:33], off offset:2080
	global_load_dwordx4 v[102:105], v[32:33], off offset:2096
	global_load_dwordx4 v[106:109], v[32:33], off offset:2112
	global_load_dwordx4 v[110:113], v[32:33], off offset:2128
	global_load_dwordx4 v[114:117], v[32:33], off offset:2144
	global_load_dwordx4 v[118:121], v[32:33], off offset:2160
	global_load_dwordx4 v[74:77], v[56:57], off
	global_load_dwordx4 v[78:81], v[56:57], off offset:16
	global_load_dwordx4 v[82:85], v[56:57], off offset:32
	global_load_dwordx4 v[86:89], v[56:57], off offset:48
	global_load_dwordx4 v[122:125], v[32:33], off offset:3072
	global_load_dwordx4 v[126:129], v[32:33], off offset:3088
	global_load_dwordx4 v[130:133], v[32:33], off offset:3104
	global_load_dwordx4 v[134:137], v[32:33], off offset:3120
	global_load_dwordx4 v[138:141], v[32:33], off offset:3136
	global_load_dwordx4 v[142:145], v[32:33], off offset:3152
	global_load_dwordx4 v[146:149], v[32:33], off offset:3168
	global_load_dwordx4 v[150:153], v[32:33], off offset:3184
	s_waitcnt vmcnt(0)
	v_lshlrev_b32_e32 v154, 16, v58
	v_and_b32_e32 v155, 0xffff0000, v58
	v_pk_fma_f32 v[4:5], v[90:91], v[154:155], v[4:5]
	v_lshlrev_b32_e32 v154, 16, v59
	v_and_b32_e32 v155, 0xffff0000, v59
	v_pk_fma_f32 v[6:7], v[92:93], v[154:155], v[6:7]
	v_lshlrev_b32_e32 v154, 16, v60
	v_and_b32_e32 v155, 0xffff0000, v60
	v_pk_fma_f32 v[0:1], v[94:95], v[154:155], v[0:1]
	v_lshlrev_b32_e32 v154, 16, v61
	v_and_b32_e32 v155, 0xffff0000, v61
	v_pk_fma_f32 v[2:3], v[96:97], v[154:155], v[2:3]
	v_lshlrev_b32_e32 v154, 16, v74
	v_and_b32_e32 v155, 0xffff0000, v74
	v_pk_fma_f32 v[4:5], v[122:123], v[154:155], v[4:5]
	v_lshlrev_b32_e32 v154, 16, v75
	v_and_b32_e32 v155, 0xffff0000, v75
	v_pk_fma_f32 v[6:7], v[124:125], v[154:155], v[6:7]
	v_lshlrev_b32_e32 v154, 16, v76
	v_and_b32_e32 v155, 0xffff0000, v76
	v_pk_fma_f32 v[0:1], v[126:127], v[154:155], v[0:1]
	v_lshlrev_b32_e32 v154, 16, v77
	v_and_b32_e32 v155, 0xffff0000, v77
	v_pk_fma_f32 v[2:3], v[128:129], v[154:155], v[2:3]
	v_lshlrev_b32_e32 v154, 16, v62
	v_and_b32_e32 v155, 0xffff0000, v62
	v_pk_fma_f32 v[12:13], v[98:99], v[154:155], v[12:13]
	v_lshlrev_b32_e32 v154, 16, v63
	v_and_b32_e32 v155, 0xffff0000, v63
	v_pk_fma_f32 v[14:15], v[100:101], v[154:155], v[14:15]
	v_lshlrev_b32_e32 v154, 16, v64
	v_and_b32_e32 v155, 0xffff0000, v64
	v_pk_fma_f32 v[8:9], v[102:103], v[154:155], v[8:9]
	v_lshlrev_b32_e32 v154, 16, v65
	v_and_b32_e32 v155, 0xffff0000, v65
	v_pk_fma_f32 v[10:11], v[104:105], v[154:155], v[10:11]
	v_lshlrev_b32_e32 v154, 16, v78
	v_and_b32_e32 v155, 0xffff0000, v78
	v_pk_fma_f32 v[12:13], v[130:131], v[154:155], v[12:13]
	v_lshlrev_b32_e32 v154, 16, v79
	v_and_b32_e32 v155, 0xffff0000, v79
	v_pk_fma_f32 v[14:15], v[132:133], v[154:155], v[14:15]
	v_lshlrev_b32_e32 v154, 16, v80
	v_and_b32_e32 v155, 0xffff0000, v80
	v_pk_fma_f32 v[8:9], v[134:135], v[154:155], v[8:9]
	v_lshlrev_b32_e32 v154, 16, v81
	v_and_b32_e32 v155, 0xffff0000, v81
	v_pk_fma_f32 v[10:11], v[136:137], v[154:155], v[10:11]
	v_lshlrev_b32_e32 v154, 16, v66
	v_and_b32_e32 v155, 0xffff0000, v66
	v_pk_fma_f32 v[20:21], v[106:107], v[154:155], v[20:21]
	v_lshlrev_b32_e32 v154, 16, v67
	v_and_b32_e32 v155, 0xffff0000, v67
	v_pk_fma_f32 v[22:23], v[108:109], v[154:155], v[22:23]
	v_lshlrev_b32_e32 v154, 16, v68
	v_and_b32_e32 v155, 0xffff0000, v68
	v_pk_fma_f32 v[16:17], v[110:111], v[154:155], v[16:17]
	v_lshlrev_b32_e32 v154, 16, v69
	v_and_b32_e32 v155, 0xffff0000, v69
	v_pk_fma_f32 v[18:19], v[112:113], v[154:155], v[18:19]
	v_lshlrev_b32_e32 v154, 16, v82
	v_and_b32_e32 v155, 0xffff0000, v82
	v_pk_fma_f32 v[20:21], v[138:139], v[154:155], v[20:21]
	v_lshlrev_b32_e32 v154, 16, v83
	v_and_b32_e32 v155, 0xffff0000, v83
	v_pk_fma_f32 v[22:23], v[140:141], v[154:155], v[22:23]
	v_lshlrev_b32_e32 v154, 16, v84
	v_and_b32_e32 v155, 0xffff0000, v84
	v_pk_fma_f32 v[16:17], v[142:143], v[154:155], v[16:17]
	v_lshlrev_b32_e32 v154, 16, v85
	v_and_b32_e32 v155, 0xffff0000, v85
	v_pk_fma_f32 v[18:19], v[144:145], v[154:155], v[18:19]
	v_lshlrev_b32_e32 v154, 16, v70
	v_and_b32_e32 v155, 0xffff0000, v70
	v_pk_fma_f32 v[28:29], v[114:115], v[154:155], v[28:29]
	v_lshlrev_b32_e32 v154, 16, v71
	v_and_b32_e32 v155, 0xffff0000, v71
	v_pk_fma_f32 v[30:31], v[116:117], v[154:155], v[30:31]
	v_lshlrev_b32_e32 v154, 16, v72
	v_and_b32_e32 v155, 0xffff0000, v72
	v_pk_fma_f32 v[24:25], v[118:119], v[154:155], v[24:25]
	v_lshlrev_b32_e32 v154, 16, v73
	v_and_b32_e32 v155, 0xffff0000, v73
	v_pk_fma_f32 v[26:27], v[120:121], v[154:155], v[26:27]
	v_lshlrev_b32_e32 v154, 16, v86
	v_and_b32_e32 v155, 0xffff0000, v86
	v_pk_fma_f32 v[28:29], v[146:147], v[154:155], v[28:29]
	v_lshlrev_b32_e32 v154, 16, v87
	v_and_b32_e32 v155, 0xffff0000, v87
	v_pk_fma_f32 v[30:31], v[148:149], v[154:155], v[30:31]
	v_lshlrev_b32_e32 v154, 16, v88
	v_and_b32_e32 v155, 0xffff0000, v88
	v_pk_fma_f32 v[24:25], v[150:151], v[154:155], v[24:25]
	v_lshlrev_b32_e32 v154, 16, v89
	v_and_b32_e32 v155, 0xffff0000, v89
	v_pk_fma_f32 v[26:27], v[152:153], v[154:155], v[26:27]
	s_branch .Llru_tail
.Llru_slow:
	s_and_saveexec_b64 s[6:7], vcc
	s_cbranch_execz .LBB0_883
	v_mad_i64_i32 v[12:13], s[0:1], v39, s93, v[8:9]
	global_load_dwordx4 v[12:15], v[12:13], off
	s_nop 0
	global_load_dwordx4 v[16:19], v[32:33], off offset:16
	global_load_dwordx4 v[20:23], v[32:33], off
	s_waitcnt vmcnt(2)
	v_lshlrev_b32_e32 v24, 16, v12
	v_and_b32_e32 v25, 0xffff0000, v12
	v_lshlrev_b32_e32 v12, 16, v13
	v_and_b32_e32 v13, 0xffff0000, v13
	s_waitcnt vmcnt(0)
	v_pk_fma_f32 v[6:7], v[22:23], v[12:13], v[6:7]
	v_lshlrev_b32_e32 v12, 16, v14
	v_and_b32_e32 v13, 0xffff0000, v14
	v_pk_fma_f32 v[0:1], v[16:17], v[12:13], v[0:1]
	v_lshlrev_b32_e32 v12, 16, v15
	v_and_b32_e32 v13, 0xffff0000, v15
	v_pk_fma_f32 v[4:5], v[20:21], v[24:25], v[4:5]
	v_pk_fma_f32 v[2:3], v[18:19], v[12:13], v[2:3]

.Llru_tail:
	s_movk_i32 s0, 0x110
	v_ashrrev_i32_e32 v161, 6, v160
	v_and_b32_e32 v162, 31, v160
	v_mul_lo_u32 v33, v36, s0
	v_lshlrev_b32_e32 v34, 2, v37
	v_add3_u32 v33, s89, v33, v34
	v_lshl_or_b32 v163, v161, 5, v162
	s_waitcnt vmcnt(6)
	ds_write_b128 v33, v[4:7]
	ds_write_b128 v33, v[0:3] offset:16
	s_waitcnt vmcnt(4)
	ds_write_b128 v33, v[12:15] offset:32
	ds_write_b128 v33, v[8:11] offset:48
	s_waitcnt vmcnt(2)
	ds_write_b128 v33, v[20:23] offset:64
	ds_write_b128 v33, v[16:19] offset:80
	s_waitcnt vmcnt(0)
	ds_write_b128 v33, v[28:31] offset:96
	ds_write_b128 v33, v[24:27] offset:112
	v_mul_lo_u32 v0, v163, s0
	v_and_b32_e32 v1, 32, v160
	v_add3_u32 v64, s89, v0, v1
	s_waitcnt lgkmcnt(0)
	s_barrier
	ds_read_b128 v[0:3], v64
	ds_read_b128 v[4:7], v64 offset:16
	v_bfe_u32 v32, v160, 5, 1
	v_lshlrev_b32_e32 v168, 4, v32
	v_lshlrev_b32_e32 v100, 7, v162
	s_waitcnt lgkmcnt(1)
	v_cvt_pk_bf16_f32 v56, v0, v1
	v_cvt_pk_bf16_f32 v57, v2, v3
	s_waitcnt lgkmcnt(0)
	v_cvt_pk_bf16_f32 v58, v4, v5
	v_cvt_pk_bf16_f32 v59, v6, v7
	ds_read_b128 v[0:3], v64 offset:64
	ds_read_b128 v[4:7], v64 offset:80
	v_mov_b32_e32 v101, v169
	v_lshlrev_b32_e32 v164, 2, v32
	v_sub_u32_e32 v124, v64, v168
	s_waitcnt lgkmcnt(1)
	v_cvt_pk_bf16_f32 v52, v0, v1
	v_cvt_pk_bf16_f32 v53, v2, v3
	s_waitcnt lgkmcnt(0)
	v_cvt_pk_bf16_f32 v54, v4, v5
	v_cvt_pk_bf16_f32 v55, v6, v7
	ds_read_b128 v[0:3], v64 offset:128
	ds_read_b128 v[4:7], v64 offset:144
	s_waitcnt lgkmcnt(1)
	v_cvt_pk_bf16_f32 v48, v0, v1
	v_cvt_pk_bf16_f32 v49, v2, v3
	s_waitcnt lgkmcnt(0)
	v_cvt_pk_bf16_f32 v50, v4, v5
	v_cvt_pk_bf16_f32 v51, v6, v7
	ds_read_b128 v[0:3], v64 offset:192
	ds_read_b128 v[4:7], v64 offset:208
	s_load_dwordx2 s[6:7], s[54:55], 0x98
	s_load_dwordx4 s[0:3], s[54:55], 0xa8
	s_waitcnt lgkmcnt(0)
	v_cvt_pk_bf16_f32 v44, v0, v1
	s_add_u32 s5, s6, s60
	s_addc_u32 s6, s7, s61
	s_lshl_b32 s75, s74, 2
	s_add_u32 s10, s5, s75
	s_addc_u32 s11, s6, 0
	s_add_u32 s0, s0, s60
	s_addc_u32 s1, s1, s61
	s_add_u32 s12, s0, s75
	s_addc_u32 s13, s1, 0
	s_add_u32 s0, s2, s60
	s_addc_u32 s1, s3, s61
	s_add_u32 s8, s0, s75
	s_addc_u32 s9, s1, 0
	s_lshl_b32 s2, s4, 13
	s_add_u32 s0, s36, s2
	s_addc_u32 s1, s37, 0
	v_lshl_add_u64 v[96:97], s[0:1], 0, v[168:169]
	s_add_u32 s0, s38, s2
	s_addc_u32 s1, s39, 0
	v_lshl_add_u64 v[98:99], s[0:1], 0, v[168:169]
	v_lshl_add_u64 v[40:41], v[96:97], 0, v[100:101]
	v_cvt_pk_bf16_f32 v45, v2, v3
	v_cvt_pk_bf16_f32 v46, v4, v5
	v_cvt_pk_bf16_f32 v47, v6, v7
	v_lshl_add_u64 v[42:43], v[98:99], 0, v[100:101]
	global_load_dwordx4 v[0:3], v[40:41], off
	global_load_dwordx4 v[4:7], v[42:43], off
	global_load_dwordx4 v[32:35], v[40:41], off offset:32
	global_load_dwordx4 v[36:39], v[42:43], off offset:32
	s_mov_b32 s0, 0x3f317217
	s_mov_b32 s1, 0x7f800000
	s_mov_b32 s3, 0x3cf5c28f
	s_mov_b32 s2, 0xc1700000
	s_mov_b32 s4, 0xbdcccccd
	s_waitcnt vmcnt(3)
	v_mfma_f32_32x32x16_bf16 v[16:31], v[0:3], v[56:59], 0
	s_waitcnt vmcnt(2)
	v_mfma_f32_32x32x16_bf16 v[0:15], v[4:7], v[56:59], 0
	s_waitcnt vmcnt(1)
	v_mfma_f32_32x32x16_bf16 v[16:31], v[32:35], v[52:55], v[16:31]
	s_waitcnt vmcnt(0)
	v_mfma_f32_32x32x16_bf16 v[0:15], v[36:39], v[52:55], v[0:15]
	global_load_dwordx4 v[32:35], v[40:41], off offset:64
	global_load_dwordx4 v[36:39], v[42:43], off offset:64
	s_waitcnt vmcnt(1)
	v_mfma_f32_32x32x16_bf16 v[16:31], v[32:35], v[48:51], v[16:31]
	s_waitcnt vmcnt(0)
	v_mfma_f32_32x32x16_bf16 v[0:15], v[36:39], v[48:51], v[0:15]
	global_load_dwordx4 v[32:35], v[40:41], off offset:96
	global_load_dwordx4 v[36:39], v[42:43], off offset:96
	s_waitcnt vmcnt(1)
	v_mfma_f32_32x32x16_bf16 v[16:31], v[32:35], v[44:47], v[16:31]
	s_waitcnt vmcnt(0)
	v_mfma_f32_32x32x16_bf16 v[0:15], v[36:39], v[44:47], v[0:15]
	global_load_dwordx4 v[40:43], v168, s[10:11]
	global_load_dwordx4 v[36:39], v168, s[12:13]
	global_load_dwordx4 v[60:63], v168, s[8:9]
	ds_read_b128 v[64:67], v124
	ds_read_b128 v[32:35], v124 offset:32
	s_waitcnt vmcnt(2)
	s_nop 3
	v_add_f32_e32 v16, v16, v40
	s_waitcnt vmcnt(1)
	v_add_f32_e32 v0, v0, v36
	s_waitcnt vmcnt(0)
	v_mul_f32_e32 v36, 0xbfb8aa3b, v60
	v_exp_f32_e32 v36, v36
	v_mul_f32_e32 v16, 0xbfb8aa3b, v16
	v_exp_f32_e32 v16, v16
	v_mul_f32_e32 v0, 0xbfb8aa3b, v0
	v_add_f32_e32 v40, 1.0, v36
	v_cmp_gt_f32_e32 vcc, s28, v40
	v_add_f32_e32 v16, 1.0, v16
	v_rcp_f32_e32 v16, v16
	v_cndmask_b32_e64 v68, 0, 32, vcc
	v_ldexp_f32 v40, v40, v68
	v_log_f32_e32 v40, v40
	v_mul_f32_e32 v16, 0xc1000000, v16
	v_exp_f32_e32 v0, v0
	v_add_f32_e32 v1, v1, v37
	v_mul_f32_e32 v68, 0x3f317217, v40
	v_fma_f32 v68, v40, s0, -v68
	v_fmac_f32_e32 v68, 0x3377d1cf, v40
	v_fmac_f32_e32 v68, 0x3f317217, v40
	v_cmp_lt_f32_e64 s[6:7], |v40|, s1
	v_add_f32_e32 v0, 1.0, v0
	v_rcp_f32_e32 v0, v0
	v_cndmask_b32_e64 v40, v40, v68, s[6:7]
	v_cndmask_b32_e32 v68, 0, v201, vcc
	v_sub_f32_e32 v40, v40, v68
	v_fmamk_f32 v68, v36, 0xbe800000, v188
	v_fma_f32 v68, -v36, v68, 0.5
	v_fma_f32 v68, -v36, v68, 1.0
	v_mul_f32_e32 v68, v36, v68
	v_cmp_gt_f32_e64 s[6:7], s3, v36
	v_cmp_gt_f32_e32 vcc, s2, v60
	s_waitcnt lgkmcnt(1)
	v_mul_f32_e32 v0, v64, v0
	v_cndmask_b32_e64 v36, v40, v68, s[6:7]
	v_cndmask_b32_e64 v36, v36, -v60, vcc
	v_mul_f32_e32 v16, v16, v36
	v_mul_f32_e32 v36, 0x3fb8aa3b, v16
	v_add_f32_e32 v16, v16, v16
	v_mul_f32_e32 v40, 0x3fb8aa3b, v16
	v_exp_f32_e32 v136, v36
	v_fmamk_f32 v36, v16, 0x3c088889, v189
	v_exp_f32_e32 v40, v40
	v_fmaak_f32 v36, v16, v36, 0x3e2aaaab
	v_fma_f32 v36, v16, v36, 0.5
	v_fma_f32 v36, v16, v36, 1.0
	v_mul_f32_e64 v36, v36, -v16
	v_sub_f32_e32 v40, 1.0, v40
	v_cmp_lt_f32_e32 vcc, s4, v16
	v_mul_f32_e32 v1, 0xbfb8aa3b, v1
	v_exp_f32_e32 v1, v1
	v_cndmask_b32_e32 v16, v40, v36, vcc
	v_sqrt_f32_e32 v16, v16
	v_add_f32_e32 v1, 1.0, v1
	v_rcp_f32_e32 v1, v1
	v_mul_f32_e32 v137, v0, v16
	v_mul_f32_e32 v16, 0xbfb8aa3b, v61
	v_exp_f32_e32 v16, v16
	v_add_f32_e32 v0, v17, v41
	v_mul_f32_e32 v0, 0xbfb8aa3b, v0
	v_exp_f32_e32 v0, v0
	v_add_f32_e32 v17, 1.0, v16
	v_cmp_gt_f32_e32 vcc, s28, v17
	v_mul_f32_e32 v1, v65, v1
	v_add_f32_e32 v0, 1.0, v0
	v_cndmask_b32_e64 v36, 0, 32, vcc
	v_ldexp_f32 v17, v17, v36
	v_log_f32_e32 v17, v17
	v_rcp_f32_e32 v0, v0
	v_mul_f32_e32 v36, 0x3f317217, v17
	v_fma_f32 v36, v17, s0, -v36
	v_fmac_f32_e32 v36, 0x3377d1cf, v17
	v_fmac_f32_e32 v36, 0x3f317217, v17
	v_cmp_lt_f32_e64 s[6:7], |v17|, s1
	v_mul_f32_e32 v0, 0xc1000000, v0
	s_nop 0
	v_cndmask_b32_e64 v17, v17, v36, s[6:7]
	v_cndmask_b32_e32 v36, 0, v201, vcc
	v_sub_f32_e32 v17, v17, v36
	v_fmamk_f32 v36, v16, 0xbe800000, v188
	v_fma_f32 v36, -v16, v36, 0.5
	v_fma_f32 v36, -v16, v36, 1.0
	v_mul_f32_e32 v36, v16, v36
	v_cmp_gt_f32_e64 s[6:7], s3, v16
	v_cmp_gt_f32_e32 vcc, s2, v61
	s_nop 0
	v_cndmask_b32_e64 v16, v17, v36, s[6:7]
	v_cndmask_b32_e64 v16, v16, -v61, vcc
	v_mul_f32_e32 v0, v0, v16
	v_mul_f32_e32 v16, 0x3fb8aa3b, v0
	v_add_f32_e32 v0, v0, v0
	v_mul_f32_e32 v17, 0x3fb8aa3b, v0
	v_exp_f32_e32 v138, v16
	v_fmamk_f32 v16, v0, 0x3c088889, v189
	v_exp_f32_e32 v17, v17
	v_fmaak_f32 v16, v0, v16, 0x3e2aaaab
	v_fma_f32 v16, v0, v16, 0.5
	v_fma_f32 v16, v0, v16, 1.0
	v_mul_f32_e64 v16, v16, -v0
	v_sub_f32_e32 v17, 1.0, v17
	v_cmp_lt_f32_e32 vcc, s4, v0
	s_nop 1
	v_cndmask_b32_e32 v0, v17, v16, vcc
	v_sqrt_f32_e32 v0, v0
	s_nop 0
	v_mul_f32_e32 v139, v1, v0
	v_add_f32_e32 v1, v2, v38
	v_mul_f32_e32 v2, 0xbfb8aa3b, v62
	v_exp_f32_e32 v2, v2
	v_add_f32_e32 v0, v18, v42
	v_mul_f32_e32 v0, 0xbfb8aa3b, v0
	v_exp_f32_e32 v0, v0
	v_add_f32_e32 v16, 1.0, v2
	v_cmp_gt_f32_e32 vcc, s28, v16
	v_mul_f32_e32 v1, 0xbfb8aa3b, v1
	v_add_f32_e32 v0, 1.0, v0
	v_cndmask_b32_e64 v17, 0, 32, vcc
	v_ldexp_f32 v16, v16, v17
	v_log_f32_e32 v16, v16
	v_rcp_f32_e32 v0, v0
	v_exp_f32_e32 v1, v1
	v_mul_f32_e32 v17, 0x3f317217, v16
	v_fma_f32 v17, v16, s0, -v17
	v_fmac_f32_e32 v17, 0x3377d1cf, v16
	v_fmac_f32_e32 v17, 0x3f317217, v16
	v_cmp_lt_f32_e64 s[6:7], |v16|, s1
	v_mul_f32_e32 v0, 0xc1000000, v0
	v_add_f32_e32 v1, 1.0, v1
	v_cndmask_b32_e64 v16, v16, v17, s[6:7]
	v_cndmask_b32_e32 v17, 0, v201, vcc
	v_sub_f32_e32 v16, v16, v17
	v_fmamk_f32 v17, v2, 0xbe800000, v188
	v_fma_f32 v17, -v2, v17, 0.5
	v_fma_f32 v17, -v2, v17, 1.0
	v_mul_f32_e32 v17, v2, v17
	v_cmp_gt_f32_e64 s[6:7], s3, v2
	v_cmp_gt_f32_e32 vcc, s2, v62
	v_rcp_f32_e32 v1, v1
	v_cndmask_b32_e64 v2, v16, v17, s[6:7]
	v_cndmask_b32_e64 v2, v2, -v62, vcc
	v_mul_f32_e32 v0, v0, v2
	v_mul_f32_e32 v2, 0x3fb8aa3b, v0
	v_add_f32_e32 v0, v0, v0
	v_mul_f32_e32 v16, 0x3fb8aa3b, v0
	v_exp_f32_e32 v140, v2
	v_fmamk_f32 v2, v0, 0x3c088889, v189
	v_exp_f32_e32 v16, v16
	v_fmaak_f32 v2, v0, v2, 0x3e2aaaab
	v_fma_f32 v2, v0, v2, 0.5
	v_fma_f32 v2, v0, v2, 1.0
	v_mul_f32_e64 v2, v2, -v0
	v_sub_f32_e32 v16, 1.0, v16
	v_cmp_lt_f32_e32 vcc, s4, v0
	v_mul_f32_e32 v1, v66, v1
	s_nop 0
	v_cndmask_b32_e32 v0, v16, v2, vcc
	v_mul_f32_e32 v2, 0xbfb8aa3b, v63
	v_sqrt_f32_e32 v0, v0
	v_exp_f32_e32 v2, v2
	v_mul_f32_e32 v141, v1, v0
	v_add_f32_e32 v1, v3, v39
	v_add_f32_e32 v3, 1.0, v2
	v_cmp_gt_f32_e32 vcc, s28, v3
	v_add_f32_e32 v0, v19, v43
	v_mul_f32_e32 v0, 0xbfb8aa3b, v0
	v_cndmask_b32_e64 v16, 0, 32, vcc
	v_ldexp_f32 v3, v3, v16
	v_log_f32_e32 v3, v3
	v_exp_f32_e32 v0, v0
	v_mul_f32_e32 v1, 0xbfb8aa3b, v1
	v_exp_f32_e32 v1, v1
	v_mul_f32_e32 v16, 0x3f317217, v3
	v_fma_f32 v16, v3, s0, -v16
	v_fmac_f32_e32 v16, 0x3377d1cf, v3
	v_fmac_f32_e32 v16, 0x3f317217, v3
	v_cmp_lt_f32_e64 s[6:7], |v3|, s1
	v_add_f32_e32 v0, 1.0, v0
	v_rcp_f32_e32 v0, v0
	v_cndmask_b32_e64 v3, v3, v16, s[6:7]
	v_cndmask_b32_e32 v16, 0, v201, vcc
	v_sub_f32_e32 v3, v3, v16
	v_fmamk_f32 v16, v2, 0xbe800000, v188
	v_fma_f32 v16, -v2, v16, 0.5
	v_fma_f32 v16, -v2, v16, 1.0
	v_mul_f32_e32 v16, v2, v16
	v_cmp_gt_f32_e64 s[6:7], s3, v2
	v_cmp_gt_f32_e32 vcc, s2, v63
	v_mul_f32_e32 v0, 0xc1000000, v0
	v_cndmask_b32_e64 v2, v3, v16, s[6:7]
	v_cndmask_b32_e64 v2, v2, -v63, vcc
	v_mul_f32_e32 v0, v0, v2
	v_mul_f32_e32 v2, 0x3fb8aa3b, v0
	v_add_f32_e32 v0, v0, v0
	v_mul_f32_e32 v3, 0x3fb8aa3b, v0
	v_exp_f32_e32 v142, v2
	v_fmamk_f32 v2, v0, 0x3c088889, v189
	v_exp_f32_e32 v3, v3
	v_fmaak_f32 v2, v0, v2, 0x3e2aaaab
	v_fma_f32 v2, v0, v2, 0.5
	v_fma_f32 v2, v0, v2, 1.0
	v_add_f32_e32 v1, 1.0, v1
	v_mul_f32_e64 v2, v2, -v0
	v_sub_f32_e32 v3, 1.0, v3
	v_cmp_lt_f32_e32 vcc, s4, v0
	v_rcp_f32_e32 v1, v1
	s_nop 0
	v_cndmask_b32_e32 v0, v3, v2, vcc
	v_sqrt_f32_e32 v0, v0
	v_mul_f32_e32 v1, v67, v1
	v_mul_f32_e32 v143, v1, v0
	global_load_dwordx4 v[36:39], v168, s[10:11] offset:32
	global_load_dwordx4 v[16:19], v168, s[12:13] offset:32
	global_load_dwordx4 v[0:3], v168, s[8:9] offset:32
	s_waitcnt vmcnt(2)
	v_add_f32_e32 v20, v20, v36
	v_mul_f32_e32 v20, 0xbfb8aa3b, v20
	v_exp_f32_e32 v20, v20
	s_waitcnt vmcnt(1)
	v_add_f32_e32 v4, v4, v16
	v_mul_f32_e32 v4, 0xbfb8aa3b, v4
	v_exp_f32_e32 v4, v4
	v_add_f32_e32 v20, 1.0, v20
	s_waitcnt vmcnt(0)
	v_mul_f32_e32 v16, 0xbfb8aa3b, v0
	v_rcp_f32_e32 v20, v20
	v_exp_f32_e32 v16, v16
	v_add_f32_e32 v4, 1.0, v4
	v_rcp_f32_e32 v60, v4
	v_mul_f32_e32 v4, 0xc1000000, v20
	v_add_f32_e32 v20, 1.0, v16
	v_cmp_gt_f32_e32 vcc, s28, v20
	s_nop 1
	v_cndmask_b32_e64 v36, 0, 32, vcc
	v_ldexp_f32 v20, v20, v36
	v_log_f32_e32 v20, v20
	s_nop 0
	v_mul_f32_e32 v36, 0x3f317217, v20
	v_fma_f32 v36, v20, s0, -v36
	v_fmac_f32_e32 v36, 0x3377d1cf, v20
	v_fmac_f32_e32 v36, 0x3f317217, v20
	v_cmp_lt_f32_e64 s[6:7], |v20|, s1
	s_nop 1
	v_cndmask_b32_e64 v20, v20, v36, s[6:7]
	v_cndmask_b32_e32 v36, 0, v201, vcc
	v_sub_f32_e32 v20, v20, v36
	v_fmamk_f32 v36, v16, 0xbe800000, v188
	v_fma_f32 v36, -v16, v36, 0.5
	v_fma_f32 v36, -v16, v36, 1.0
	v_mul_f32_e32 v36, v16, v36
	v_cmp_gt_f32_e64 s[6:7], s3, v16
	v_cmp_gt_f32_e32 vcc, s2, v0
	s_nop 0
	v_cndmask_b32_e64 v16, v20, v36, s[6:7]
	v_cndmask_b32_e64 v0, v16, -v0, vcc
	v_mul_f32_e32 v0, v4, v0
	v_mul_f32_e32 v4, 0x3fb8aa3b, v0
	v_add_f32_e32 v0, v0, v0
	v_mul_f32_e32 v16, 0x3fb8aa3b, v0
	v_exp_f32_e32 v62, v4
	v_fmamk_f32 v4, v0, 0x3c088889, v189
	v_exp_f32_e32 v16, v16
	v_fmaak_f32 v4, v0, v4, 0x3e2aaaab
	v_fma_f32 v4, v0, v4, 0.5
	v_fma_f32 v4, v0, v4, 1.0
	v_mul_f32_e64 v4, v4, -v0
	v_sub_f32_e32 v16, 1.0, v16
	v_cmp_lt_f32_e32 vcc, s4, v0
	s_nop 1
	v_cndmask_b32_e32 v0, v16, v4, vcc
	v_add_f32_e32 v4, v5, v17
	v_mul_f32_e32 v4, 0xbfb8aa3b, v4
	v_exp_f32_e32 v4, v4
	v_sqrt_f32_e32 v64, v0
	v_add_f32_e32 v0, v21, v37
	v_mul_f32_e32 v0, 0xbfb8aa3b, v0
	v_add_f32_e32 v4, 1.0, v4
	v_rcp_f32_e32 v61, v4
	v_mul_f32_e32 v4, 0xbfb8aa3b, v1
	v_exp_f32_e32 v4, v4
	v_exp_f32_e32 v0, v0
	v_add_f32_e32 v5, 1.0, v4
	v_cmp_gt_f32_e32 vcc, s28, v5
	v_add_f32_e32 v0, 1.0, v0
	v_rcp_f32_e32 v0, v0
	v_cndmask_b32_e64 v16, 0, 32, vcc
	v_ldexp_f32 v5, v5, v16
	v_log_f32_e32 v5, v5
	v_mul_f32_e32 v0, 0xc1000000, v0
	v_mul_f32_e32 v16, 0x3f317217, v5
	v_fma_f32 v16, v5, s0, -v16
	v_fmac_f32_e32 v16, 0x3377d1cf, v5
	v_fmac_f32_e32 v16, 0x3f317217, v5
	v_cmp_lt_f32_e64 s[6:7], |v5|, s1
	s_nop 1
	v_cndmask_b32_e64 v5, v5, v16, s[6:7]
	v_cndmask_b32_e32 v16, 0, v201, vcc
	v_sub_f32_e32 v5, v5, v16
	v_fmamk_f32 v16, v4, 0xbe800000, v188
	v_fma_f32 v16, -v4, v16, 0.5
	v_fma_f32 v16, -v4, v16, 1.0
	v_mul_f32_e32 v16, v4, v16
	v_cmp_gt_f32_e64 s[6:7], s3, v4
	v_cmp_gt_f32_e32 vcc, s2, v1
	s_nop 0
	v_cndmask_b32_e64 v4, v5, v16, s[6:7]
	v_cndmask_b32_e64 v1, v4, -v1, vcc
	v_mul_f32_e32 v0, v0, v1
	v_mul_f32_e32 v1, 0x3fb8aa3b, v0
	v_add_f32_e32 v0, v0, v0
	v_mul_f32_e32 v4, 0x3fb8aa3b, v0
	v_exp_f32_e32 v63, v1
	v_fmamk_f32 v1, v0, 0x3c088889, v189
	v_exp_f32_e32 v4, v4
	v_fmaak_f32 v1, v0, v1, 0x3e2aaaab
	v_fma_f32 v1, v0, v1, 0.5
	v_fma_f32 v1, v0, v1, 1.0
	v_mul_f32_e64 v1, v1, -v0
	v_sub_f32_e32 v4, 1.0, v4
	v_cmp_lt_f32_e32 vcc, s4, v0
	s_nop 1
	v_cndmask_b32_e32 v0, v4, v1, vcc
	v_add_f32_e32 v1, v6, v18
	v_mul_f32_e32 v1, 0xbfb8aa3b, v1
	v_exp_f32_e32 v1, v1
	v_sqrt_f32_e32 v65, v0
	v_add_f32_e32 v0, v22, v38
	v_mul_f32_e32 v0, 0xbfb8aa3b, v0
	v_add_f32_e32 v1, 1.0, v1
	v_rcp_f32_e32 v66, v1
	v_mul_f32_e32 v1, 0xbfb8aa3b, v2
	v_exp_f32_e32 v1, v1
	v_exp_f32_e32 v0, v0
	v_add_f32_e32 v4, 1.0, v1
	v_cmp_gt_f32_e32 vcc, s28, v4
	v_add_f32_e32 v0, 1.0, v0
	v_rcp_f32_e32 v0, v0
	v_cndmask_b32_e64 v5, 0, 32, vcc
	v_ldexp_f32 v4, v4, v5
	v_log_f32_e32 v4, v4
	v_mul_f32_e32 v0, 0xc1000000, v0
	v_mul_f32_e32 v5, 0x3f317217, v4
	v_fma_f32 v5, v4, s0, -v5
	v_fmac_f32_e32 v5, 0x3377d1cf, v4
	v_fmac_f32_e32 v5, 0x3f317217, v4
	v_cmp_lt_f32_e64 s[6:7], |v4|, s1
	s_nop 1
	v_cndmask_b32_e64 v4, v4, v5, s[6:7]
	v_cndmask_b32_e32 v5, 0, v201, vcc
	v_sub_f32_e32 v4, v4, v5
	v_fmamk_f32 v5, v1, 0xbe800000, v188
	v_fma_f32 v5, -v1, v5, 0.5
	v_fma_f32 v5, -v1, v5, 1.0
	v_mul_f32_e32 v5, v1, v5
	v_cmp_gt_f32_e64 s[6:7], s3, v1
	v_cmp_gt_f32_e32 vcc, s2, v2
	s_nop 0
	v_cndmask_b32_e64 v1, v4, v5, s[6:7]
	v_cndmask_b32_e64 v1, v1, -v2, vcc
	v_mul_f32_e32 v0, v0, v1
	v_mul_f32_e32 v1, 0x3fb8aa3b, v0
	v_add_f32_e32 v0, v0, v0
	v_mul_f32_e32 v2, 0x3fb8aa3b, v0
	v_exp_f32_e32 v68, v1
	v_fmamk_f32 v1, v0, 0x3c088889, v189
	v_exp_f32_e32 v2, v2
	v_fmaak_f32 v1, v0, v1, 0x3e2aaaab
	v_fma_f32 v1, v0, v1, 0.5
	v_fma_f32 v1, v0, v1, 1.0
	v_mul_f32_e64 v1, v1, -v0
	v_sub_f32_e32 v2, 1.0, v2
	v_cmp_lt_f32_e32 vcc, s4, v0
	s_nop 1
	v_cndmask_b32_e32 v0, v2, v1, vcc
	v_add_f32_e32 v1, v7, v19
	v_mul_f32_e32 v1, 0xbfb8aa3b, v1
	v_exp_f32_e32 v1, v1
	v_sqrt_f32_e32 v70, v0
	v_add_f32_e32 v0, v23, v39
	v_mul_f32_e32 v0, 0xbfb8aa3b, v0
	v_add_f32_e32 v1, 1.0, v1
	v_rcp_f32_e32 v67, v1
	v_mul_f32_e32 v1, 0xbfb8aa3b, v3
	v_exp_f32_e32 v1, v1
	v_exp_f32_e32 v0, v0
	v_add_f32_e32 v2, 1.0, v1
	v_cmp_gt_f32_e32 vcc, s28, v2
	v_add_f32_e32 v0, 1.0, v0
	v_rcp_f32_e32 v0, v0
	v_cndmask_b32_e64 v4, 0, 32, vcc
	v_ldexp_f32 v2, v2, v4
	v_log_f32_e32 v2, v2
	v_mul_f32_e32 v0, 0xc1000000, v0
	v_mul_f32_e32 v4, 0x3f317217, v2
	v_fma_f32 v4, v2, s0, -v4
	v_fmac_f32_e32 v4, 0x3377d1cf, v2
	v_fmac_f32_e32 v4, 0x3f317217, v2
	v_cmp_lt_f32_e64 s[6:7], |v2|, s1
	s_nop 1
	v_cndmask_b32_e64 v2, v2, v4, s[6:7]
	v_cndmask_b32_e32 v4, 0, v201, vcc
	v_sub_f32_e32 v2, v2, v4
	v_fmamk_f32 v4, v1, 0xbe800000, v188
	v_fma_f32 v4, -v1, v4, 0.5
	v_fma_f32 v4, -v1, v4, 1.0
	v_mul_f32_e32 v4, v1, v4
	v_cmp_gt_f32_e64 s[6:7], s3, v1
	v_cmp_gt_f32_e32 vcc, s2, v3
	s_nop 0
	v_cndmask_b32_e64 v1, v2, v4, s[6:7]
	v_cndmask_b32_e64 v1, v1, -v3, vcc
	v_mul_f32_e32 v0, v0, v1
	v_mul_f32_e32 v1, 0x3fb8aa3b, v0
	v_add_f32_e32 v0, v0, v0
	v_mul_f32_e32 v2, 0x3fb8aa3b, v0
	v_exp_f32_e32 v69, v1
	v_fmamk_f32 v1, v0, 0x3c088889, v189
	v_exp_f32_e32 v2, v2
	v_fmaak_f32 v1, v0, v1, 0x3e2aaaab
	v_fma_f32 v1, v0, v1, 0.5
	v_fma_f32 v1, v0, v1, 1.0
	v_mul_f32_e64 v1, v1, -v0
	v_sub_f32_e32 v2, 1.0, v2
	v_cmp_lt_f32_e32 vcc, s4, v0
	s_nop 1
	v_cndmask_b32_e32 v0, v2, v1, vcc
	v_sqrt_f32_e32 v71, v0
	global_load_dwordx4 v[0:3], v168, s[10:11] offset:64
	global_load_dwordx4 v[4:7], v168, s[12:13] offset:64
	global_load_dwordx4 v[16:19], v168, s[8:9] offset:64
	ds_read_b128 v[36:39], v124 offset:64
	s_waitcnt vmcnt(2)
	v_add_f32_e32 v0, v24, v0
	s_waitcnt vmcnt(1)
	v_add_f32_e32 v4, v8, v4
	v_mul_f32_e32 v4, 0xbfb8aa3b, v4
	v_exp_f32_e32 v4, v4
	v_mul_f32_e32 v0, 0xbfb8aa3b, v0
	v_exp_f32_e32 v0, v0
	v_add_f32_e32 v4, 1.0, v4
	v_rcp_f32_e32 v72, v4
	s_waitcnt vmcnt(0)
	v_mul_f32_e32 v4, 0xbfb8aa3b, v16
	v_exp_f32_e32 v4, v4
	v_add_f32_e32 v0, 1.0, v0
	v_rcp_f32_e32 v0, v0
	v_add_f32_e32 v8, 1.0, v4
	v_cmp_gt_f32_e32 vcc, s28, v8
	v_mul_f32_e32 v0, 0xc1000000, v0
	s_nop 0
	v_cndmask_b32_e64 v20, 0, 32, vcc
	v_ldexp_f32 v8, v8, v20
	v_log_f32_e32 v8, v8
	s_nop 0
	v_mul_f32_e32 v20, 0x3f317217, v8
	v_fma_f32 v20, v8, s0, -v20
	v_fmac_f32_e32 v20, 0x3377d1cf, v8
	v_fmac_f32_e32 v20, 0x3f317217, v8
	v_cmp_lt_f32_e64 s[6:7], |v8|, s1
	s_nop 1
	v_cndmask_b32_e64 v8, v8, v20, s[6:7]
	v_cndmask_b32_e32 v20, 0, v201, vcc
	v_sub_f32_e32 v8, v8, v20
	v_fmamk_f32 v20, v4, 0xbe800000, v188
	v_fma_f32 v20, -v4, v20, 0.5
	v_fma_f32 v20, -v4, v20, 1.0
	v_mul_f32_e32 v20, v4, v20
	v_cmp_gt_f32_e64 s[6:7], s3, v4
	v_cmp_gt_f32_e32 vcc, s2, v16
	s_nop 0
	v_cndmask_b32_e64 v4, v8, v20, s[6:7]
	v_cndmask_b32_e64 v4, v4, -v16, vcc
	v_mul_f32_e32 v0, v0, v4
	v_mul_f32_e32 v4, 0x3fb8aa3b, v0
	v_add_f32_e32 v0, v0, v0
	v_mul_f32_e32 v8, 0x3fb8aa3b, v0
	v_exp_f32_e32 v76, v4
	v_fmamk_f32 v4, v0, 0x3c088889, v189
	v_exp_f32_e32 v8, v8
	v_fmaak_f32 v4, v0, v4, 0x3e2aaaab
	v_fma_f32 v4, v0, v4, 0.5
	v_fma_f32 v4, v0, v4, 1.0
	v_mul_f32_e64 v4, v4, -v0
	v_sub_f32_e32 v8, 1.0, v8
	v_cmp_lt_f32_e32 vcc, s4, v0
	s_nop 1
	v_cndmask_b32_e32 v0, v8, v4, vcc
	v_sqrt_f32_e32 v80, v0
	v_add_f32_e32 v0, v25, v1
	v_add_f32_e32 v1, v9, v5
	v_mul_f32_e32 v1, 0xbfb8aa3b, v1
	v_exp_f32_e32 v1, v1
	v_mul_f32_e32 v0, 0xbfb8aa3b, v0
	v_exp_f32_e32 v0, v0
	v_add_f32_e32 v1, 1.0, v1
	v_rcp_f32_e32 v73, v1
	v_mul_f32_e32 v1, 0xbfb8aa3b, v17
	v_exp_f32_e32 v1, v1
	v_add_f32_e32 v0, 1.0, v0
	v_rcp_f32_e32 v0, v0
	v_add_f32_e32 v4, 1.0, v1
	v_cmp_gt_f32_e32 vcc, s28, v4
	v_mul_f32_e32 v0, 0xc1000000, v0
	s_nop 0
	v_cndmask_b32_e64 v5, 0, 32, vcc
	v_ldexp_f32 v4, v4, v5
	v_log_f32_e32 v4, v4
	s_nop 0
	v_mul_f32_e32 v5, 0x3f317217, v4
	v_fma_f32 v5, v4, s0, -v5
	v_fmac_f32_e32 v5, 0x3377d1cf, v4
	v_fmac_f32_e32 v5, 0x3f317217, v4
	v_cmp_lt_f32_e64 s[6:7], |v4|, s1
	s_nop 1
	v_cndmask_b32_e64 v4, v4, v5, s[6:7]
	v_cndmask_b32_e32 v5, 0, v201, vcc
	v_sub_f32_e32 v4, v4, v5
	v_fmamk_f32 v5, v1, 0xbe800000, v188
	v_fma_f32 v5, -v1, v5, 0.5
	v_fma_f32 v5, -v1, v5, 1.0
	v_mul_f32_e32 v5, v1, v5
	v_cmp_gt_f32_e64 s[6:7], s3, v1
	v_cmp_gt_f32_e32 vcc, s2, v17
	s_nop 0
	v_cndmask_b32_e64 v1, v4, v5, s[6:7]
	v_cndmask_b32_e64 v1, v1, -v17, vcc
	v_mul_f32_e32 v0, v0, v1
	v_mul_f32_e32 v1, 0x3fb8aa3b, v0
	v_add_f32_e32 v0, v0, v0
	v_mul_f32_e32 v4, 0x3fb8aa3b, v0
	v_exp_f32_e32 v77, v1
	v_fmamk_f32 v1, v0, 0x3c088889, v189
	v_exp_f32_e32 v4, v4
	v_fmaak_f32 v1, v0, v1, 0x3e2aaaab
	v_fma_f32 v1, v0, v1, 0.5
	v_fma_f32 v1, v0, v1, 1.0
	v_mul_f32_e64 v1, v1, -v0
	v_sub_f32_e32 v4, 1.0, v4
	v_cmp_lt_f32_e32 vcc, s4, v0
	s_nop 1
	v_cndmask_b32_e32 v0, v4, v1, vcc
	v_add_f32_e32 v1, v10, v6
	v_mul_f32_e32 v1, 0xbfb8aa3b, v1
	v_exp_f32_e32 v1, v1
	v_sqrt_f32_e32 v81, v0
	v_add_f32_e32 v0, v26, v2
	v_mul_f32_e32 v0, 0xbfb8aa3b, v0
	v_add_f32_e32 v1, 1.0, v1
	v_rcp_f32_e32 v74, v1
	v_mul_f32_e32 v1, 0xbfb8aa3b, v18
	v_exp_f32_e32 v1, v1
	v_exp_f32_e32 v0, v0
	v_add_f32_e32 v2, 1.0, v1
	v_cmp_gt_f32_e32 vcc, s28, v2
	v_add_f32_e32 v0, 1.0, v0
	v_rcp_f32_e32 v0, v0
	v_cndmask_b32_e64 v4, 0, 32, vcc
	v_ldexp_f32 v2, v2, v4
	v_log_f32_e32 v2, v2
	v_mul_f32_e32 v0, 0xc1000000, v0
	v_mul_f32_e32 v4, 0x3f317217, v2
	v_fma_f32 v4, v2, s0, -v4
	v_fmac_f32_e32 v4, 0x3377d1cf, v2
	v_fmac_f32_e32 v4, 0x3f317217, v2
	v_cmp_lt_f32_e64 s[6:7], |v2|, s1
	s_nop 1
	v_cndmask_b32_e64 v2, v2, v4, s[6:7]
	v_cndmask_b32_e32 v4, 0, v201, vcc
	v_sub_f32_e32 v2, v2, v4
	v_fmamk_f32 v4, v1, 0xbe800000, v188
	v_fma_f32 v4, -v1, v4, 0.5
	v_fma_f32 v4, -v1, v4, 1.0
	v_mul_f32_e32 v4, v1, v4
	v_cmp_gt_f32_e64 s[6:7], s3, v1
	v_cmp_gt_f32_e32 vcc, s2, v18
	s_nop 0
	v_cndmask_b32_e64 v1, v2, v4, s[6:7]
	v_cndmask_b32_e64 v1, v1, -v18, vcc
	v_mul_f32_e32 v0, v0, v1
	v_mul_f32_e32 v1, 0x3fb8aa3b, v0
	v_add_f32_e32 v0, v0, v0
	v_mul_f32_e32 v2, 0x3fb8aa3b, v0
	v_exp_f32_e32 v78, v1
	v_fmamk_f32 v1, v0, 0x3c088889, v189
	v_exp_f32_e32 v2, v2
	v_fmaak_f32 v1, v0, v1, 0x3e2aaaab
	v_fma_f32 v1, v0, v1, 0.5
	v_fma_f32 v1, v0, v1, 1.0
	v_mul_f32_e64 v1, v1, -v0
	v_sub_f32_e32 v2, 1.0, v2
	v_cmp_lt_f32_e32 vcc, s4, v0
	s_nop 1
	v_cndmask_b32_e32 v0, v2, v1, vcc
	v_add_f32_e32 v1, v11, v7
	v_mul_f32_e32 v1, 0xbfb8aa3b, v1
	v_exp_f32_e32 v1, v1
	v_sqrt_f32_e32 v82, v0
	v_add_f32_e32 v0, v27, v3
	v_mul_f32_e32 v0, 0xbfb8aa3b, v0
	v_add_f32_e32 v1, 1.0, v1
	v_rcp_f32_e32 v75, v1
	v_mul_f32_e32 v1, 0xbfb8aa3b, v19
	v_exp_f32_e32 v1, v1
	v_exp_f32_e32 v0, v0
	v_add_f32_e32 v2, 1.0, v1
	v_cmp_gt_f32_e32 vcc, s28, v2
	v_add_f32_e32 v0, 1.0, v0
	v_rcp_f32_e32 v0, v0
	v_cndmask_b32_e64 v3, 0, 32, vcc
	v_ldexp_f32 v2, v2, v3
	v_log_f32_e32 v2, v2
	v_mul_f32_e32 v0, 0xc1000000, v0
	v_mul_f32_e32 v3, 0x3f317217, v2
	v_fma_f32 v3, v2, s0, -v3
	v_fmac_f32_e32 v3, 0x3377d1cf, v2
	v_fmac_f32_e32 v3, 0x3f317217, v2
	v_cmp_lt_f32_e64 s[6:7], |v2|, s1
	s_nop 1
	v_cndmask_b32_e64 v2, v2, v3, s[6:7]
	v_cndmask_b32_e32 v3, 0, v201, vcc
	v_sub_f32_e32 v2, v2, v3
	v_fmamk_f32 v3, v1, 0xbe800000, v188
	v_fma_f32 v3, -v1, v3, 0.5
	v_fma_f32 v3, -v1, v3, 1.0
	v_mul_f32_e32 v3, v1, v3
	v_cmp_gt_f32_e64 s[6:7], s3, v1
	v_cmp_gt_f32_e32 vcc, s2, v19
	s_nop 0
	v_cndmask_b32_e64 v1, v2, v3, s[6:7]
	v_cndmask_b32_e64 v1, v1, -v19, vcc
	v_mul_f32_e32 v0, v0, v1
	v_mul_f32_e32 v1, 0x3fb8aa3b, v0
	v_add_f32_e32 v0, v0, v0
	v_mul_f32_e32 v2, 0x3fb8aa3b, v0
	v_exp_f32_e32 v79, v1
	v_fmamk_f32 v1, v0, 0x3c088889, v189
	v_exp_f32_e32 v2, v2
	v_fmaak_f32 v1, v0, v1, 0x3e2aaaab
	v_fma_f32 v1, v0, v1, 0.5
	v_fma_f32 v1, v0, v1, 1.0
	v_mul_f32_e64 v1, v1, -v0
	v_sub_f32_e32 v2, 1.0, v2
	v_cmp_lt_f32_e32 vcc, s4, v0
	s_nop 1
	v_cndmask_b32_e32 v0, v2, v1, vcc
	v_sqrt_f32_e32 v83, v0
	global_load_dwordx4 v[4:7], v168, s[10:11] offset:96
	global_load_dwordx4 v[0:3], v168, s[12:13] offset:96
	global_load_dwordx4 v[8:11], v168, s[8:9] offset:96
	ds_read_b128 v[40:43], v124 offset:96
	s_waitcnt vmcnt(2)
	v_add_f32_e32 v4, v28, v4
	v_mul_f32_e32 v4, 0xbfb8aa3b, v4
	v_exp_f32_e32 v4, v4
	s_waitcnt vmcnt(1)
	v_add_f32_e32 v0, v12, v0
	v_mul_f32_e32 v0, 0xbfb8aa3b, v0
	v_exp_f32_e32 v0, v0
	v_add_f32_e32 v4, 1.0, v4
	v_rcp_f32_e32 v4, v4
	v_add_f32_e32 v1, v13, v1
	v_add_f32_e32 v0, 1.0, v0
	v_rcp_f32_e32 v84, v0
	v_mul_f32_e32 v0, 0xc1000000, v4
	s_waitcnt vmcnt(0)
	v_mul_f32_e32 v4, 0xbfb8aa3b, v8
	v_exp_f32_e32 v4, v4
	v_mul_f32_e32 v1, 0xbfb8aa3b, v1
	v_exp_f32_e32 v1, v1
	v_add_f32_e32 v12, 1.0, v4
	v_cmp_gt_f32_e32 vcc, s28, v12
	v_add_f32_e32 v1, 1.0, v1
	v_rcp_f32_e32 v85, v1
	v_cndmask_b32_e64 v16, 0, 32, vcc
	v_ldexp_f32 v12, v12, v16
	v_log_f32_e32 v12, v12
	v_mul_f32_e32 v1, 0xbfb8aa3b, v9
	v_exp_f32_e32 v1, v1
	v_mul_f32_e32 v16, 0x3f317217, v12
	v_fma_f32 v16, v12, s0, -v16
	v_fmac_f32_e32 v16, 0x3377d1cf, v12
	v_fmac_f32_e32 v16, 0x3f317217, v12
	v_cmp_lt_f32_e64 s[6:7], |v12|, s1
	s_nop 1
	v_cndmask_b32_e64 v12, v12, v16, s[6:7]
	v_cndmask_b32_e32 v16, 0, v201, vcc
	v_sub_f32_e32 v12, v12, v16
	v_fmamk_f32 v16, v4, 0xbe800000, v188
	v_fma_f32 v16, -v4, v16, 0.5
	v_fma_f32 v16, -v4, v16, 1.0
	v_mul_f32_e32 v16, v4, v16
	v_cmp_gt_f32_e64 s[6:7], s3, v4
	v_cmp_gt_f32_e32 vcc, s2, v8
	s_nop 0
	v_cndmask_b32_e64 v4, v12, v16, s[6:7]
	v_cndmask_b32_e64 v4, v4, -v8, vcc
	v_mul_f32_e32 v0, v0, v4
	v_mul_f32_e32 v4, 0x3fb8aa3b, v0
	v_add_f32_e32 v0, v0, v0
	v_mul_f32_e32 v8, 0x3fb8aa3b, v0
	v_exp_f32_e32 v86, v4
	v_fmamk_f32 v4, v0, 0x3c088889, v189
	v_exp_f32_e32 v8, v8
	v_fmaak_f32 v4, v0, v4, 0x3e2aaaab
	v_fma_f32 v4, v0, v4, 0.5
	v_fma_f32 v4, v0, v4, 1.0
	v_mul_f32_e64 v4, v4, -v0
	v_sub_f32_e32 v8, 1.0, v8
	v_cmp_lt_f32_e32 vcc, s4, v0
	s_nop 1
	v_cndmask_b32_e32 v0, v8, v4, vcc
	v_add_f32_e32 v4, 1.0, v1
	v_cmp_gt_f32_e32 vcc, s28, v4
	v_sqrt_f32_e32 v88, v0
	v_add_f32_e32 v0, v29, v5
	v_cndmask_b32_e64 v5, 0, 32, vcc
	v_ldexp_f32 v4, v4, v5
	v_log_f32_e32 v4, v4
	v_mul_f32_e32 v0, 0xbfb8aa3b, v0
	v_exp_f32_e32 v0, v0
	v_mul_f32_e32 v5, 0x3f317217, v4
	v_fma_f32 v5, v4, s0, -v5
	v_fmac_f32_e32 v5, 0x3377d1cf, v4
	v_fmac_f32_e32 v5, 0x3f317217, v4
	v_cmp_lt_f32_e64 s[6:7], |v4|, s1
	v_add_f32_e32 v0, 1.0, v0
	v_rcp_f32_e32 v0, v0
	v_cndmask_b32_e64 v4, v4, v5, s[6:7]
	v_cndmask_b32_e32 v5, 0, v201, vcc
	v_sub_f32_e32 v4, v4, v5
	v_fmamk_f32 v5, v1, 0xbe800000, v188
	v_fma_f32 v5, -v1, v5, 0.5
	v_fma_f32 v5, -v1, v5, 1.0
	v_mul_f32_e32 v5, v1, v5
	v_cmp_gt_f32_e64 s[6:7], s3, v1
	v_cmp_gt_f32_e32 vcc, s2, v9
	v_mul_f32_e32 v0, 0xc1000000, v0
	v_cndmask_b32_e64 v1, v4, v5, s[6:7]
	v_cndmask_b32_e64 v1, v1, -v9, vcc
	v_mul_f32_e32 v0, v0, v1
	v_mul_f32_e32 v1, 0x3fb8aa3b, v0
	v_add_f32_e32 v0, v0, v0
	v_mul_f32_e32 v4, 0x3fb8aa3b, v0
	v_exp_f32_e32 v87, v1
	v_fmamk_f32 v1, v0, 0x3c088889, v189
	v_exp_f32_e32 v4, v4
	v_fmaak_f32 v1, v0, v1, 0x3e2aaaab
	v_fma_f32 v1, v0, v1, 0.5
	v_fma_f32 v1, v0, v1, 1.0
	v_mul_f32_e64 v1, v1, -v0
	v_sub_f32_e32 v4, 1.0, v4
	v_cmp_lt_f32_e32 vcc, s4, v0
	s_nop 1
	v_cndmask_b32_e32 v0, v4, v1, vcc
	v_add_f32_e32 v1, v14, v2
	v_mul_f32_e32 v1, 0xbfb8aa3b, v1
	v_exp_f32_e32 v1, v1
	v_sqrt_f32_e32 v89, v0
	v_add_f32_e32 v0, v30, v6
	v_mul_f32_e32 v0, 0xbfb8aa3b, v0
	v_add_f32_e32 v1, 1.0, v1
	v_rcp_f32_e32 v90, v1
	v_mul_f32_e32 v1, 0xbfb8aa3b, v10
	v_exp_f32_e32 v1, v1
	v_exp_f32_e32 v0, v0
	v_add_f32_e32 v2, 1.0, v1
	v_cmp_gt_f32_e32 vcc, s28, v2
	v_add_f32_e32 v0, 1.0, v0
	v_rcp_f32_e32 v0, v0
	v_cndmask_b32_e64 v4, 0, 32, vcc
	v_ldexp_f32 v2, v2, v4
	v_log_f32_e32 v2, v2
	v_mul_f32_e32 v0, 0xc1000000, v0
	v_mul_f32_e32 v4, 0x3f317217, v2
	v_fma_f32 v4, v2, s0, -v4
	v_fmac_f32_e32 v4, 0x3377d1cf, v2
	v_fmac_f32_e32 v4, 0x3f317217, v2
	v_cmp_lt_f32_e64 s[6:7], |v2|, s1
	s_nop 1
	v_cndmask_b32_e64 v2, v2, v4, s[6:7]
	v_cndmask_b32_e32 v4, 0, v201, vcc
	v_sub_f32_e32 v2, v2, v4
	v_fmamk_f32 v4, v1, 0xbe800000, v188
	v_fma_f32 v4, -v1, v4, 0.5
	v_fma_f32 v4, -v1, v4, 1.0
	v_mul_f32_e32 v4, v1, v4
	v_cmp_gt_f32_e64 s[6:7], s3, v1
	v_cmp_gt_f32_e32 vcc, s2, v10
	s_nop 0
	v_cndmask_b32_e64 v1, v2, v4, s[6:7]
	v_cndmask_b32_e64 v1, v1, -v10, vcc
	v_mul_f32_e32 v0, v0, v1
	v_mul_f32_e32 v1, 0x3fb8aa3b, v0
	v_add_f32_e32 v0, v0, v0
	v_mul_f32_e32 v2, 0x3fb8aa3b, v0
	v_exp_f32_e32 v92, v1
	v_fmamk_f32 v1, v0, 0x3c088889, v189
	v_exp_f32_e32 v2, v2
	v_fmaak_f32 v1, v0, v1, 0x3e2aaaab
	v_fma_f32 v1, v0, v1, 0.5
	v_fma_f32 v1, v0, v1, 1.0
	v_mul_f32_e64 v1, v1, -v0
	v_sub_f32_e32 v2, 1.0, v2
	v_cmp_lt_f32_e32 vcc, s4, v0
	s_nop 1
	v_cndmask_b32_e32 v0, v2, v1, vcc
	v_add_f32_e32 v1, v15, v3
	v_mul_f32_e32 v1, 0xbfb8aa3b, v1
	v_exp_f32_e32 v1, v1
	v_sqrt_f32_e32 v94, v0
	v_add_f32_e32 v0, v31, v7
	v_mul_f32_e32 v0, 0xbfb8aa3b, v0
	v_add_f32_e32 v1, 1.0, v1
	v_rcp_f32_e32 v91, v1
	v_mul_f32_e32 v1, 0xbfb8aa3b, v11
	v_exp_f32_e32 v1, v1
	v_exp_f32_e32 v0, v0
	v_add_f32_e32 v2, 1.0, v1
	v_cmp_gt_f32_e32 vcc, s28, v2
	v_add_f32_e32 v0, 1.0, v0
	v_rcp_f32_e32 v0, v0
	v_cndmask_b32_e64 v3, 0, 32, vcc
	v_ldexp_f32 v2, v2, v3
	v_log_f32_e32 v2, v2
	v_mul_f32_e32 v0, 0xc1000000, v0
	v_mul_f32_e32 v3, 0x3f317217, v2
	v_fma_f32 v3, v2, s0, -v3
	v_fmac_f32_e32 v3, 0x3377d1cf, v2
	v_fmac_f32_e32 v3, 0x3f317217, v2
	v_cmp_lt_f32_e64 s[6:7], |v2|, s1
	s_nop 1
	v_cndmask_b32_e64 v2, v2, v3, s[6:7]
	v_cndmask_b32_e32 v3, 0, v201, vcc
	v_sub_f32_e32 v2, v2, v3
	v_fmamk_f32 v3, v1, 0xbe800000, v188
	v_fma_f32 v3, -v1, v3, 0.5
	v_fma_f32 v3, -v1, v3, 1.0
	v_mul_f32_e32 v3, v1, v3
	v_cmp_gt_f32_e64 s[6:7], s3, v1
	v_cmp_gt_f32_e32 vcc, s2, v11
	s_nop 0
	v_cndmask_b32_e64 v1, v2, v3, s[6:7]
	v_cndmask_b32_e64 v1, v1, -v11, vcc
	v_mul_f32_e32 v0, v0, v1
	v_mul_f32_e32 v1, 0x3fb8aa3b, v0
	v_add_f32_e32 v0, v0, v0
	v_mul_f32_e32 v2, 0x3fb8aa3b, v0
	v_exp_f32_e32 v93, v1
	v_fmamk_f32 v1, v0, 0x3c088889, v189
	v_exp_f32_e32 v2, v2
	v_fmaak_f32 v1, v0, v1, 0x3e2aaaab
	v_fma_f32 v1, v0, v1, 0.5
	v_fma_f32 v1, v0, v1, 1.0
	v_mul_f32_e64 v1, v1, -v0
	v_sub_f32_e32 v2, 1.0, v2
	v_cmp_lt_f32_e32 vcc, s4, v0
	s_nop 1
	v_cndmask_b32_e32 v0, v2, v1, vcc
	v_sqrt_f32_e32 v95, v0
	v_or_b32_e32 v0, 0x1000, v100
	v_mov_b32_e32 v1, v169
	v_lshl_add_u64 v[100:101], v[96:97], 0, v[0:1]
	v_lshl_add_u64 v[102:103], v[98:99], 0, v[0:1]
	global_load_dwordx4 v[0:3], v[100:101], off
	global_load_dwordx4 v[4:7], v[102:103], off
	s_waitcnt vmcnt(1)
	v_mfma_f32_32x32x16_bf16 v[16:31], v[0:3], v[56:59], 0
	s_waitcnt vmcnt(0)
	v_mfma_f32_32x32x16_bf16 v[0:15], v[4:7], v[56:59], 0
	global_load_dwordx4 v[56:59], v[100:101], off offset:32
	global_load_dwordx4 v[96:99], v[102:103], off offset:32
	s_waitcnt vmcnt(1)
	v_mfma_f32_32x32x16_bf16 v[16:31], v[56:59], v[52:55], v[16:31]
	s_waitcnt vmcnt(0)
	v_mfma_f32_32x32x16_bf16 v[0:15], v[96:99], v[52:55], v[0:15]
	global_load_dwordx4 v[52:55], v[100:101], off offset:64
	global_load_dwordx4 v[56:59], v[102:103], off offset:64
	s_waitcnt vmcnt(1)
	v_mfma_f32_32x32x16_bf16 v[16:31], v[52:55], v[48:51], v[16:31]
	s_waitcnt vmcnt(0)
	v_mfma_f32_32x32x16_bf16 v[0:15], v[56:59], v[48:51], v[0:15]
	global_load_dwordx4 v[48:51], v[100:101], off offset:96
	global_load_dwordx4 v[52:55], v[102:103], off offset:96
	s_waitcnt vmcnt(0)
	v_mfma_f32_32x32x16_bf16 v[0:15], v[52:55], v[44:47], v[0:15]
	global_load_dwordx4 v[52:55], v168, s[10:11] offset:128
	global_load_dwordx4 v[56:59], v168, s[12:13] offset:128
	global_load_dwordx4 v[96:99], v168, s[8:9] offset:128
	s_waitcnt vmcnt(1)
	s_nop 7
	v_add_f32_e32 v0, v0, v56
	v_mfma_f32_32x32x16_bf16 v[16:31], v[48:51], v[44:47], v[16:31]
	v_mul_f32_e32 v0, 0xbfb8aa3b, v0
	v_exp_f32_e32 v0, v0
	v_add_f32_e32 v1, v1, v57
	v_mul_f32_e32 v1, 0xbfb8aa3b, v1
	v_exp_f32_e32 v1, v1
	v_add_f32_e32 v0, 1.0, v0
	v_rcp_f32_e32 v56, v0
	s_nop 4
	v_add_f32_e32 v16, v16, v52
	v_mul_f32_e32 v16, 0xbfb8aa3b, v16
	v_exp_f32_e32 v16, v16
	v_add_f32_e32 v1, 1.0, v1
	v_rcp_f32_e32 v57, v1
	s_waitcnt vmcnt(0)
	v_mul_f32_e32 v1, 0xbfb8aa3b, v97
	v_add_f32_e32 v16, 1.0, v16
	v_rcp_f32_e32 v16, v16
	v_exp_f32_e32 v1, v1
	ds_read_b128 v[48:51], v124 offset:128
	ds_read_b128 v[44:47], v124 offset:160
	v_mul_f32_e32 v0, 0xc1000000, v16
	v_mul_f32_e32 v16, 0xbfb8aa3b, v96
	v_exp_f32_e32 v16, v16
	s_nop 0
	v_add_f32_e32 v52, 1.0, v16
	v_cmp_gt_f32_e32 vcc, s28, v52
	s_nop 1
	v_cndmask_b32_e64 v100, 0, 32, vcc
	v_ldexp_f32 v52, v52, v100
	v_log_f32_e32 v52, v52
	s_nop 0
	v_mul_f32_e32 v100, 0x3f317217, v52
	v_fma_f32 v100, v52, s0, -v100
	v_fmac_f32_e32 v100, 0x3377d1cf, v52
	v_fmac_f32_e32 v100, 0x3f317217, v52
	v_cmp_lt_f32_e64 s[6:7], |v52|, s1
	s_nop 1
	v_cndmask_b32_e64 v52, v52, v100, s[6:7]
	v_cndmask_b32_e32 v100, 0, v201, vcc
	v_sub_f32_e32 v52, v52, v100
	v_fmamk_f32 v100, v16, 0xbe800000, v188
	v_fma_f32 v100, -v16, v100, 0.5
	v_fma_f32 v100, -v16, v100, 1.0
	v_mul_f32_e32 v100, v16, v100
	v_cmp_gt_f32_e64 s[6:7], s3, v16
	v_cmp_gt_f32_e32 vcc, s2, v96
	s_nop 0
	v_cndmask_b32_e64 v16, v52, v100, s[6:7]
	v_cndmask_b32_e64 v16, v16, -v96, vcc
	v_mul_f32_e32 v0, v0, v16
	v_mul_f32_e32 v16, 0x3fb8aa3b, v0
	v_add_f32_e32 v0, v0, v0
	v_mul_f32_e32 v52, 0x3fb8aa3b, v0
	v_exp_f32_e32 v96, v16
	v_fmamk_f32 v16, v0, 0x3c088889, v189
	v_exp_f32_e32 v52, v52
	v_fmaak_f32 v16, v0, v16, 0x3e2aaaab
	v_fma_f32 v16, v0, v16, 0.5
	v_fma_f32 v16, v0, v16, 1.0
	v_mul_f32_e64 v16, v16, -v0
	v_sub_f32_e32 v52, 1.0, v52
	v_cmp_lt_f32_e32 vcc, s4, v0
	s_nop 1
	v_cndmask_b32_e32 v0, v52, v16, vcc
	v_add_f32_e32 v16, 1.0, v1
	v_cmp_gt_f32_e32 vcc, s28, v16
	v_sqrt_f32_e32 v100, v0
	v_add_f32_e32 v0, v17, v53
	v_cndmask_b32_e64 v17, 0, 32, vcc
	v_ldexp_f32 v16, v16, v17
	v_log_f32_e32 v16, v16
	v_mul_f32_e32 v0, 0xbfb8aa3b, v0
	v_exp_f32_e32 v0, v0
	v_mul_f32_e32 v17, 0x3f317217, v16
	v_fma_f32 v17, v16, s0, -v17
	v_fmac_f32_e32 v17, 0x3377d1cf, v16
	v_fmac_f32_e32 v17, 0x3f317217, v16
	v_cmp_lt_f32_e64 s[6:7], |v16|, s1
	v_add_f32_e32 v0, 1.0, v0
	v_rcp_f32_e32 v0, v0
	v_cndmask_b32_e64 v16, v16, v17, s[6:7]
	v_cndmask_b32_e32 v17, 0, v201, vcc
	v_sub_f32_e32 v16, v16, v17
	v_fmamk_f32 v17, v1, 0xbe800000, v188
	v_fma_f32 v17, -v1, v17, 0.5
	v_fma_f32 v17, -v1, v17, 1.0
	v_mul_f32_e32 v17, v1, v17
	v_cmp_gt_f32_e64 s[6:7], s3, v1
	v_cmp_gt_f32_e32 vcc, s2, v97
	v_mul_f32_e32 v0, 0xc1000000, v0
	v_cndmask_b32_e64 v1, v16, v17, s[6:7]
	v_cndmask_b32_e64 v1, v1, -v97, vcc
	v_mul_f32_e32 v0, v0, v1
	v_mul_f32_e32 v1, 0x3fb8aa3b, v0
	v_add_f32_e32 v0, v0, v0
	v_mul_f32_e32 v16, 0x3fb8aa3b, v0
	v_exp_f32_e32 v97, v1
	v_fmamk_f32 v1, v0, 0x3c088889, v189
	v_exp_f32_e32 v16, v16
	v_fmaak_f32 v1, v0, v1, 0x3e2aaaab
	v_fma_f32 v1, v0, v1, 0.5
	v_fma_f32 v1, v0, v1, 1.0
	v_mul_f32_e64 v1, v1, -v0
	v_sub_f32_e32 v16, 1.0, v16
	v_cmp_lt_f32_e32 vcc, s4, v0
	s_nop 1
	v_cndmask_b32_e32 v0, v16, v1, vcc
	v_add_f32_e32 v1, v2, v58
	v_mul_f32_e32 v1, 0xbfb8aa3b, v1
	v_exp_f32_e32 v1, v1
	v_sqrt_f32_e32 v101, v0
	v_add_f32_e32 v0, v18, v54
	v_mul_f32_e32 v0, 0xbfb8aa3b, v0
	v_add_f32_e32 v1, 1.0, v1
	v_rcp_f32_e32 v58, v1
	v_mul_f32_e32 v1, 0xbfb8aa3b, v98
	v_exp_f32_e32 v1, v1
	v_exp_f32_e32 v0, v0
	v_add_f32_e32 v2, 1.0, v1
	v_cmp_gt_f32_e32 vcc, s28, v2
	v_add_f32_e32 v0, 1.0, v0
	v_rcp_f32_e32 v0, v0
	v_cndmask_b32_e64 v16, 0, 32, vcc
	v_ldexp_f32 v2, v2, v16
	v_log_f32_e32 v2, v2
	v_mul_f32_e32 v0, 0xc1000000, v0
	v_mul_f32_e32 v16, 0x3f317217, v2
	v_fma_f32 v16, v2, s0, -v16
	v_fmac_f32_e32 v16, 0x3377d1cf, v2
	v_fmac_f32_e32 v16, 0x3f317217, v2
	v_cmp_lt_f32_e64 s[6:7], |v2|, s1
	s_nop 1
	v_cndmask_b32_e64 v2, v2, v16, s[6:7]
	v_cndmask_b32_e32 v16, 0, v201, vcc
	v_sub_f32_e32 v2, v2, v16
	v_fmamk_f32 v16, v1, 0xbe800000, v188
	v_fma_f32 v16, -v1, v16, 0.5
	v_fma_f32 v16, -v1, v16, 1.0
	v_mul_f32_e32 v16, v1, v16
	v_cmp_gt_f32_e64 s[6:7], s3, v1
	v_cmp_gt_f32_e32 vcc, s2, v98
	s_nop 0
	v_cndmask_b32_e64 v1, v2, v16, s[6:7]
	v_cndmask_b32_e64 v1, v1, -v98, vcc
	v_mul_f32_e32 v0, v0, v1
	v_mul_f32_e32 v1, 0x3fb8aa3b, v0
	v_add_f32_e32 v0, v0, v0
	v_mul_f32_e32 v2, 0x3fb8aa3b, v0
	v_exp_f32_e32 v98, v1
	v_fmamk_f32 v1, v0, 0x3c088889, v189
	v_exp_f32_e32 v2, v2
	v_fmaak_f32 v1, v0, v1, 0x3e2aaaab
	v_fma_f32 v1, v0, v1, 0.5
	v_fma_f32 v1, v0, v1, 1.0
	v_mul_f32_e64 v1, v1, -v0
	v_sub_f32_e32 v2, 1.0, v2
	v_cmp_lt_f32_e32 vcc, s4, v0
	s_nop 1
	v_cndmask_b32_e32 v0, v2, v1, vcc
	v_add_f32_e32 v1, v3, v59
	v_mul_f32_e32 v1, 0xbfb8aa3b, v1
	v_exp_f32_e32 v1, v1
	v_sqrt_f32_e32 v102, v0
	v_add_f32_e32 v0, v19, v55
	v_mul_f32_e32 v0, 0xbfb8aa3b, v0
	v_add_f32_e32 v1, 1.0, v1
	v_rcp_f32_e32 v59, v1
	v_mul_f32_e32 v1, 0xbfb8aa3b, v99
	v_exp_f32_e32 v1, v1
	v_exp_f32_e32 v0, v0
	v_add_f32_e32 v2, 1.0, v1
	v_cmp_gt_f32_e32 vcc, s28, v2
	v_add_f32_e32 v0, 1.0, v0
	v_rcp_f32_e32 v0, v0
	v_cndmask_b32_e64 v3, 0, 32, vcc
	v_ldexp_f32 v2, v2, v3
	v_log_f32_e32 v2, v2
	v_mul_f32_e32 v0, 0xc1000000, v0
	v_mul_f32_e32 v3, 0x3f317217, v2
	v_fma_f32 v3, v2, s0, -v3
	v_fmac_f32_e32 v3, 0x3377d1cf, v2
	v_fmac_f32_e32 v3, 0x3f317217, v2
	v_cmp_lt_f32_e64 s[6:7], |v2|, s1
	s_nop 1
	v_cndmask_b32_e64 v2, v2, v3, s[6:7]
	v_cndmask_b32_e32 v3, 0, v201, vcc
	v_sub_f32_e32 v2, v2, v3
	v_fmamk_f32 v3, v1, 0xbe800000, v188
	v_fma_f32 v3, -v1, v3, 0.5
	v_fma_f32 v3, -v1, v3, 1.0
	v_mul_f32_e32 v3, v1, v3
	v_cmp_gt_f32_e64 s[6:7], s3, v1
	v_cmp_gt_f32_e32 vcc, s2, v99
	s_nop 0
	v_cndmask_b32_e64 v1, v2, v3, s[6:7]
	v_cndmask_b32_e64 v1, v1, -v99, vcc
	v_mul_f32_e32 v0, v0, v1
	v_mul_f32_e32 v1, 0x3fb8aa3b, v0
	v_add_f32_e32 v0, v0, v0
	v_mul_f32_e32 v2, 0x3fb8aa3b, v0
	v_exp_f32_e32 v99, v1
	v_fmamk_f32 v1, v0, 0x3c088889, v189
	v_exp_f32_e32 v2, v2
	v_fmaak_f32 v1, v0, v1, 0x3e2aaaab
	v_fma_f32 v1, v0, v1, 0.5
	v_fma_f32 v1, v0, v1, 1.0
	v_mul_f32_e64 v1, v1, -v0
	v_sub_f32_e32 v2, 1.0, v2
	v_cmp_lt_f32_e32 vcc, s4, v0
	s_nop 1
	v_cndmask_b32_e32 v0, v2, v1, vcc
	v_sqrt_f32_e32 v103, v0
	global_load_dwordx4 v[16:19], v168, s[10:11] offset:160
	global_load_dwordx4 v[0:3], v168, s[12:13] offset:160
	global_load_dwordx4 v[52:55], v168, s[8:9] offset:160
	s_waitcnt vmcnt(2)
	v_add_f32_e32 v16, v20, v16
	v_mul_f32_e32 v16, 0xbfb8aa3b, v16
	v_exp_f32_e32 v16, v16
	s_waitcnt vmcnt(1)
	v_add_f32_e32 v0, v4, v0
	v_mul_f32_e32 v0, 0xbfb8aa3b, v0
	v_exp_f32_e32 v0, v0
	v_add_f32_e32 v16, 1.0, v16
	s_waitcnt vmcnt(0)
	v_mul_f32_e32 v4, 0xbfb8aa3b, v52
	v_rcp_f32_e32 v16, v16
	v_exp_f32_e32 v4, v4
	v_add_f32_e32 v0, 1.0, v0
	v_rcp_f32_e32 v104, v0
	v_mul_f32_e32 v0, 0xc1000000, v16
	v_add_f32_e32 v16, 1.0, v4
	v_cmp_gt_f32_e32 vcc, s28, v16
	v_add_f32_e32 v1, v5, v1
	v_mul_f32_e32 v1, 0xbfb8aa3b, v1
	v_cndmask_b32_e64 v20, 0, 32, vcc
	v_ldexp_f32 v16, v16, v20
	v_log_f32_e32 v16, v16
	v_exp_f32_e32 v1, v1
	v_mul_f32_e32 v20, 0x3f317217, v16
	v_fma_f32 v20, v16, s0, -v20
	v_fmac_f32_e32 v20, 0x3377d1cf, v16
	v_fmac_f32_e32 v20, 0x3f317217, v16
	v_cmp_lt_f32_e64 s[6:7], |v16|, s1
	v_add_f32_e32 v1, 1.0, v1
	v_rcp_f32_e32 v105, v1
	v_cndmask_b32_e64 v16, v16, v20, s[6:7]
	v_cndmask_b32_e32 v20, 0, v201, vcc
	v_sub_f32_e32 v16, v16, v20
	v_fmamk_f32 v20, v4, 0xbe800000, v188
	v_fma_f32 v20, -v4, v20, 0.5
	v_fma_f32 v20, -v4, v20, 1.0
	v_mul_f32_e32 v20, v4, v20
	v_cmp_gt_f32_e64 s[6:7], s3, v4
	v_cmp_gt_f32_e32 vcc, s2, v52
	v_mul_f32_e32 v1, 0xbfb8aa3b, v53
	v_cndmask_b32_e64 v4, v16, v20, s[6:7]
	v_cndmask_b32_e64 v4, v4, -v52, vcc
	v_mul_f32_e32 v0, v0, v4
	v_mul_f32_e32 v4, 0x3fb8aa3b, v0
	v_add_f32_e32 v0, v0, v0
	v_mul_f32_e32 v16, 0x3fb8aa3b, v0
	v_exp_f32_e32 v52, v4
	v_fmamk_f32 v4, v0, 0x3c088889, v189
	v_exp_f32_e32 v16, v16
	v_fmaak_f32 v4, v0, v4, 0x3e2aaaab
	v_exp_f32_e32 v1, v1
	v_fma_f32 v4, v0, v4, 0.5
	v_fma_f32 v4, v0, v4, 1.0
	v_mul_f32_e64 v4, v4, -v0
	v_sub_f32_e32 v16, 1.0, v16
	v_cmp_lt_f32_e32 vcc, s4, v0
	s_nop 1
	v_cndmask_b32_e32 v0, v16, v4, vcc
	v_add_f32_e32 v4, 1.0, v1
	v_cmp_gt_f32_e32 vcc, s28, v4
	v_sqrt_f32_e32 v106, v0
	v_add_f32_e32 v0, v21, v17
	v_cndmask_b32_e64 v5, 0, 32, vcc
	v_ldexp_f32 v4, v4, v5
	v_log_f32_e32 v4, v4
	v_mul_f32_e32 v0, 0xbfb8aa3b, v0
	v_exp_f32_e32 v0, v0
	v_mul_f32_e32 v5, 0x3f317217, v4
	v_fma_f32 v5, v4, s0, -v5
	v_fmac_f32_e32 v5, 0x3377d1cf, v4
	v_fmac_f32_e32 v5, 0x3f317217, v4
	v_cmp_lt_f32_e64 s[6:7], |v4|, s1
	v_add_f32_e32 v0, 1.0, v0
	v_rcp_f32_e32 v0, v0
	v_cndmask_b32_e64 v4, v4, v5, s[6:7]
	v_cndmask_b32_e32 v5, 0, v201, vcc
	v_sub_f32_e32 v4, v4, v5
	v_fmamk_f32 v5, v1, 0xbe800000, v188
	v_fma_f32 v5, -v1, v5, 0.5
	v_fma_f32 v5, -v1, v5, 1.0
	v_mul_f32_e32 v5, v1, v5
	v_cmp_gt_f32_e64 s[6:7], s3, v1
	v_cmp_gt_f32_e32 vcc, s2, v53
	v_mul_f32_e32 v0, 0xc1000000, v0
	v_cndmask_b32_e64 v1, v4, v5, s[6:7]
	v_cndmask_b32_e64 v1, v1, -v53, vcc
	v_mul_f32_e32 v0, v0, v1
	v_mul_f32_e32 v1, 0x3fb8aa3b, v0
	v_add_f32_e32 v0, v0, v0
	v_mul_f32_e32 v4, 0x3fb8aa3b, v0
	v_exp_f32_e32 v53, v1
	v_fmamk_f32 v1, v0, 0x3c088889, v189
	v_exp_f32_e32 v4, v4
	v_fmaak_f32 v1, v0, v1, 0x3e2aaaab
	v_fma_f32 v1, v0, v1, 0.5
	v_fma_f32 v1, v0, v1, 1.0
	v_mul_f32_e64 v1, v1, -v0
	v_sub_f32_e32 v4, 1.0, v4
	v_cmp_lt_f32_e32 vcc, s4, v0
	s_nop 1
	v_cndmask_b32_e32 v0, v4, v1, vcc
	v_add_f32_e32 v1, v6, v2
	v_mul_f32_e32 v1, 0xbfb8aa3b, v1
	v_exp_f32_e32 v1, v1
	v_sqrt_f32_e32 v107, v0
	v_add_f32_e32 v0, v22, v18
	v_mul_f32_e32 v0, 0xbfb8aa3b, v0
	v_add_f32_e32 v1, 1.0, v1
	v_rcp_f32_e32 v108, v1
	v_mul_f32_e32 v1, 0xbfb8aa3b, v54
	v_exp_f32_e32 v1, v1
	v_exp_f32_e32 v0, v0
	v_add_f32_e32 v2, 1.0, v1
	v_cmp_gt_f32_e32 vcc, s28, v2
	v_add_f32_e32 v0, 1.0, v0
	v_rcp_f32_e32 v0, v0
	v_cndmask_b32_e64 v4, 0, 32, vcc
	v_ldexp_f32 v2, v2, v4
	v_log_f32_e32 v2, v2
	v_mul_f32_e32 v0, 0xc1000000, v0
	v_mul_f32_e32 v4, 0x3f317217, v2
	v_fma_f32 v4, v2, s0, -v4
	v_fmac_f32_e32 v4, 0x3377d1cf, v2
	v_fmac_f32_e32 v4, 0x3f317217, v2
	v_cmp_lt_f32_e64 s[6:7], |v2|, s1
	s_nop 1
	v_cndmask_b32_e64 v2, v2, v4, s[6:7]
	v_cndmask_b32_e32 v4, 0, v201, vcc
	v_sub_f32_e32 v2, v2, v4
	v_fmamk_f32 v4, v1, 0xbe800000, v188
	v_fma_f32 v4, -v1, v4, 0.5
	v_fma_f32 v4, -v1, v4, 1.0
	v_mul_f32_e32 v4, v1, v4
	v_cmp_gt_f32_e64 s[6:7], s3, v1
	v_cmp_gt_f32_e32 vcc, s2, v54
	s_nop 0
	v_cndmask_b32_e64 v1, v2, v4, s[6:7]
	v_cndmask_b32_e64 v1, v1, -v54, vcc
	v_mul_f32_e32 v0, v0, v1
	v_mul_f32_e32 v1, 0x3fb8aa3b, v0
	v_add_f32_e32 v0, v0, v0
	v_mul_f32_e32 v2, 0x3fb8aa3b, v0
	v_exp_f32_e32 v54, v1
	v_fmamk_f32 v1, v0, 0x3c088889, v189
	v_exp_f32_e32 v2, v2
	v_fmaak_f32 v1, v0, v1, 0x3e2aaaab
	v_fma_f32 v1, v0, v1, 0.5
	v_fma_f32 v1, v0, v1, 1.0
	v_mul_f32_e64 v1, v1, -v0
	v_sub_f32_e32 v2, 1.0, v2
	v_cmp_lt_f32_e32 vcc, s4, v0
	s_nop 1
	v_cndmask_b32_e32 v0, v2, v1, vcc
	v_sqrt_f32_e32 v110, v0
	v_add_f32_e32 v0, v23, v19
	v_add_f32_e32 v1, v7, v3
	global_load_dwordx4 v[4:7], v168, s[10:11] offset:192
	global_load_dwordx4 v[16:19], v168, s[12:13] offset:192
	global_load_dwordx4 v[20:23], v168, s[8:9] offset:192
	v_mul_f32_e32 v1, 0xbfb8aa3b, v1
	v_exp_f32_e32 v1, v1
	v_mul_f32_e32 v0, 0xbfb8aa3b, v0
	v_exp_f32_e32 v0, v0
	v_add_f32_e32 v1, 1.0, v1
	v_rcp_f32_e32 v109, v1
	v_mul_f32_e32 v1, 0xbfb8aa3b, v55
	v_exp_f32_e32 v1, v1
	v_add_f32_e32 v0, 1.0, v0
	v_rcp_f32_e32 v0, v0
	v_add_f32_e32 v2, 1.0, v1
	v_cmp_gt_f32_e32 vcc, s28, v2
	v_mul_f32_e32 v0, 0xc1000000, v0
	s_waitcnt vmcnt(2)
	v_add_f32_e32 v4, v24, v4
	v_cndmask_b32_e64 v3, 0, 32, vcc
	v_ldexp_f32 v2, v2, v3
	v_log_f32_e32 v2, v2
	s_waitcnt vmcnt(1)
	v_add_f32_e32 v8, v8, v16
	v_mul_f32_e32 v8, 0xbfb8aa3b, v8
	v_exp_f32_e32 v8, v8
	v_mul_f32_e32 v3, 0x3f317217, v2
	v_fma_f32 v3, v2, s0, -v3
	v_fmac_f32_e32 v3, 0x3377d1cf, v2
	v_fmac_f32_e32 v3, 0x3f317217, v2
	v_cmp_lt_f32_e64 s[6:7], |v2|, s1
	v_add_f32_e32 v8, 1.0, v8
	v_rcp_f32_e32 v112, v8
	v_cndmask_b32_e64 v2, v2, v3, s[6:7]
	v_cndmask_b32_e32 v3, 0, v201, vcc
	v_sub_f32_e32 v2, v2, v3
	v_fmamk_f32 v3, v1, 0xbe800000, v188
	v_fma_f32 v3, -v1, v3, 0.5
	v_fma_f32 v3, -v1, v3, 1.0
	v_mul_f32_e32 v3, v1, v3
	v_cmp_gt_f32_e64 s[6:7], s3, v1
	v_cmp_gt_f32_e32 vcc, s2, v55
	s_waitcnt vmcnt(0)
	v_mul_f32_e32 v8, 0xbfb8aa3b, v20
	v_cndmask_b32_e64 v1, v2, v3, s[6:7]
	v_cndmask_b32_e64 v1, v1, -v55, vcc
	v_mul_f32_e32 v0, v0, v1
	v_mul_f32_e32 v1, 0x3fb8aa3b, v0
	v_add_f32_e32 v0, v0, v0
	v_mul_f32_e32 v2, 0x3fb8aa3b, v0
	v_exp_f32_e32 v55, v1
	v_fmamk_f32 v1, v0, 0x3c088889, v189
	v_exp_f32_e32 v2, v2
	v_exp_f32_e32 v8, v8
	v_fmaak_f32 v1, v0, v1, 0x3e2aaaab
	v_fma_f32 v1, v0, v1, 0.5
	v_fma_f32 v1, v0, v1, 1.0
	v_mul_f32_e64 v1, v1, -v0
	v_sub_f32_e32 v2, 1.0, v2
	v_cmp_lt_f32_e32 vcc, s4, v0
	v_add_f32_e32 v16, 1.0, v8
	v_mul_f32_e32 v4, 0xbfb8aa3b, v4
	v_cndmask_b32_e32 v0, v2, v1, vcc
	v_cmp_gt_f32_e32 vcc, s28, v16
	v_exp_f32_e32 v4, v4
	v_sqrt_f32_e32 v111, v0
	v_cndmask_b32_e64 v24, 0, 32, vcc
	v_ldexp_f32 v16, v16, v24
	v_log_f32_e32 v16, v16
	v_add_f32_e32 v4, 1.0, v4
	v_rcp_f32_e32 v4, v4
	ds_read_b128 v[0:3], v124 offset:192
	v_mul_f32_e32 v24, 0x3f317217, v16
	v_fma_f32 v24, v16, s0, -v24
	v_fmac_f32_e32 v24, 0x3377d1cf, v16
	v_fmac_f32_e32 v24, 0x3f317217, v16
	v_cmp_lt_f32_e64 s[6:7], |v16|, s1
	v_mul_f32_e32 v4, 0xc1000000, v4
	s_nop 0
	v_cndmask_b32_e64 v16, v16, v24, s[6:7]
	v_cndmask_b32_e32 v24, 0, v201, vcc
	v_sub_f32_e32 v16, v16, v24
	v_fmamk_f32 v24, v8, 0xbe800000, v188
	v_fma_f32 v24, -v8, v24, 0.5
	v_fma_f32 v24, -v8, v24, 1.0
	v_mul_f32_e32 v24, v8, v24
	v_cmp_gt_f32_e64 s[6:7], s3, v8
	v_cmp_gt_f32_e32 vcc, s2, v20
	s_nop 0
	v_cndmask_b32_e64 v8, v16, v24, s[6:7]
	v_cndmask_b32_e64 v8, v8, -v20, vcc
	v_mul_f32_e32 v4, v4, v8
	v_mul_f32_e32 v8, 0x3fb8aa3b, v4
	v_add_f32_e32 v4, v4, v4
	v_mul_f32_e32 v16, 0x3fb8aa3b, v4
	v_exp_f32_e32 v116, v8
	v_fmamk_f32 v8, v4, 0x3c088889, v189
	v_exp_f32_e32 v16, v16
	v_fmaak_f32 v8, v4, v8, 0x3e2aaaab
	v_fma_f32 v8, v4, v8, 0.5
	v_fma_f32 v8, v4, v8, 1.0
	v_mul_f32_e64 v8, v8, -v4
	v_sub_f32_e32 v16, 1.0, v16
	v_cmp_lt_f32_e32 vcc, s4, v4
	s_nop 1
	v_cndmask_b32_e32 v4, v16, v8, vcc
	v_sqrt_f32_e32 v120, v4
	v_add_f32_e32 v4, v25, v5
	v_add_f32_e32 v5, v9, v17
	v_mul_f32_e32 v5, 0xbfb8aa3b, v5
	v_exp_f32_e32 v5, v5
	v_mul_f32_e32 v4, 0xbfb8aa3b, v4
	v_exp_f32_e32 v4, v4
	v_add_f32_e32 v5, 1.0, v5
	v_rcp_f32_e32 v113, v5
	v_mul_f32_e32 v5, 0xbfb8aa3b, v21
	v_exp_f32_e32 v5, v5
	v_add_f32_e32 v4, 1.0, v4
	v_rcp_f32_e32 v4, v4
	v_add_f32_e32 v8, 1.0, v5
	v_cmp_gt_f32_e32 vcc, s28, v8
	v_mul_f32_e32 v4, 0xc1000000, v4
	s_nop 0
	v_cndmask_b32_e64 v9, 0, 32, vcc
	v_ldexp_f32 v8, v8, v9
	v_log_f32_e32 v8, v8
	s_nop 0
	v_mul_f32_e32 v9, 0x3f317217, v8
	v_fma_f32 v9, v8, s0, -v9
	v_fmac_f32_e32 v9, 0x3377d1cf, v8
	v_fmac_f32_e32 v9, 0x3f317217, v8
	v_cmp_lt_f32_e64 s[6:7], |v8|, s1
	s_nop 1
	v_cndmask_b32_e64 v8, v8, v9, s[6:7]
	v_cndmask_b32_e32 v9, 0, v201, vcc
	v_sub_f32_e32 v8, v8, v9
	v_fmamk_f32 v9, v5, 0xbe800000, v188
	v_fma_f32 v9, -v5, v9, 0.5
	v_fma_f32 v9, -v5, v9, 1.0
	v_mul_f32_e32 v9, v5, v9
	v_cmp_gt_f32_e64 s[6:7], s3, v5
	v_cmp_gt_f32_e32 vcc, s2, v21
	s_nop 0
	v_cndmask_b32_e64 v5, v8, v9, s[6:7]
	v_cndmask_b32_e64 v5, v5, -v21, vcc
	v_mul_f32_e32 v4, v4, v5
	v_mul_f32_e32 v5, 0x3fb8aa3b, v4
	v_add_f32_e32 v4, v4, v4
	v_mul_f32_e32 v8, 0x3fb8aa3b, v4
	v_exp_f32_e32 v117, v5
	v_fmamk_f32 v5, v4, 0x3c088889, v189
	v_exp_f32_e32 v8, v8
	v_fmaak_f32 v5, v4, v5, 0x3e2aaaab
	v_fma_f32 v5, v4, v5, 0.5
	v_fma_f32 v5, v4, v5, 1.0
	v_mul_f32_e64 v5, v5, -v4
	v_sub_f32_e32 v8, 1.0, v8
	v_cmp_lt_f32_e32 vcc, s4, v4
	s_nop 1
	v_cndmask_b32_e32 v4, v8, v5, vcc
	v_add_f32_e32 v5, v10, v18
	v_mul_f32_e32 v5, 0xbfb8aa3b, v5
	v_exp_f32_e32 v5, v5
	v_sqrt_f32_e32 v121, v4
	v_add_f32_e32 v4, v26, v6
	v_mul_f32_e32 v4, 0xbfb8aa3b, v4
	v_add_f32_e32 v5, 1.0, v5
	v_rcp_f32_e32 v114, v5
	v_mul_f32_e32 v5, 0xbfb8aa3b, v22
	v_exp_f32_e32 v5, v5
	v_exp_f32_e32 v4, v4
	v_add_f32_e32 v6, 1.0, v5
	v_cmp_gt_f32_e32 vcc, s28, v6
	v_add_f32_e32 v4, 1.0, v4
	v_rcp_f32_e32 v4, v4
	v_cndmask_b32_e64 v8, 0, 32, vcc
	v_ldexp_f32 v6, v6, v8
	v_log_f32_e32 v6, v6
	v_mul_f32_e32 v4, 0xc1000000, v4
	v_mul_f32_e32 v8, 0x3f317217, v6
	v_fma_f32 v8, v6, s0, -v8
	v_fmac_f32_e32 v8, 0x3377d1cf, v6
	v_fmac_f32_e32 v8, 0x3f317217, v6
	v_cmp_lt_f32_e64 s[6:7], |v6|, s1
	s_nop 1
	v_cndmask_b32_e64 v6, v6, v8, s[6:7]
	v_cndmask_b32_e32 v8, 0, v201, vcc
	v_sub_f32_e32 v6, v6, v8
	v_fmamk_f32 v8, v5, 0xbe800000, v188
	v_fma_f32 v8, -v5, v8, 0.5
	v_fma_f32 v8, -v5, v8, 1.0
	v_mul_f32_e32 v8, v5, v8
	v_cmp_gt_f32_e64 s[6:7], s3, v5
	v_cmp_gt_f32_e32 vcc, s2, v22
	s_nop 0
	v_cndmask_b32_e64 v5, v6, v8, s[6:7]
	v_cndmask_b32_e64 v5, v5, -v22, vcc
	v_mul_f32_e32 v4, v4, v5
	v_mul_f32_e32 v5, 0x3fb8aa3b, v4
	v_add_f32_e32 v4, v4, v4
	v_mul_f32_e32 v6, 0x3fb8aa3b, v4
	v_exp_f32_e32 v118, v5
	v_fmamk_f32 v5, v4, 0x3c088889, v189
	v_exp_f32_e32 v6, v6
	v_fmaak_f32 v5, v4, v5, 0x3e2aaaab
	v_fma_f32 v5, v4, v5, 0.5
	v_fma_f32 v5, v4, v5, 1.0
	v_mul_f32_e64 v5, v5, -v4
	v_sub_f32_e32 v6, 1.0, v6
	v_cmp_lt_f32_e32 vcc, s4, v4
	s_nop 1
	v_cndmask_b32_e32 v4, v6, v5, vcc
	v_add_f32_e32 v5, v11, v19
	v_mul_f32_e32 v5, 0xbfb8aa3b, v5
	v_exp_f32_e32 v5, v5
	v_sqrt_f32_e32 v122, v4
	v_add_f32_e32 v4, v27, v7
	v_mul_f32_e32 v4, 0xbfb8aa3b, v4
	v_add_f32_e32 v5, 1.0, v5
	v_rcp_f32_e32 v115, v5
	v_mul_f32_e32 v5, 0xbfb8aa3b, v23
	v_exp_f32_e32 v5, v5
	v_exp_f32_e32 v4, v4
	v_add_f32_e32 v6, 1.0, v5
	v_cmp_gt_f32_e32 vcc, s28, v6
	v_add_f32_e32 v4, 1.0, v4
	v_rcp_f32_e32 v4, v4
	v_cndmask_b32_e64 v7, 0, 32, vcc
	v_ldexp_f32 v6, v6, v7
	v_log_f32_e32 v6, v6
	v_mul_f32_e32 v4, 0xc1000000, v4
	v_mul_f32_e32 v7, 0x3f317217, v6
	v_fma_f32 v7, v6, s0, -v7
	v_fmac_f32_e32 v7, 0x3377d1cf, v6
	v_fmac_f32_e32 v7, 0x3f317217, v6
	v_cmp_lt_f32_e64 s[6:7], |v6|, s1
	s_nop 1
	v_cndmask_b32_e64 v6, v6, v7, s[6:7]
	v_cndmask_b32_e32 v7, 0, v201, vcc
	v_sub_f32_e32 v6, v6, v7
	v_fmamk_f32 v7, v5, 0xbe800000, v188
	v_fma_f32 v7, -v5, v7, 0.5
	v_fma_f32 v7, -v5, v7, 1.0
	v_mul_f32_e32 v7, v5, v7
	v_cmp_gt_f32_e64 s[6:7], s3, v5
	v_cmp_gt_f32_e32 vcc, s2, v23
	s_nop 0
	v_cndmask_b32_e64 v5, v6, v7, s[6:7]
	v_cndmask_b32_e64 v5, v5, -v23, vcc
	global_load_dwordx4 v[20:23], v168, s[10:11] offset:224
	global_load_dwordx4 v[16:19], v168, s[12:13] offset:224
	global_load_dwordx4 v[8:11], v168, s[8:9] offset:224
	v_mul_f32_e32 v4, v4, v5
	v_mul_f32_e32 v5, 0x3fb8aa3b, v4
	v_add_f32_e32 v4, v4, v4
	v_mul_f32_e32 v6, 0x3fb8aa3b, v4
	v_exp_f32_e32 v119, v5
	v_fmamk_f32 v5, v4, 0x3c088889, v189
	v_exp_f32_e32 v6, v6
	v_fmaak_f32 v5, v4, v5, 0x3e2aaaab
	v_fma_f32 v5, v4, v5, 0.5
	v_fma_f32 v5, v4, v5, 1.0
	v_mul_f32_e64 v5, v5, -v4
	v_sub_f32_e32 v6, 1.0, v6
	v_cmp_lt_f32_e32 vcc, s4, v4
	s_waitcnt vmcnt(2)
	v_add_f32_e32 v20, v28, v20
	v_mul_f32_e32 v20, 0xbfb8aa3b, v20
	v_exp_f32_e32 v20, v20
	s_waitcnt vmcnt(1)
	v_add_f32_e32 v12, v12, v16
	v_mul_f32_e32 v12, 0xbfb8aa3b, v12
	v_exp_f32_e32 v12, v12
	v_add_f32_e32 v20, 1.0, v20
	s_waitcnt vmcnt(0)
	v_mul_f32_e32 v16, 0xbfb8aa3b, v8
	v_rcp_f32_e32 v20, v20
	v_exp_f32_e32 v16, v16
	v_cndmask_b32_e32 v4, v6, v5, vcc
	v_add_f32_e32 v12, 1.0, v12
	v_sqrt_f32_e32 v123, v4
	ds_read_b128 v[4:7], v124 offset:224
	v_rcp_f32_e32 v124, v12
	v_mul_f32_e32 v12, 0xc1000000, v20
	v_add_f32_e32 v20, 1.0, v16
	v_cmp_gt_f32_e32 vcc, s28, v20
	s_nop 1
	v_cndmask_b32_e64 v24, 0, 32, vcc
	v_ldexp_f32 v20, v20, v24
	v_log_f32_e32 v20, v20
	s_nop 0
	v_mul_f32_e32 v24, 0x3f317217, v20
	v_fma_f32 v24, v20, s0, -v24
	v_fmac_f32_e32 v24, 0x3377d1cf, v20
	v_fmac_f32_e32 v24, 0x3f317217, v20
	v_cmp_lt_f32_e64 s[6:7], |v20|, s1
	s_nop 1
	v_cndmask_b32_e64 v20, v20, v24, s[6:7]
	v_cndmask_b32_e32 v24, 0, v201, vcc
	v_sub_f32_e32 v20, v20, v24
	v_fmamk_f32 v24, v16, 0xbe800000, v188
	v_fma_f32 v24, -v16, v24, 0.5
	v_fma_f32 v24, -v16, v24, 1.0
	v_mul_f32_e32 v24, v16, v24
	v_cmp_gt_f32_e64 s[6:7], s3, v16
	v_cmp_gt_f32_e32 vcc, s2, v8
	s_nop 0
	v_cndmask_b32_e64 v16, v20, v24, s[6:7]
	v_cndmask_b32_e64 v8, v16, -v8, vcc
	v_mul_f32_e32 v8, v12, v8
	v_mul_f32_e32 v12, 0x3fb8aa3b, v8
	v_add_f32_e32 v8, v8, v8
	v_mul_f32_e32 v16, 0x3fb8aa3b, v8
	v_exp_f32_e32 v126, v12
	v_fmamk_f32 v12, v8, 0x3c088889, v189
	v_exp_f32_e32 v16, v16
	v_fmaak_f32 v12, v8, v12, 0x3e2aaaab
	v_fma_f32 v12, v8, v12, 0.5
	v_fma_f32 v12, v8, v12, 1.0
	v_mul_f32_e64 v12, v12, -v8
	v_sub_f32_e32 v16, 1.0, v16
	v_cmp_lt_f32_e32 vcc, s4, v8
	s_nop 1
	v_cndmask_b32_e32 v8, v16, v12, vcc
	v_add_f32_e32 v12, v13, v17
	v_mul_f32_e32 v12, 0xbfb8aa3b, v12
	v_exp_f32_e32 v12, v12
	v_sqrt_f32_e32 v128, v8
	v_add_f32_e32 v8, v29, v21
	v_mul_f32_e32 v8, 0xbfb8aa3b, v8
	v_add_f32_e32 v12, 1.0, v12
	v_rcp_f32_e32 v125, v12
	v_mul_f32_e32 v12, 0xbfb8aa3b, v9
	v_exp_f32_e32 v12, v12
	v_exp_f32_e32 v8, v8
	v_add_f32_e32 v13, 1.0, v12
	v_cmp_gt_f32_e32 vcc, s28, v13
	v_add_f32_e32 v8, 1.0, v8
	v_rcp_f32_e32 v8, v8
	v_cndmask_b32_e64 v16, 0, 32, vcc
	v_ldexp_f32 v13, v13, v16
	v_log_f32_e32 v13, v13
	v_mul_f32_e32 v8, 0xc1000000, v8
	v_mul_f32_e32 v16, 0x3f317217, v13
	v_fma_f32 v16, v13, s0, -v16
	v_fmac_f32_e32 v16, 0x3377d1cf, v13
	v_fmac_f32_e32 v16, 0x3f317217, v13
	v_cmp_lt_f32_e64 s[6:7], |v13|, s1
	s_nop 1
	v_cndmask_b32_e64 v13, v13, v16, s[6:7]
	v_cndmask_b32_e32 v16, 0, v201, vcc
	v_sub_f32_e32 v13, v13, v16
	v_fmamk_f32 v16, v12, 0xbe800000, v188
	v_fma_f32 v16, -v12, v16, 0.5
	v_fma_f32 v16, -v12, v16, 1.0
	v_mul_f32_e32 v16, v12, v16
	v_cmp_gt_f32_e64 s[6:7], s3, v12
	v_cmp_gt_f32_e32 vcc, s2, v9
	s_nop 0
	v_cndmask_b32_e64 v12, v13, v16, s[6:7]
	v_cndmask_b32_e64 v9, v12, -v9, vcc
	v_mul_f32_e32 v8, v8, v9
	v_mul_f32_e32 v9, 0x3fb8aa3b, v8
	v_add_f32_e32 v8, v8, v8
	v_mul_f32_e32 v12, 0x3fb8aa3b, v8
	v_exp_f32_e32 v127, v9
	v_fmamk_f32 v9, v8, 0x3c088889, v189
	v_exp_f32_e32 v12, v12
	v_fmaak_f32 v9, v8, v9, 0x3e2aaaab
	v_fma_f32 v9, v8, v9, 0.5
	v_fma_f32 v9, v8, v9, 1.0
	v_mul_f32_e64 v9, v9, -v8
	v_sub_f32_e32 v12, 1.0, v12
	v_cmp_lt_f32_e32 vcc, s4, v8
	s_nop 1
	v_cndmask_b32_e32 v8, v12, v9, vcc
	v_add_f32_e32 v9, v14, v18
	v_mul_f32_e32 v9, 0xbfb8aa3b, v9
	v_exp_f32_e32 v9, v9
	v_sqrt_f32_e32 v129, v8
	v_add_f32_e32 v8, v30, v22
	v_mul_f32_e32 v8, 0xbfb8aa3b, v8
	v_add_f32_e32 v9, 1.0, v9
	v_rcp_f32_e32 v130, v9
	v_mul_f32_e32 v9, 0xbfb8aa3b, v10
	v_exp_f32_e32 v9, v9
	v_exp_f32_e32 v8, v8
	v_add_f32_e32 v12, 1.0, v9
	v_cmp_gt_f32_e32 vcc, s28, v12
	v_add_f32_e32 v8, 1.0, v8
	v_rcp_f32_e32 v8, v8
	v_cndmask_b32_e64 v13, 0, 32, vcc
	v_ldexp_f32 v12, v12, v13
	v_log_f32_e32 v12, v12
	v_mul_f32_e32 v8, 0xc1000000, v8
	v_mul_f32_e32 v13, 0x3f317217, v12
	v_fma_f32 v13, v12, s0, -v13
	v_fmac_f32_e32 v13, 0x3377d1cf, v12
	v_fmac_f32_e32 v13, 0x3f317217, v12
	v_cmp_lt_f32_e64 s[6:7], |v12|, s1
	s_nop 1
	v_cndmask_b32_e64 v12, v12, v13, s[6:7]
	v_cndmask_b32_e32 v13, 0, v201, vcc
	v_sub_f32_e32 v12, v12, v13
	v_fmamk_f32 v13, v9, 0xbe800000, v188
	v_fma_f32 v13, -v9, v13, 0.5
	v_fma_f32 v13, -v9, v13, 1.0
	v_mul_f32_e32 v13, v9, v13
	v_cmp_gt_f32_e64 s[6:7], s3, v9
	v_cmp_gt_f32_e32 vcc, s2, v10
	s_nop 0
	v_cndmask_b32_e64 v9, v12, v13, s[6:7]
	v_cndmask_b32_e64 v9, v9, -v10, vcc
	v_mul_f32_e32 v8, v8, v9
	v_mul_f32_e32 v9, 0x3fb8aa3b, v8
	v_add_f32_e32 v8, v8, v8
	v_mul_f32_e32 v10, 0x3fb8aa3b, v8
	v_exp_f32_e32 v132, v9
	v_fmamk_f32 v9, v8, 0x3c088889, v189
	v_exp_f32_e32 v10, v10
	v_fmaak_f32 v9, v8, v9, 0x3e2aaaab
	v_fma_f32 v9, v8, v9, 0.5
	v_fma_f32 v9, v8, v9, 1.0
	v_mul_f32_e64 v9, v9, -v8
	v_sub_f32_e32 v10, 1.0, v10
	v_cmp_lt_f32_e32 vcc, s4, v8
	s_nop 1
	v_cndmask_b32_e32 v8, v10, v9, vcc
	v_add_f32_e32 v9, v15, v19
	v_mul_f32_e32 v9, 0xbfb8aa3b, v9
	v_exp_f32_e32 v9, v9
	v_sqrt_f32_e32 v134, v8
	v_add_f32_e32 v8, v31, v23
	v_mul_f32_e32 v8, 0xbfb8aa3b, v8
	v_add_f32_e32 v9, 1.0, v9
	v_rcp_f32_e32 v131, v9
	v_mul_f32_e32 v9, 0xbfb8aa3b, v11
	v_exp_f32_e32 v9, v9
	v_exp_f32_e32 v8, v8
	v_add_f32_e32 v10, 1.0, v9
	v_cmp_gt_f32_e32 vcc, s28, v10
	v_add_f32_e32 v8, 1.0, v8
	v_rcp_f32_e32 v8, v8
	v_cndmask_b32_e64 v12, 0, 32, vcc
	v_ldexp_f32 v10, v10, v12
	v_log_f32_e32 v10, v10
	v_mul_f32_e32 v8, 0xc1000000, v8
	v_mul_f32_e32 v12, 0x3f317217, v10
	v_fma_f32 v12, v10, s0, -v12
	v_fmac_f32_e32 v12, 0x3377d1cf, v10
	v_fmac_f32_e32 v12, 0x3f317217, v10
	v_cmp_lt_f32_e64 s[6:7], |v10|, s1
	s_nop 1
	v_cndmask_b32_e64 v10, v10, v12, s[6:7]
	v_cndmask_b32_e32 v12, 0, v201, vcc
	v_sub_f32_e32 v10, v10, v12
	v_fmamk_f32 v12, v9, 0xbe800000, v188
	v_fma_f32 v12, -v9, v12, 0.5
	v_fma_f32 v12, -v9, v12, 1.0
	v_mul_f32_e32 v12, v9, v12
	v_cmp_gt_f32_e64 s[6:7], s3, v9
	v_cmp_gt_f32_e32 vcc, s2, v11
	s_nop 0
	v_cndmask_b32_e64 v9, v10, v12, s[6:7]
	v_cndmask_b32_e64 v9, v9, -v11, vcc
	v_mul_f32_e32 v8, v8, v9
	v_mul_f32_e32 v9, 0x3fb8aa3b, v8
	v_add_f32_e32 v8, v8, v8
	v_mul_f32_e32 v10, 0x3fb8aa3b, v8
	v_exp_f32_e32 v133, v9
	v_fmamk_f32 v9, v8, 0x3c088889, v189
	v_exp_f32_e32 v10, v10
	v_fmaak_f32 v9, v8, v9, 0x3e2aaaab
	v_fma_f32 v9, v8, v9, 0.5
	v_fma_f32 v9, v8, v9, 1.0
	v_mul_f32_e64 v9, v9, -v8
	v_sub_f32_e32 v10, 1.0, v10
	v_cmp_lt_f32_e32 vcc, s4, v8
	s_nop 1
	v_cndmask_b32_e32 v8, v10, v9, vcc
	v_sqrt_f32_e32 v135, v8
	v_and_b32_e32 v8, 0x60, v191
	v_add_u32_e32 v9, -1, v191
	v_cmp_lt_i32_e32 vcc, v9, v8
	s_nop 1
	v_cndmask_b32_e32 v9, v9, v191, vcc
	v_lshlrev_b32_e32 v165, 2, v9
	ds_bpermute_b32 v10, v165, v137
	v_cmp_eq_u32_e32 vcc, 0, v162
	ds_bpermute_b32 v11, v165, v139
	ds_bpermute_b32 v9, v165, v136
	ds_bpermute_b32 v14, v165, v68
	s_waitcnt lgkmcnt(3)
	v_fma_f32 v10, v136, v10, v137
	v_cndmask_b32_e32 v12, v10, v137, vcc
	ds_bpermute_b32 v10, v165, v138
	s_waitcnt lgkmcnt(3)
	v_fma_f32 v11, v138, v11, v139
	v_cndmask_b32_e32 v16, v11, v139, vcc
	ds_bpermute_b32 v11, v165, v141
	ds_bpermute_b32 v15, v165, v69
	s_waitcnt lgkmcnt(2)
	v_mul_f32_e32 v10, v138, v10
	v_cndmask_b32_e32 v13, v10, v138, vcc
	ds_bpermute_b32 v10, v165, v140
	s_waitcnt lgkmcnt(2)
	v_fma_f32 v11, v140, v11, v141
	v_cndmask_b32_e32 v18, v11, v141, vcc
	ds_bpermute_b32 v11, v165, v143
	v_mul_f32_e32 v9, v136, v9
	s_waitcnt lgkmcnt(1)
	v_mul_f32_e32 v10, v140, v10
	v_cndmask_b32_e32 v17, v10, v140, vcc
	ds_bpermute_b32 v10, v165, v142
	s_waitcnt lgkmcnt(1)
	v_fma_f32 v11, v142, v11, v143
	v_cndmask_b32_e32 v20, v11, v143, vcc
	ds_bpermute_b32 v11, v165, v63
	v_cndmask_b32_e32 v9, v9, v136, vcc
	s_waitcnt lgkmcnt(1)
	v_mul_f32_e32 v10, v142, v10
	v_cndmask_b32_e32 v19, v10, v142, vcc
	ds_bpermute_b32 v10, v165, v62
	ds_bpermute_b32 v28, v165, v76
	ds_bpermute_b32 v29, v165, v77
	ds_bpermute_b32 v24, v165, v78
	ds_bpermute_b32 v25, v165, v79
	ds_bpermute_b32 v30, v165, v86
	ds_bpermute_b32 v31, v165, v87
	ds_bpermute_b32 v26, v165, v92
	ds_bpermute_b32 v27, v165, v93
	ds_bpermute_b32 v158, v165, v96
	ds_bpermute_b32 v159, v165, v97
	ds_bpermute_b32 v156, v165, v98
	ds_bpermute_b32 v157, v165, v99
	ds_bpermute_b32 v154, v165, v52
	ds_bpermute_b32 v155, v165, v53
	ds_bpermute_b32 v152, v165, v54
	ds_bpermute_b32 v153, v165, v55
	ds_bpermute_b32 v150, v165, v116
	ds_bpermute_b32 v151, v165, v117
	ds_bpermute_b32 v148, v165, v118
	ds_bpermute_b32 v149, v165, v119
	ds_bpermute_b32 v146, v165, v126
	ds_bpermute_b32 v147, v165, v127
	ds_bpermute_b32 v136, v165, v132
	ds_bpermute_b32 v137, v165, v133
	v_add_u32_e32 v21, -2, v191
	v_cmp_lt_i32_e64 s[6:7], v21, v8
	s_nop 1
	v_cndmask_b32_e64 v21, v21, v191, s[6:7]
	v_lshlrev_b32_e32 v166, 2, v21
	ds_bpermute_b32 v21, v166, v9
	ds_bpermute_b32 v22, v166, v12
	v_cmp_gt_u32_e64 s[6:7], 2, v162
	s_waitcnt lgkmcnt(1)
	v_mul_f32_e32 v21, v9, v21
	s_waitcnt lgkmcnt(0)
	v_fma_f32 v22, v9, v22, v12
	v_cndmask_b32_e64 v9, v21, v9, s[6:7]
	v_cndmask_b32_e64 v12, v22, v12, s[6:7]
	ds_bpermute_b32 v21, v166, v13
	ds_bpermute_b32 v22, v166, v16
	s_waitcnt lgkmcnt(1)
	v_mul_f32_e32 v21, v13, v21
	s_waitcnt lgkmcnt(0)
	v_fma_f32 v22, v13, v22, v16
	v_cndmask_b32_e64 v13, v21, v13, s[6:7]
	v_cndmask_b32_e64 v16, v22, v16, s[6:7]
	ds_bpermute_b32 v21, v166, v17
	ds_bpermute_b32 v22, v166, v18
	s_waitcnt lgkmcnt(1)
	v_mul_f32_e32 v21, v17, v21
	s_waitcnt lgkmcnt(0)
	v_fma_f32 v22, v17, v22, v18
	v_cndmask_b32_e64 v17, v21, v17, s[6:7]
	v_cndmask_b32_e64 v18, v22, v18, s[6:7]
	ds_bpermute_b32 v21, v166, v19
	ds_bpermute_b32 v22, v166, v20
	s_waitcnt lgkmcnt(1)
	v_mul_f32_e32 v21, v19, v21
	s_waitcnt lgkmcnt(0)
	v_fma_f32 v22, v19, v22, v20
	v_cndmask_b32_e64 v19, v21, v19, s[6:7]
	v_cndmask_b32_e64 v20, v22, v20, s[6:7]
	v_add_u32_e32 v21, -4, v191
	v_cmp_lt_i32_e64 s[8:9], v21, v8
	s_nop 1
	v_cndmask_b32_e64 v21, v21, v191, s[8:9]
	v_lshlrev_b32_e32 v167, 2, v21
	ds_bpermute_b32 v21, v167, v9
	ds_bpermute_b32 v22, v167, v12
	v_cmp_gt_u32_e64 s[8:9], 4, v162
	s_waitcnt lgkmcnt(1)
	v_mul_f32_e32 v21, v9, v21
	s_waitcnt lgkmcnt(0)
	v_fma_f32 v22, v9, v22, v12
	v_cndmask_b32_e64 v9, v21, v9, s[8:9]
	v_cndmask_b32_e64 v12, v22, v12, s[8:9]
	ds_bpermute_b32 v21, v167, v13
	ds_bpermute_b32 v22, v167, v16
	s_waitcnt lgkmcnt(1)
	v_mul_f32_e32 v21, v13, v21
	s_waitcnt lgkmcnt(0)
	v_fma_f32 v22, v13, v22, v16
	v_cndmask_b32_e64 v13, v21, v13, s[8:9]
	v_cndmask_b32_e64 v16, v22, v16, s[8:9]
	ds_bpermute_b32 v21, v167, v17
	ds_bpermute_b32 v22, v167, v18
	s_waitcnt lgkmcnt(1)
	v_mul_f32_e32 v21, v17, v21
	s_waitcnt lgkmcnt(0)
	v_fma_f32 v22, v17, v22, v18
	v_cndmask_b32_e64 v17, v21, v17, s[8:9]
	v_cndmask_b32_e64 v18, v22, v18, s[8:9]
	ds_bpermute_b32 v21, v167, v19
	ds_bpermute_b32 v22, v167, v20
	s_waitcnt lgkmcnt(1)
	v_mul_f32_e32 v21, v19, v21
	s_waitcnt lgkmcnt(0)
	v_fma_f32 v22, v19, v22, v20
	v_cndmask_b32_e64 v19, v21, v19, s[8:9]
	v_cndmask_b32_e64 v20, v22, v20, s[8:9]
	v_add_u32_e32 v21, -8, v191
	v_cmp_lt_i32_e64 s[10:11], v21, v8
	s_nop 1
	v_cndmask_b32_e64 v21, v21, v191, s[10:11]
	v_lshlrev_b32_e32 v168, 2, v21
	ds_bpermute_b32 v21, v168, v9
	ds_bpermute_b32 v22, v168, v12
	v_cmp_gt_u32_e64 s[10:11], 8, v162
	s_waitcnt lgkmcnt(1)
	v_mul_f32_e32 v21, v9, v21
	s_waitcnt lgkmcnt(0)
	v_fma_f32 v22, v9, v22, v12
	v_cndmask_b32_e64 v140, v21, v9, s[10:11]
	v_cndmask_b32_e64 v138, v22, v12, s[10:11]
	ds_bpermute_b32 v9, v168, v13
	ds_bpermute_b32 v12, v168, v16
	s_waitcnt lgkmcnt(1)
	v_mul_f32_e32 v9, v13, v9
	s_waitcnt lgkmcnt(0)
	v_fma_f32 v12, v13, v12, v16
	v_cndmask_b32_e64 v141, v9, v13, s[10:11]
	v_cndmask_b32_e64 v139, v12, v16, s[10:11]
	ds_bpermute_b32 v9, v168, v17
	ds_bpermute_b32 v12, v168, v18
	s_waitcnt lgkmcnt(1)
	v_mul_f32_e32 v9, v17, v9
	s_waitcnt lgkmcnt(0)
	v_fma_f32 v12, v17, v12, v18
	v_cndmask_b32_e64 v144, v9, v17, s[10:11]
	v_cndmask_b32_e64 v142, v12, v18, s[10:11]
	ds_bpermute_b32 v9, v168, v19
	ds_bpermute_b32 v12, v168, v20
	s_waitcnt lgkmcnt(1)
	v_mul_f32_e32 v9, v19, v9
	s_waitcnt lgkmcnt(0)
	v_fma_f32 v12, v19, v12, v20
	v_cndmask_b32_e64 v145, v9, v19, s[10:11]
	v_cndmask_b32_e64 v143, v12, v20, s[10:11]
	v_pk_mul_f32 v[12:13], v[32:33], v[60:61]
	v_add_u32_e32 v9, -16, v191
	v_pk_mul_f32 v[12:13], v[12:13], v[64:65]
	ds_bpermute_b32 v16, v165, v12
	ds_bpermute_b32 v17, v165, v13
	v_pk_mul_f32 v[10:11], v[62:63], v[10:11]
	v_cmp_lt_i32_e64 s[12:13], v9, v8
	v_cndmask_b32_e32 v11, v11, v63, vcc
	v_cndmask_b32_e32 v10, v10, v62, vcc
	s_waitcnt lgkmcnt(0)
	v_pk_fma_f32 v[16:17], v[62:63], v[16:17], v[12:13]
	v_cndmask_b32_e64 v8, v9, v191, s[12:13]
	v_cndmask_b32_e32 v17, v17, v13, vcc
	v_cndmask_b32_e32 v16, v16, v12, vcc
	ds_bpermute_b32 v20, v166, v10
	ds_bpermute_b32 v22, v166, v16
	ds_bpermute_b32 v21, v166, v11
	ds_bpermute_b32 v23, v166, v17
	v_lshlrev_b32_e32 v170, 2, v8
	ds_bpermute_b32 v18, v170, v138
	ds_bpermute_b32 v19, v170, v139
	s_waitcnt lgkmcnt(3)
	v_pk_mul_f32 v[20:21], v[10:11], v[20:21]
	s_waitcnt lgkmcnt(2)
	v_pk_fma_f32 v[22:23], v[10:11], v[22:23], v[16:17]
	v_cndmask_b32_e64 v21, v21, v11, s[6:7]
	v_cndmask_b32_e64 v20, v20, v10, s[6:7]
	v_cndmask_b32_e64 v17, v23, v17, s[6:7]
	v_cndmask_b32_e64 v16, v22, v16, s[6:7]
	s_waitcnt lgkmcnt(0)
	v_pk_fma_f32 v[12:13], v[140:141], v[18:19], v[138:139]
	ds_bpermute_b32 v18, v170, v144
	ds_bpermute_b32 v19, v170, v145
	ds_bpermute_b32 v22, v167, v20
	ds_bpermute_b32 v32, v167, v16
	ds_bpermute_b32 v23, v167, v21
	ds_bpermute_b32 v33, v167, v17
	s_waitcnt lgkmcnt(4)
	v_pk_mul_f32 v[10:11], v[144:145], v[18:19]
	v_pk_mul_f32 v[14:15], v[68:69], v[14:15]
	ds_bpermute_b32 v8, v170, v140
	s_waitcnt lgkmcnt(2)
	v_pk_mul_f32 v[18:19], v[20:21], v[22:23]
	s_waitcnt lgkmcnt(1)
	v_pk_fma_f32 v[22:23], v[20:21], v[32:33], v[16:17]
	v_cndmask_b32_e64 v19, v19, v21, s[8:9]
	v_cndmask_b32_e64 v17, v23, v17, s[8:9]
	v_cndmask_b32_e64 v16, v22, v16, s[8:9]
	v_pk_mul_f32 v[22:23], v[34:35], v[66:67]
	v_cndmask_b32_e64 v18, v18, v20, s[8:9]
	v_pk_mul_f32 v[22:23], v[22:23], v[70:71]
	ds_bpermute_b32 v32, v165, v22
	ds_bpermute_b32 v33, v165, v23
	ds_bpermute_b32 v20, v168, v18
	ds_bpermute_b32 v21, v168, v19
	v_cndmask_b32_e32 v15, v15, v69, vcc
	v_cndmask_b32_e32 v14, v14, v68, vcc
	s_waitcnt lgkmcnt(2)
	v_pk_fma_f32 v[32:33], v[68:69], v[32:33], v[22:23]
	ds_bpermute_b32 v34, v168, v16
	v_cndmask_b32_e32 v23, v33, v23, vcc
	v_cndmask_b32_e32 v22, v32, v22, vcc
	ds_bpermute_b32 v35, v168, v17
	ds_bpermute_b32 v32, v166, v14
	ds_bpermute_b32 v62, v166, v22
	ds_bpermute_b32 v33, v166, v15
	ds_bpermute_b32 v63, v166, v23
	s_waitcnt lgkmcnt(6)
	v_pk_mul_f32 v[20:21], v[18:19], v[20:21]
	s_waitcnt lgkmcnt(4)
	v_pk_fma_f32 v[34:35], v[18:19], v[34:35], v[16:17]
	v_cndmask_b32_e64 v65, v21, v19, s[10:11]
	v_cndmask_b32_e64 v64, v20, v18, s[10:11]
	s_waitcnt lgkmcnt(1)
	v_pk_mul_f32 v[18:19], v[14:15], v[32:33]
	s_waitcnt lgkmcnt(0)
	v_pk_fma_f32 v[20:21], v[14:15], v[62:63], v[22:23]
	v_cndmask_b32_e64 v15, v19, v15, s[6:7]
	v_cndmask_b32_e64 v14, v18, v14, s[6:7]
	v_cndmask_b32_e64 v19, v21, v23, s[6:7]
	v_cndmask_b32_e64 v18, v20, v22, s[6:7]
	ds_bpermute_b32 v20, v167, v14
	ds_bpermute_b32 v22, v167, v18
	ds_bpermute_b32 v21, v167, v15
	ds_bpermute_b32 v23, v167, v19
	v_cndmask_b32_e64 v67, v35, v17, s[10:11]
	v_cndmask_b32_e64 v66, v34, v16, s[10:11]
	ds_bpermute_b32 v9, v170, v141
	s_waitcnt lgkmcnt(2)
	v_pk_mul_f32 v[20:21], v[14:15], v[20:21]
	s_waitcnt lgkmcnt(1)
	v_pk_fma_f32 v[22:23], v[14:15], v[22:23], v[18:19]
	v_cndmask_b32_e64 v15, v21, v15, s[8:9]
	v_cndmask_b32_e64 v14, v20, v14, s[8:9]
	v_cndmask_b32_e64 v19, v23, v19, s[8:9]
	v_cndmask_b32_e64 v18, v22, v18, s[8:9]
	ds_bpermute_b32 v20, v168, v14
	ds_bpermute_b32 v22, v168, v18
	ds_bpermute_b32 v21, v168, v15
	ds_bpermute_b32 v23, v168, v19
	ds_bpermute_b32 v60, v170, v142
	ds_bpermute_b32 v61, v170, v143
	ds_bpermute_b32 v16, v170, v64
	s_waitcnt lgkmcnt(4)
	v_pk_mul_f32 v[20:21], v[14:15], v[20:21]
	s_waitcnt lgkmcnt(3)
	v_pk_fma_f32 v[22:23], v[14:15], v[22:23], v[18:19]
	v_cndmask_b32_e64 v69, v21, v15, s[10:11]
	v_cndmask_b32_e64 v68, v20, v14, s[10:11]
	v_cndmask_b32_e64 v71, v23, v19, s[10:11]
	v_cndmask_b32_e64 v70, v22, v18, s[10:11]
	ds_bpermute_b32 v32, v170, v66
	ds_bpermute_b32 v17, v170, v65
	ds_bpermute_b32 v33, v170, v67
	ds_bpermute_b32 v18, v170, v68
	ds_bpermute_b32 v34, v170, v70
	ds_bpermute_b32 v19, v170, v69
	ds_bpermute_b32 v35, v170, v71
	v_pk_mul_f32 v[8:9], v[140:141], v[8:9]
	s_waitcnt lgkmcnt(8)
	v_pk_fma_f32 v[14:15], v[144:145], v[60:61], v[142:143]
	s_waitcnt lgkmcnt(5)
	v_pk_mul_f32 v[20:21], v[64:65], v[16:17]
	s_waitcnt lgkmcnt(4)
	v_pk_fma_f32 v[16:17], v[64:65], v[32:33], v[66:67]
	s_waitcnt lgkmcnt(1)
	v_pk_mul_f32 v[22:23], v[68:69], v[18:19]
	s_waitcnt lgkmcnt(0)
	v_pk_fma_f32 v[18:19], v[68:69], v[34:35], v[70:71]
	v_pk_mul_f32 v[32:33], v[36:37], v[72:73]
	v_pk_mul_f32 v[28:29], v[76:77], v[28:29]
	v_pk_mul_f32 v[32:33], v[32:33], v[80:81]
	ds_bpermute_b32 v34, v165, v32
	ds_bpermute_b32 v35, v165, v33
	v_cndmask_b32_e32 v29, v29, v77, vcc
	v_cndmask_b32_e32 v28, v28, v76, vcc
	v_pk_mul_f32 v[38:39], v[38:39], v[74:75]
	v_pk_mul_f32 v[24:25], v[78:79], v[24:25]
	s_waitcnt lgkmcnt(0)
	v_pk_fma_f32 v[34:35], v[76:77], v[34:35], v[32:33]
	v_pk_mul_f32 v[38:39], v[38:39], v[82:83]
	v_cndmask_b32_e32 v33, v35, v33, vcc
	v_cndmask_b32_e32 v32, v34, v32, vcc
	ds_bpermute_b32 v34, v166, v28
	ds_bpermute_b32 v35, v166, v29
	ds_bpermute_b32 v36, v166, v32
	ds_bpermute_b32 v37, v166, v33
	ds_bpermute_b32 v60, v165, v38
	ds_bpermute_b32 v61, v165, v39
	s_waitcnt lgkmcnt(4)
	v_pk_mul_f32 v[34:35], v[28:29], v[34:35]
	v_cndmask_b32_e32 v25, v25, v79, vcc
	s_waitcnt lgkmcnt(2)
	v_pk_fma_f32 v[36:37], v[28:29], v[36:37], v[32:33]
	v_cndmask_b32_e64 v29, v35, v29, s[6:7]
	v_cndmask_b32_e64 v28, v34, v28, s[6:7]
	v_cndmask_b32_e64 v33, v37, v33, s[6:7]
	v_cndmask_b32_e64 v32, v36, v32, s[6:7]
	ds_bpermute_b32 v34, v167, v28
	ds_bpermute_b32 v35, v167, v29
	ds_bpermute_b32 v36, v167, v32
	ds_bpermute_b32 v37, v167, v33
	v_cndmask_b32_e32 v24, v24, v78, vcc
	v_pk_mul_f32 v[40:41], v[40:41], v[84:85]
	s_waitcnt lgkmcnt(2)
	v_pk_mul_f32 v[34:35], v[28:29], v[34:35]
	v_pk_mul_f32 v[40:41], v[40:41], v[88:89]
	s_waitcnt lgkmcnt(0)
	v_pk_fma_f32 v[36:37], v[28:29], v[36:37], v[32:33]
	v_cndmask_b32_e64 v29, v35, v29, s[8:9]
	v_cndmask_b32_e64 v28, v34, v28, s[8:9]
	ds_bpermute_b32 v34, v168, v28
	ds_bpermute_b32 v35, v168, v29
	v_cndmask_b32_e64 v33, v37, v33, s[8:9]
	v_cndmask_b32_e64 v32, v36, v32, s[8:9]
	ds_bpermute_b32 v36, v168, v32
	ds_bpermute_b32 v37, v168, v33
	s_waitcnt lgkmcnt(2)
	v_pk_mul_f32 v[34:35], v[28:29], v[34:35]
	v_pk_mul_f32 v[30:31], v[86:87], v[30:31]
	v_cndmask_b32_e64 v73, v35, v29, s[10:11]
	v_cndmask_b32_e64 v72, v34, v28, s[10:11]
	s_waitcnt lgkmcnt(0)
	v_pk_fma_f32 v[36:37], v[28:29], v[36:37], v[32:33]
	v_pk_fma_f32 v[28:29], v[78:79], v[60:61], v[38:39]
	ds_bpermute_b32 v34, v166, v24
	v_cndmask_b32_e32 v29, v29, v39, vcc
	v_cndmask_b32_e32 v28, v28, v38, vcc
	ds_bpermute_b32 v35, v166, v25
	ds_bpermute_b32 v38, v166, v28
	ds_bpermute_b32 v39, v166, v29
	v_cndmask_b32_e64 v75, v37, v33, s[10:11]
	v_cndmask_b32_e64 v74, v36, v32, s[10:11]
	s_waitcnt lgkmcnt(2)
	v_pk_mul_f32 v[34:35], v[24:25], v[34:35]
	ds_bpermute_b32 v32, v170, v72
	s_waitcnt lgkmcnt(1)
	v_pk_fma_f32 v[36:37], v[24:25], v[38:39], v[28:29]
	v_cndmask_b32_e64 v25, v35, v25, s[6:7]
	v_cndmask_b32_e64 v24, v34, v24, s[6:7]
	ds_bpermute_b32 v34, v167, v24
	ds_bpermute_b32 v35, v167, v25
	v_cndmask_b32_e64 v29, v37, v29, s[6:7]
	v_cndmask_b32_e64 v28, v36, v28, s[6:7]
	ds_bpermute_b32 v36, v167, v28
	ds_bpermute_b32 v37, v167, v29
	s_waitcnt lgkmcnt(2)
	v_pk_mul_f32 v[34:35], v[24:25], v[34:35]
	ds_bpermute_b32 v33, v170, v73
	v_cndmask_b32_e64 v35, v35, v25, s[8:9]
	v_cndmask_b32_e64 v34, v34, v24, s[8:9]
	ds_bpermute_b32 v60, v168, v34
	ds_bpermute_b32 v61, v168, v35
	s_waitcnt lgkmcnt(3)
	v_pk_fma_f32 v[36:37], v[24:25], v[36:37], v[28:29]
	ds_bpermute_b32 v38, v170, v74
	v_cndmask_b32_e64 v37, v37, v29, s[8:9]
	v_cndmask_b32_e64 v36, v36, v28, s[8:9]
	s_waitcnt lgkmcnt(3)
	v_pk_mul_f32 v[28:29], v[72:73], v[32:33]
	s_waitcnt lgkmcnt(1)
	v_pk_mul_f32 v[32:33], v[34:35], v[60:61]
	ds_bpermute_b32 v60, v165, v40
	ds_bpermute_b32 v61, v165, v41
	ds_bpermute_b32 v39, v170, v75
	ds_bpermute_b32 v62, v168, v36
	ds_bpermute_b32 v63, v168, v37
	v_cndmask_b32_e64 v79, v33, v35, s[10:11]
	v_cndmask_b32_e64 v78, v32, v34, s[10:11]
	s_waitcnt lgkmcnt(3)
	v_pk_fma_f32 v[32:33], v[86:87], v[60:61], v[40:41]
	v_cndmask_b32_e32 v31, v31, v87, vcc
	v_cndmask_b32_e32 v30, v30, v86, vcc
	v_cndmask_b32_e32 v33, v33, v41, vcc
	v_cndmask_b32_e32 v32, v32, v40, vcc
	s_waitcnt lgkmcnt(2)
	v_pk_fma_f32 v[24:25], v[72:73], v[38:39], v[74:75]
	s_waitcnt lgkmcnt(0)
	v_pk_fma_f32 v[38:39], v[34:35], v[62:63], v[36:37]
	ds_bpermute_b32 v34, v166, v30
	ds_bpermute_b32 v40, v166, v32
	ds_bpermute_b32 v35, v166, v31
	ds_bpermute_b32 v41, v166, v33
	v_cndmask_b32_e64 v77, v39, v37, s[10:11]
	v_cndmask_b32_e64 v76, v38, v36, s[10:11]
	ds_bpermute_b32 v36, v170, v78
	s_waitcnt lgkmcnt(2)
	v_pk_mul_f32 v[34:35], v[30:31], v[34:35]
	s_waitcnt lgkmcnt(1)
	v_pk_fma_f32 v[38:39], v[30:31], v[40:41], v[32:33]
	v_cndmask_b32_e64 v35, v35, v31, s[6:7]
	v_cndmask_b32_e64 v34, v34, v30, s[6:7]
	v_cndmask_b32_e64 v33, v39, v33, s[6:7]
	v_cndmask_b32_e64 v32, v38, v32, s[6:7]
	ds_bpermute_b32 v37, v170, v79
	ds_bpermute_b32 v38, v167, v34
	ds_bpermute_b32 v40, v167, v32
	ds_bpermute_b32 v39, v167, v35
	ds_bpermute_b32 v41, v167, v33
	s_waitcnt lgkmcnt(4)
	v_pk_mul_f32 v[30:31], v[78:79], v[36:37]
	v_pk_mul_f32 v[26:27], v[92:93], v[26:27]
	ds_bpermute_b32 v60, v170, v76
	s_waitcnt lgkmcnt(2)
	v_pk_mul_f32 v[36:37], v[34:35], v[38:39]
	s_waitcnt lgkmcnt(1)
	v_pk_fma_f32 v[38:39], v[34:35], v[40:41], v[32:33]
	v_cndmask_b32_e64 v35, v37, v35, s[8:9]
	v_cndmask_b32_e64 v33, v39, v33, s[8:9]
	v_cndmask_b32_e64 v32, v38, v32, s[8:9]
	v_pk_mul_f32 v[38:39], v[42:43], v[90:91]
	v_cndmask_b32_e64 v34, v36, v34, s[8:9]
	v_pk_mul_f32 v[38:39], v[38:39], v[94:95]
	ds_bpermute_b32 v40, v165, v38
	ds_bpermute_b32 v41, v165, v39
	ds_bpermute_b32 v36, v168, v34
	ds_bpermute_b32 v37, v168, v35
	v_cndmask_b32_e32 v27, v27, v93, vcc
	v_cndmask_b32_e32 v26, v26, v92, vcc
	s_waitcnt lgkmcnt(2)
	v_pk_fma_f32 v[40:41], v[92:93], v[40:41], v[38:39]
	ds_bpermute_b32 v42, v168, v32
	v_cndmask_b32_e32 v39, v41, v39, vcc
	v_cndmask_b32_e32 v38, v40, v38, vcc
	ds_bpermute_b32 v43, v168, v33
	ds_bpermute_b32 v40, v166, v26
	ds_bpermute_b32 v62, v166, v38
	ds_bpermute_b32 v41, v166, v27
	ds_bpermute_b32 v63, v166, v39
	s_waitcnt lgkmcnt(6)
	v_pk_mul_f32 v[36:37], v[34:35], v[36:37]
	s_waitcnt lgkmcnt(4)
	v_pk_fma_f32 v[42:43], v[34:35], v[42:43], v[32:33]
	v_cndmask_b32_e64 v81, v37, v35, s[10:11]
	v_cndmask_b32_e64 v80, v36, v34, s[10:11]
	s_waitcnt lgkmcnt(1)
	v_pk_mul_f32 v[34:35], v[26:27], v[40:41]
	s_waitcnt lgkmcnt(0)
	v_pk_fma_f32 v[36:37], v[26:27], v[62:63], v[38:39]
	v_cndmask_b32_e64 v27, v35, v27, s[6:7]
	v_cndmask_b32_e64 v26, v34, v26, s[6:7]
	v_cndmask_b32_e64 v35, v37, v39, s[6:7]
	v_cndmask_b32_e64 v34, v36, v38, s[6:7]
	ds_bpermute_b32 v36, v167, v26
	ds_bpermute_b32 v38, v167, v34
	ds_bpermute_b32 v37, v167, v27
	ds_bpermute_b32 v39, v167, v35
	v_cndmask_b32_e64 v83, v43, v33, s[10:11]
	v_cndmask_b32_e64 v82, v42, v32, s[10:11]
	ds_bpermute_b32 v61, v170, v77
	s_waitcnt lgkmcnt(2)
	v_pk_mul_f32 v[36:37], v[26:27], v[36:37]
	s_waitcnt lgkmcnt(1)
	v_pk_fma_f32 v[38:39], v[26:27], v[38:39], v[34:35]
	v_cndmask_b32_e64 v27, v37, v27, s[8:9]
	v_cndmask_b32_e64 v26, v36, v26, s[8:9]
	v_cndmask_b32_e64 v35, v39, v35, s[8:9]
	v_cndmask_b32_e64 v34, v38, v34, s[8:9]
	ds_bpermute_b32 v36, v168, v26
	ds_bpermute_b32 v38, v168, v34
	ds_bpermute_b32 v37, v168, v27
	ds_bpermute_b32 v39, v168, v35
	ds_bpermute_b32 v32, v170, v80
	ds_bpermute_b32 v40, v170, v82
	ds_bpermute_b32 v33, v170, v81
	s_waitcnt lgkmcnt(4)
	v_pk_mul_f32 v[36:37], v[26:27], v[36:37]
	s_waitcnt lgkmcnt(3)
	v_pk_fma_f32 v[38:39], v[26:27], v[38:39], v[34:35]
	v_cndmask_b32_e64 v85, v37, v27, s[10:11]
	v_cndmask_b32_e64 v84, v36, v26, s[10:11]
	v_cndmask_b32_e64 v87, v39, v35, s[10:11]
	v_cndmask_b32_e64 v86, v38, v34, s[10:11]
	ds_bpermute_b32 v41, v170, v83
	ds_bpermute_b32 v34, v170, v84
	ds_bpermute_b32 v42, v170, v86
	ds_bpermute_b32 v35, v170, v85
	ds_bpermute_b32 v43, v170, v87
	v_pk_fma_f32 v[26:27], v[78:79], v[60:61], v[76:77]
	s_waitcnt lgkmcnt(5)
	v_pk_mul_f32 v[36:37], v[80:81], v[32:33]
	s_waitcnt lgkmcnt(4)
	v_pk_fma_f32 v[32:33], v[80:81], v[40:41], v[82:83]
	s_waitcnt lgkmcnt(1)
	v_pk_mul_f32 v[38:39], v[84:85], v[34:35]
	s_waitcnt lgkmcnt(0)
	v_pk_fma_f32 v[34:35], v[84:85], v[42:43], v[86:87]
	v_pk_mul_f32 v[40:41], v[48:49], v[56:57]
	v_pk_mul_f32 v[48:49], v[96:97], v[158:159]
	v_pk_mul_f32 v[40:41], v[40:41], v[100:101]
	ds_bpermute_b32 v42, v165, v40
	ds_bpermute_b32 v43, v165, v41
	v_cndmask_b32_e32 v49, v49, v97, vcc
	v_cndmask_b32_e32 v48, v48, v96, vcc
	v_pk_mul_f32 v[50:51], v[50:51], v[58:59]
	v_pk_mul_f32 v[44:45], v[44:45], v[104:105]
	s_waitcnt lgkmcnt(0)
	v_pk_fma_f32 v[42:43], v[96:97], v[42:43], v[40:41]
	v_pk_mul_f32 v[50:51], v[50:51], v[102:103]
	v_cndmask_b32_e32 v41, v43, v41, vcc
	v_cndmask_b32_e32 v40, v42, v40, vcc
	ds_bpermute_b32 v42, v166, v48
	ds_bpermute_b32 v43, v166, v49
	ds_bpermute_b32 v56, v166, v40
	ds_bpermute_b32 v57, v166, v41
	ds_bpermute_b32 v58, v165, v50
	ds_bpermute_b32 v59, v165, v51
	s_waitcnt lgkmcnt(4)
	v_pk_mul_f32 v[42:43], v[48:49], v[42:43]
	v_pk_mul_f32 v[44:45], v[44:45], v[106:107]
	s_waitcnt lgkmcnt(2)
	v_pk_fma_f32 v[56:57], v[48:49], v[56:57], v[40:41]
	v_cndmask_b32_e64 v43, v43, v49, s[6:7]
	v_cndmask_b32_e64 v42, v42, v48, s[6:7]
	v_cndmask_b32_e64 v41, v57, v41, s[6:7]
	v_cndmask_b32_e64 v40, v56, v40, s[6:7]
	ds_bpermute_b32 v48, v167, v42
	ds_bpermute_b32 v49, v167, v43
	ds_bpermute_b32 v56, v167, v40
	ds_bpermute_b32 v57, v167, v41
	v_pk_mul_f32 v[46:47], v[46:47], v[108:109]
	v_pk_mul_f32 v[62:63], v[54:55], v[152:153]
	s_waitcnt lgkmcnt(2)
	v_pk_mul_f32 v[48:49], v[42:43], v[48:49]
	v_pk_mul_f32 v[46:47], v[46:47], v[110:111]
	s_waitcnt lgkmcnt(0)
	v_pk_fma_f32 v[56:57], v[42:43], v[56:57], v[40:41]
	v_cndmask_b32_e64 v43, v49, v43, s[8:9]
	v_cndmask_b32_e64 v42, v48, v42, s[8:9]
	ds_bpermute_b32 v48, v168, v42
	ds_bpermute_b32 v49, v168, v43
	v_cndmask_b32_e64 v41, v57, v41, s[8:9]
	v_cndmask_b32_e64 v40, v56, v40, s[8:9]
	ds_bpermute_b32 v56, v168, v40
	ds_bpermute_b32 v57, v168, v41
	s_waitcnt lgkmcnt(2)
	v_pk_mul_f32 v[48:49], v[42:43], v[48:49]
	s_waitcnt lgkmcnt(0)
	v_pk_fma_f32 v[56:57], v[42:43], v[56:57], v[40:41]
	v_cndmask_b32_e64 v89, v49, v43, s[10:11]
	v_cndmask_b32_e64 v88, v48, v42, s[10:11]
	v_pk_mul_f32 v[42:43], v[98:99], v[156:157]
	v_pk_fma_f32 v[48:49], v[98:99], v[58:59], v[50:51]
	v_cndmask_b32_e32 v43, v43, v99, vcc
	v_cndmask_b32_e32 v42, v42, v98, vcc
	v_cndmask_b32_e32 v49, v49, v51, vcc
	v_cndmask_b32_e32 v48, v48, v50, vcc
	ds_bpermute_b32 v50, v166, v42
	ds_bpermute_b32 v58, v166, v48
	ds_bpermute_b32 v51, v166, v43
	ds_bpermute_b32 v59, v166, v49
	v_cndmask_b32_e64 v91, v57, v41, s[10:11]
	v_cndmask_b32_e64 v90, v56, v40, s[10:11]
	ds_bpermute_b32 v40, v170, v88
	s_waitcnt lgkmcnt(2)
	v_pk_mul_f32 v[50:51], v[42:43], v[50:51]
	s_waitcnt lgkmcnt(1)
	v_pk_fma_f32 v[56:57], v[42:43], v[58:59], v[48:49]
	v_cndmask_b32_e64 v43, v51, v43, s[6:7]
	v_cndmask_b32_e64 v42, v50, v42, s[6:7]
	v_cndmask_b32_e64 v49, v57, v49, s[6:7]
	v_cndmask_b32_e64 v48, v56, v48, s[6:7]
	ds_bpermute_b32 v50, v167, v42
	ds_bpermute_b32 v56, v167, v48
	ds_bpermute_b32 v51, v167, v43
	ds_bpermute_b32 v57, v167, v49
	ds_bpermute_b32 v58, v170, v90
	ds_bpermute_b32 v41, v170, v89
	ds_bpermute_b32 v59, v170, v91
	s_waitcnt lgkmcnt(4)
	v_pk_mul_f32 v[50:51], v[42:43], v[50:51]
	s_waitcnt lgkmcnt(3)
	v_pk_fma_f32 v[56:57], v[42:43], v[56:57], v[48:49]
	v_cndmask_b32_e64 v43, v51, v43, s[8:9]
	v_cndmask_b32_e64 v42, v50, v42, s[8:9]
	v_cndmask_b32_e64 v51, v57, v49, s[8:9]
	v_cndmask_b32_e64 v50, v56, v48, s[8:9]
	ds_bpermute_b32 v60, v168, v50
	ds_bpermute_b32 v61, v168, v51
	ds_bpermute_b32 v56, v168, v42
	ds_bpermute_b32 v57, v168, v43
	s_waitcnt lgkmcnt(5)
	v_pk_mul_f32 v[48:49], v[88:89], v[40:41]
	s_waitcnt lgkmcnt(4)
	v_pk_fma_f32 v[40:41], v[88:89], v[58:59], v[90:91]
	s_waitcnt lgkmcnt(2)
	v_pk_fma_f32 v[58:59], v[42:43], v[60:61], v[50:51]
	ds_bpermute_b32 v60, v165, v44
	ds_bpermute_b32 v61, v165, v45
	s_waitcnt lgkmcnt(2)
	v_pk_mul_f32 v[56:57], v[42:43], v[56:57]
	v_cndmask_b32_e64 v93, v59, v51, s[10:11]
	v_cndmask_b32_e64 v95, v57, v43, s[10:11]
	v_cndmask_b32_e64 v94, v56, v42, s[10:11]
	s_waitcnt lgkmcnt(0)
	v_pk_fma_f32 v[56:57], v[52:53], v[60:61], v[44:45]
	v_pk_mul_f32 v[42:43], v[52:53], v[154:155]
	v_cndmask_b32_e32 v45, v57, v45, vcc
	v_cndmask_b32_e32 v44, v56, v44, vcc
	ds_bpermute_b32 v56, v166, v44
	ds_bpermute_b32 v57, v166, v45
	v_cndmask_b32_e32 v43, v43, v53, vcc
	v_cndmask_b32_e32 v42, v42, v52, vcc
	ds_bpermute_b32 v52, v166, v42
	ds_bpermute_b32 v53, v166, v43
	s_waitcnt lgkmcnt(2)
	v_pk_fma_f32 v[56:57], v[42:43], v[56:57], v[44:45]
	v_cndmask_b32_e64 v92, v58, v50, s[10:11]
	v_cndmask_b32_e64 v45, v57, v45, s[6:7]
	v_cndmask_b32_e64 v44, v56, v44, s[6:7]
	ds_bpermute_b32 v56, v167, v44
	ds_bpermute_b32 v57, v167, v45
	s_waitcnt lgkmcnt(2)
	v_pk_mul_f32 v[52:53], v[42:43], v[52:53]
	ds_bpermute_b32 v50, v170, v94
	v_cndmask_b32_e64 v43, v53, v43, s[6:7]
	v_cndmask_b32_e64 v42, v52, v42, s[6:7]
	ds_bpermute_b32 v52, v167, v42
	ds_bpermute_b32 v53, v167, v43
	s_waitcnt lgkmcnt(3)
	v_pk_fma_f32 v[56:57], v[42:43], v[56:57], v[44:45]
	ds_bpermute_b32 v51, v170, v95
	v_cndmask_b32_e64 v45, v57, v45, s[8:9]
	v_cndmask_b32_e64 v44, v56, v44, s[8:9]
	ds_bpermute_b32 v56, v165, v46
	ds_bpermute_b32 v57, v165, v47
	s_waitcnt lgkmcnt(3)
	v_pk_mul_f32 v[52:53], v[42:43], v[52:53]
	ds_bpermute_b32 v60, v168, v44
	v_cndmask_b32_e64 v43, v53, v43, s[8:9]
	v_cndmask_b32_e64 v42, v52, v42, s[8:9]
	s_waitcnt lgkmcnt(1)
	v_pk_fma_f32 v[56:57], v[54:55], v[56:57], v[46:47]
	ds_bpermute_b32 v52, v168, v42
	ds_bpermute_b32 v53, v168, v43
	v_cndmask_b32_e32 v55, v63, v55, vcc
	v_cndmask_b32_e32 v54, v62, v54, vcc
	v_cndmask_b32_e32 v47, v57, v47, vcc
	v_cndmask_b32_e32 v46, v56, v46, vcc
	ds_bpermute_b32 v61, v168, v45
	ds_bpermute_b32 v56, v166, v54
	ds_bpermute_b32 v62, v166, v46
	ds_bpermute_b32 v57, v166, v55
	ds_bpermute_b32 v63, v166, v47
	s_waitcnt lgkmcnt(5)
	v_pk_mul_f32 v[52:53], v[42:43], v[52:53]
	s_waitcnt lgkmcnt(4)
	v_pk_fma_f32 v[60:61], v[42:43], v[60:61], v[44:45]
	v_cndmask_b32_e64 v97, v53, v43, s[10:11]
	v_cndmask_b32_e64 v96, v52, v42, s[10:11]
	s_waitcnt lgkmcnt(1)
	v_pk_mul_f32 v[42:43], v[54:55], v[56:57]
	s_waitcnt lgkmcnt(0)
	v_pk_fma_f32 v[52:53], v[54:55], v[62:63], v[46:47]
	v_cndmask_b32_e64 v43, v43, v55, s[6:7]
	v_cndmask_b32_e64 v42, v42, v54, s[6:7]
	v_cndmask_b32_e64 v47, v53, v47, s[6:7]
	v_cndmask_b32_e64 v46, v52, v46, s[6:7]
	ds_bpermute_b32 v52, v167, v42
	ds_bpermute_b32 v54, v167, v46
	ds_bpermute_b32 v53, v167, v43
	ds_bpermute_b32 v55, v167, v47
	v_cndmask_b32_e64 v99, v61, v45, s[10:11]
	v_cndmask_b32_e64 v98, v60, v44, s[10:11]
	ds_bpermute_b32 v58, v170, v92
	s_waitcnt lgkmcnt(2)
	v_pk_mul_f32 v[52:53], v[42:43], v[52:53]
	s_waitcnt lgkmcnt(1)
	v_pk_fma_f32 v[54:55], v[42:43], v[54:55], v[46:47]
	v_cndmask_b32_e64 v43, v53, v43, s[8:9]
	v_cndmask_b32_e64 v42, v52, v42, s[8:9]
	v_cndmask_b32_e64 v47, v55, v47, s[8:9]
	v_cndmask_b32_e64 v46, v54, v46, s[8:9]
	ds_bpermute_b32 v52, v168, v42
	ds_bpermute_b32 v54, v168, v46
	ds_bpermute_b32 v53, v168, v43
	ds_bpermute_b32 v55, v168, v47
	ds_bpermute_b32 v59, v170, v93
	ds_bpermute_b32 v44, v170, v96
	ds_bpermute_b32 v56, v170, v98
	s_waitcnt lgkmcnt(4)
	v_pk_mul_f32 v[52:53], v[42:43], v[52:53]
	s_waitcnt lgkmcnt(3)
	v_pk_fma_f32 v[54:55], v[42:43], v[54:55], v[46:47]
	v_cndmask_b32_e64 v101, v53, v43, s[10:11]
	v_cndmask_b32_e64 v100, v52, v42, s[10:11]
	v_cndmask_b32_e64 v103, v55, v47, s[10:11]
	v_cndmask_b32_e64 v102, v54, v46, s[10:11]
	ds_bpermute_b32 v45, v170, v97
	ds_bpermute_b32 v57, v170, v99
	ds_bpermute_b32 v46, v170, v100
	ds_bpermute_b32 v60, v170, v102
	ds_bpermute_b32 v47, v170, v101
	ds_bpermute_b32 v61, v170, v103
	v_pk_mul_f32 v[50:51], v[94:95], v[50:51]
	s_waitcnt lgkmcnt(8)
	v_pk_fma_f32 v[42:43], v[94:95], v[58:59], v[92:93]
	s_waitcnt lgkmcnt(5)
	v_pk_mul_f32 v[52:53], v[96:97], v[44:45]
	s_waitcnt lgkmcnt(4)
	v_pk_fma_f32 v[44:45], v[96:97], v[56:57], v[98:99]
	s_waitcnt lgkmcnt(1)
	v_pk_mul_f32 v[54:55], v[100:101], v[46:47]
	s_waitcnt lgkmcnt(0)
	v_pk_fma_f32 v[46:47], v[100:101], v[60:61], v[102:103]
	v_pk_mul_f32 v[0:1], v[0:1], v[112:113]
	v_pk_mul_f32 v[58:59], v[116:117], v[150:151]
	v_pk_mul_f32 v[0:1], v[0:1], v[120:121]
	ds_bpermute_b32 v56, v165, v0
	ds_bpermute_b32 v57, v165, v1
	v_cndmask_b32_e32 v59, v59, v117, vcc
	v_cndmask_b32_e32 v58, v58, v116, vcc
	v_pk_mul_f32 v[2:3], v[2:3], v[114:115]
	v_pk_mul_f32 v[4:5], v[4:5], v[124:125]
	s_waitcnt lgkmcnt(0)
	v_pk_fma_f32 v[56:57], v[116:117], v[56:57], v[0:1]
	v_pk_mul_f32 v[2:3], v[2:3], v[122:123]
	v_cndmask_b32_e32 v1, v57, v1, vcc
	v_cndmask_b32_e32 v0, v56, v0, vcc
	ds_bpermute_b32 v56, v166, v58
	ds_bpermute_b32 v57, v166, v59
	ds_bpermute_b32 v60, v166, v0
	ds_bpermute_b32 v61, v166, v1
	ds_bpermute_b32 v62, v165, v2
	ds_bpermute_b32 v63, v165, v3
	s_waitcnt lgkmcnt(4)
	v_pk_mul_f32 v[56:57], v[58:59], v[56:57]
	v_pk_mul_f32 v[4:5], v[4:5], v[128:129]
	s_waitcnt lgkmcnt(2)
	v_pk_fma_f32 v[60:61], v[58:59], v[60:61], v[0:1]
	v_cndmask_b32_e64 v57, v57, v59, s[6:7]
	v_cndmask_b32_e64 v56, v56, v58, s[6:7]
	v_cndmask_b32_e64 v1, v61, v1, s[6:7]
	v_cndmask_b32_e64 v0, v60, v0, s[6:7]
	ds_bpermute_b32 v58, v167, v56
	ds_bpermute_b32 v59, v167, v57
	ds_bpermute_b32 v60, v167, v0
	ds_bpermute_b32 v61, v167, v1
	ds_bpermute_b32 v112, v165, v4
	ds_bpermute_b32 v113, v165, v5
	s_waitcnt lgkmcnt(4)
	v_pk_mul_f32 v[58:59], v[56:57], v[58:59]
	v_pk_mul_f32 v[6:7], v[6:7], v[130:131]
	s_waitcnt lgkmcnt(2)
	v_pk_fma_f32 v[60:61], v[56:57], v[60:61], v[0:1]
	v_cndmask_b32_e64 v57, v59, v57, s[8:9]
	v_cndmask_b32_e64 v56, v58, v56, s[8:9]
	ds_bpermute_b32 v58, v168, v56
	ds_bpermute_b32 v59, v168, v57
	v_cndmask_b32_e64 v1, v61, v1, s[8:9]
	v_cndmask_b32_e64 v0, v60, v0, s[8:9]
	ds_bpermute_b32 v60, v168, v0
	ds_bpermute_b32 v61, v168, v1
	s_waitcnt lgkmcnt(2)
	v_pk_mul_f32 v[58:59], v[56:57], v[58:59]
	v_pk_mul_f32 v[6:7], v[6:7], v[134:135]
	v_cndmask_b32_e64 v105, v59, v57, s[10:11]
	v_cndmask_b32_e64 v104, v58, v56, s[10:11]
	s_waitcnt lgkmcnt(0)
	v_pk_fma_f32 v[60:61], v[56:57], v[60:61], v[0:1]
	v_pk_mul_f32 v[56:57], v[118:119], v[148:149]
	v_pk_fma_f32 v[58:59], v[118:119], v[62:63], v[2:3]
	v_cndmask_b32_e32 v57, v57, v119, vcc
	v_cndmask_b32_e32 v56, v56, v118, vcc
	v_cndmask_b32_e32 v3, v59, v3, vcc
	v_cndmask_b32_e32 v2, v58, v2, vcc
	ds_bpermute_b32 v58, v166, v56
	ds_bpermute_b32 v59, v166, v57
	ds_bpermute_b32 v62, v166, v2
	ds_bpermute_b32 v63, v166, v3
	v_cndmask_b32_e64 v107, v61, v1, s[10:11]
	v_cndmask_b32_e64 v106, v60, v0, s[10:11]
	s_waitcnt lgkmcnt(2)
	v_pk_mul_f32 v[58:59], v[56:57], v[58:59]
	ds_bpermute_b32 v0, v170, v104
	s_waitcnt lgkmcnt(1)
	v_pk_fma_f32 v[60:61], v[56:57], v[62:63], v[2:3]
	v_cndmask_b32_e64 v57, v59, v57, s[6:7]
	v_cndmask_b32_e64 v56, v58, v56, s[6:7]
	v_cndmask_b32_e64 v3, v61, v3, s[6:7]
	v_cndmask_b32_e64 v2, v60, v2, s[6:7]
	ds_bpermute_b32 v58, v167, v56
	ds_bpermute_b32 v59, v167, v57
	ds_bpermute_b32 v60, v167, v2
	ds_bpermute_b32 v61, v167, v3
	ds_bpermute_b32 v62, v170, v106
	ds_bpermute_b32 v1, v170, v105
	s_waitcnt lgkmcnt(4)
	v_pk_mul_f32 v[58:59], v[56:57], v[58:59]
	ds_bpermute_b32 v63, v170, v107
	s_waitcnt lgkmcnt(3)
	v_pk_fma_f32 v[60:61], v[56:57], v[60:61], v[2:3]
	v_cndmask_b32_e64 v59, v59, v57, s[8:9]
	v_cndmask_b32_e64 v58, v58, v56, s[8:9]
	v_cndmask_b32_e64 v3, v61, v3, s[8:9]
	v_cndmask_b32_e64 v2, v60, v2, s[8:9]
	ds_bpermute_b32 v60, v168, v58
	ds_bpermute_b32 v61, v168, v59
	ds_bpermute_b32 v108, v168, v2
	ds_bpermute_b32 v109, v168, v3
	s_waitcnt lgkmcnt(5)
	v_pk_mul_f32 v[56:57], v[104:105], v[0:1]
	s_waitcnt lgkmcnt(4)
	v_pk_fma_f32 v[0:1], v[104:105], v[62:63], v[106:107]
	s_waitcnt lgkmcnt(2)
	v_pk_mul_f32 v[60:61], v[58:59], v[60:61]
	v_pk_mul_f32 v[114:115], v[132:133], v[136:137]
	s_waitcnt lgkmcnt(0)
	v_pk_fma_f32 v[62:63], v[58:59], v[108:109], v[2:3]
	v_cndmask_b32_e64 v111, v61, v59, s[10:11]
	v_cndmask_b32_e64 v110, v60, v58, s[10:11]
	v_pk_mul_f32 v[58:59], v[126:127], v[146:147]
	v_pk_fma_f32 v[60:61], v[126:127], v[112:113], v[4:5]
	v_cndmask_b32_e32 v59, v59, v127, vcc
	v_cndmask_b32_e32 v58, v58, v126, vcc
	v_cndmask_b32_e32 v5, v61, v5, vcc
	v_cndmask_b32_e32 v4, v60, v4, vcc
	ds_bpermute_b32 v60, v166, v58
	ds_bpermute_b32 v112, v166, v4
	ds_bpermute_b32 v61, v166, v59
	ds_bpermute_b32 v113, v166, v5
	v_cndmask_b32_e64 v109, v63, v3, s[10:11]
	v_cndmask_b32_e64 v108, v62, v2, s[10:11]
	ds_bpermute_b32 v2, v170, v110
	s_waitcnt lgkmcnt(2)
	v_pk_mul_f32 v[60:61], v[58:59], v[60:61]
	s_waitcnt lgkmcnt(1)
	v_pk_fma_f32 v[62:63], v[58:59], v[112:113], v[4:5]
	v_cndmask_b32_e64 v61, v61, v59, s[6:7]
	v_cndmask_b32_e64 v60, v60, v58, s[6:7]
	v_cndmask_b32_e64 v5, v63, v5, s[6:7]
	v_cndmask_b32_e64 v4, v62, v4, s[6:7]
	ds_bpermute_b32 v3, v170, v111
	ds_bpermute_b32 v62, v167, v60
	ds_bpermute_b32 v112, v167, v4
	ds_bpermute_b32 v63, v167, v61
	ds_bpermute_b32 v113, v167, v5
	s_waitcnt lgkmcnt(4)
	v_pk_mul_f32 v[58:59], v[110:111], v[2:3]
	v_cndmask_b32_e32 v115, v115, v133, vcc
	v_cndmask_b32_e32 v114, v114, v132, vcc
	s_waitcnt lgkmcnt(1)
	v_pk_mul_f32 v[2:3], v[60:61], v[62:63]
	s_waitcnt lgkmcnt(0)
	v_pk_fma_f32 v[62:63], v[60:61], v[112:113], v[4:5]
	v_cndmask_b32_e64 v3, v3, v61, s[8:9]
	v_cndmask_b32_e64 v5, v63, v5, s[8:9]
	v_cndmask_b32_e64 v4, v62, v4, s[8:9]
	ds_bpermute_b32 v62, v165, v6
	ds_bpermute_b32 v63, v165, v7
	v_cndmask_b32_e64 v2, v2, v60, s[8:9]
	ds_bpermute_b32 v60, v168, v2
	ds_bpermute_b32 v61, v168, v3
	ds_bpermute_b32 v112, v168, v4
	s_waitcnt lgkmcnt(3)
	v_pk_fma_f32 v[62:63], v[132:133], v[62:63], v[6:7]
	ds_bpermute_b32 v113, v168, v5
	v_cndmask_b32_e32 v7, v63, v7, vcc
	v_cndmask_b32_e32 v6, v62, v6, vcc
	ds_bpermute_b32 v62, v166, v114
	ds_bpermute_b32 v116, v166, v6
	ds_bpermute_b32 v63, v166, v115
	ds_bpermute_b32 v117, v166, v7
	s_waitcnt lgkmcnt(6)
	v_pk_mul_f32 v[60:61], v[2:3], v[60:61]
	s_waitcnt lgkmcnt(4)
	v_pk_fma_f32 v[118:119], v[2:3], v[112:113], v[4:5]
	v_cndmask_b32_e64 v113, v61, v3, s[10:11]
	v_cndmask_b32_e64 v112, v60, v2, s[10:11]
	s_waitcnt lgkmcnt(1)
	v_pk_mul_f32 v[2:3], v[114:115], v[62:63]
	s_waitcnt lgkmcnt(0)
	v_pk_fma_f32 v[60:61], v[114:115], v[116:117], v[6:7]
	v_cndmask_b32_e64 v3, v3, v115, s[6:7]
	v_cndmask_b32_e64 v2, v2, v114, s[6:7]
	v_cndmask_b32_e64 v7, v61, v7, s[6:7]
	v_cndmask_b32_e64 v6, v60, v6, s[6:7]
	ds_bpermute_b32 v60, v167, v2
	ds_bpermute_b32 v62, v167, v6
	ds_bpermute_b32 v61, v167, v3
	ds_bpermute_b32 v63, v167, v7
	v_cndmask_b32_e64 v115, v119, v5, s[10:11]
	v_cndmask_b32_e64 v114, v118, v4, s[10:11]
	ds_bpermute_b32 v120, v170, v108
	s_waitcnt lgkmcnt(2)
	v_pk_mul_f32 v[60:61], v[2:3], v[60:61]
	s_waitcnt lgkmcnt(1)
	v_pk_fma_f32 v[62:63], v[2:3], v[62:63], v[6:7]
	v_cndmask_b32_e64 v3, v61, v3, s[8:9]
	v_cndmask_b32_e64 v2, v60, v2, s[8:9]
	v_cndmask_b32_e64 v7, v63, v7, s[8:9]
	v_cndmask_b32_e64 v6, v62, v6, s[8:9]
	ds_bpermute_b32 v60, v168, v2
	ds_bpermute_b32 v62, v168, v6
	ds_bpermute_b32 v61, v168, v3
	ds_bpermute_b32 v63, v168, v7
	ds_bpermute_b32 v121, v170, v109
	ds_bpermute_b32 v4, v170, v112
	ds_bpermute_b32 v122, v170, v114
	s_waitcnt lgkmcnt(4)
	v_pk_mul_f32 v[60:61], v[2:3], v[60:61]
	s_waitcnt lgkmcnt(3)
	v_pk_fma_f32 v[62:63], v[2:3], v[62:63], v[6:7]
	v_cndmask_b32_e64 v117, v61, v3, s[10:11]
	v_cndmask_b32_e64 v116, v60, v2, s[10:11]
	v_cndmask_b32_e64 v119, v63, v7, s[10:11]
	v_cndmask_b32_e64 v118, v62, v6, s[10:11]
	ds_bpermute_b32 v5, v170, v113
	ds_bpermute_b32 v123, v170, v115
	ds_bpermute_b32 v6, v170, v116
	ds_bpermute_b32 v124, v170, v118
	ds_bpermute_b32 v7, v170, v117
	ds_bpermute_b32 v125, v170, v119
	s_waitcnt lgkmcnt(8)
	v_pk_fma_f32 v[2:3], v[110:111], v[120:121], v[108:109]
	s_waitcnt lgkmcnt(5)
	v_pk_mul_f32 v[60:61], v[112:113], v[4:5]
	s_waitcnt lgkmcnt(4)
	v_pk_fma_f32 v[4:5], v[112:113], v[122:123], v[114:115]
	s_waitcnt lgkmcnt(1)
	v_pk_mul_f32 v[62:63], v[116:117], v[6:7]
	s_waitcnt lgkmcnt(0)
	v_pk_fma_f32 v[6:7], v[116:117], v[124:125], v[118:119]
	v_cmp_eq_u32_e64 s[6:7], 31, v162
	v_and_b32_e32 v122, 0xffffffc0, v160
	s_and_saveexec_b64 s[2:3], s[6:7]
	s_cbranch_execz .LBB0_906
	v_or_b32_e32 v120, v164, v122
	v_lshl_add_u32 v120, v120, 2, s89
	ds_write_b128 v120, v[8:11] offset:34816
	ds_write_b128 v120, v[12:15] offset:35840
	ds_write_b128 v120, v[20:23] offset:34848
	ds_write_b128 v120, v[16:19] offset:35872
	ds_write_b128 v120, v[28:31] offset:34880
	ds_write_b128 v120, v[24:27] offset:35904
	ds_write_b128 v120, v[36:39] offset:34912
	ds_write_b128 v120, v[32:35] offset:35936
	ds_write_b128 v120, v[48:51] offset:34944
	ds_write_b128 v120, v[40:43] offset:35968
	ds_write_b128 v120, v[52:55] offset:34976
	ds_write_b128 v120, v[44:47] offset:36000
	ds_write_b128 v120, v[56:59] offset:35008
	ds_write_b128 v120, v[0:3] offset:36032
	ds_write_b128 v120, v[60:63] offset:35040
	ds_write_b128 v120, v[4:7] offset:36064

.LBB0_935:
	s_or_b64 exec, exec, s[2:3]
	s_add_u32 s14, s8, s46
	s_addc_u32 s15, s9, s47
	s_add_u32 s74, s10, s78
	s_addc_u32 s75, s11, s79
	v_and_b32_e32 v45, 1, v66
	s_lshl_b32 s0, s42, 5
	s_and_b32 s5, s0, 64
	v_lshlrev_b32_e32 v44, 5, v45
	v_or_b32_e32 v0, s5, v44
	v_lshlrev_b32_e32 v168, 2, v0
	v_lshlrev_b32_e32 v0, 1, v0
	v_mov_b32_e32 v1, v169
	v_lshl_add_u64 v[32:33], s[30:31], 0, v[0:1]
	global_load_dwordx4 v[0:3], v168, s[74:75] offset:1040
	global_load_dwordx4 v[4:7], v168, s[74:75] offset:1024
	v_ashrrev_i32_e32 v39, 1, v66
	v_add_u32_e32 v40, s86, v39
	v_add_u32_e32 v8, s68, v39
	v_lshl_add_u64 v[34:35], s[14:15], 0, v[168:169]
	v_add_u32_e32 v41, -3, v40
	v_cmp_lt_i32_e64 s[6:7], 2, v8
	s_cmp_eq_u64 s[6:7], -1
	s_cbranch_scc0 .Lssdb_slow
	v_cmp_lt_i32_e64 s[8:9], 1, v8
	v_cmp_lt_i32_e64 s[10:11], 0, v8
	v_cmp_lt_i32_e64 s[12:13], -1, v8
	v_add_u32_e32 v42, -2, v40
	v_add_u32_e32 v43, -1, v40
	global_load_dwordx4 v[12:15], v168, s[74:75] offset:1056
	global_load_dwordx4 v[8:11], v168, s[74:75] offset:1072
	global_load_dwordx4 v[20:23], v168, s[74:75] offset:1088
	global_load_dwordx4 v[16:19], v168, s[74:75] offset:1104
	global_load_dwordx4 v[28:31], v168, s[74:75] offset:1120
	global_load_dwordx4 v[24:27], v168, s[74:75] offset:1136
	v_mad_i64_i32 v[48:49], s[0:1], v41, s93, v[32:33]
	v_mad_i64_i32 v[50:51], s[0:1], v42, s93, v[32:33]
	v_mad_i64_i32 v[52:53], s[0:1], v43, s93, v[32:33]
	v_mad_i64_i32 v[54:55], s[0:1], v40, s93, v[32:33]
	s_mov_b64 s[0:1], 0x1000
	v_lshl_add_u64 v[56:57], v[34:35], 0, s[0:1]
	global_load_dwordx4 v[92:95], v[48:49], off offset:2048
	global_load_dwordx4 v[96:99], v[48:49], off offset:2064
	global_load_dwordx4 v[100:103], v[48:49], off offset:2080
	global_load_dwordx4 v[104:107], v[48:49], off offset:2096
	global_load_dwordx4 v[108:111], v[34:35], off offset:1024
	global_load_dwordx4 v[112:115], v[34:35], off offset:1040
	global_load_dwordx4 v[116:119], v[34:35], off offset:1056
	global_load_dwordx4 v[120:123], v[34:35], off offset:1072
	global_load_dwordx4 v[124:127], v[34:35], off offset:1088
	global_load_dwordx4 v[128:131], v[34:35], off offset:1104
	global_load_dwordx4 v[132:135], v[34:35], off offset:1120
	global_load_dwordx4 v[136:139], v[34:35], off offset:1136
	s_waitcnt vmcnt(0)
	v_lshlrev_b32_e32 v140, 16, v92
	v_and_b32_e32 v141, 0xffff0000, v92
	v_pk_fma_f32 v[4:5], v[108:109], v[140:141], v[4:5]
	v_lshlrev_b32_e32 v140, 16, v93
	v_and_b32_e32 v141, 0xffff0000, v93
	v_pk_fma_f32 v[6:7], v[110:111], v[140:141], v[6:7]
	v_lshlrev_b32_e32 v140, 16, v94
	v_and_b32_e32 v141, 0xffff0000, v94
	v_pk_fma_f32 v[0:1], v[112:113], v[140:141], v[0:1]
	v_lshlrev_b32_e32 v140, 16, v95
	v_and_b32_e32 v141, 0xffff0000, v95
	v_pk_fma_f32 v[2:3], v[114:115], v[140:141], v[2:3]
	v_lshlrev_b32_e32 v140, 16, v96
	v_and_b32_e32 v141, 0xffff0000, v96
	v_pk_fma_f32 v[12:13], v[116:117], v[140:141], v[12:13]
	v_lshlrev_b32_e32 v140, 16, v97
	v_and_b32_e32 v141, 0xffff0000, v97
	v_pk_fma_f32 v[14:15], v[118:119], v[140:141], v[14:15]
	v_lshlrev_b32_e32 v140, 16, v98
	v_and_b32_e32 v141, 0xffff0000, v98
	v_pk_fma_f32 v[8:9], v[120:121], v[140:141], v[8:9]
	v_lshlrev_b32_e32 v140, 16, v99
	v_and_b32_e32 v141, 0xffff0000, v99
	v_pk_fma_f32 v[10:11], v[122:123], v[140:141], v[10:11]
	v_lshlrev_b32_e32 v140, 16, v100
	v_and_b32_e32 v141, 0xffff0000, v100
	v_pk_fma_f32 v[20:21], v[124:125], v[140:141], v[20:21]
	v_lshlrev_b32_e32 v140, 16, v101
	v_and_b32_e32 v141, 0xffff0000, v101
	v_pk_fma_f32 v[22:23], v[126:127], v[140:141], v[22:23]
	v_lshlrev_b32_e32 v140, 16, v102
	v_and_b32_e32 v141, 0xffff0000, v102
	v_pk_fma_f32 v[16:17], v[128:129], v[140:141], v[16:17]
	v_lshlrev_b32_e32 v140, 16, v103
	v_and_b32_e32 v141, 0xffff0000, v103
	v_pk_fma_f32 v[18:19], v[130:131], v[140:141], v[18:19]
	v_lshlrev_b32_e32 v140, 16, v104
	v_and_b32_e32 v141, 0xffff0000, v104
	v_pk_fma_f32 v[28:29], v[132:133], v[140:141], v[28:29]
	v_lshlrev_b32_e32 v140, 16, v105
	v_and_b32_e32 v141, 0xffff0000, v105
	v_pk_fma_f32 v[30:31], v[134:135], v[140:141], v[30:31]
	v_lshlrev_b32_e32 v140, 16, v106
	v_and_b32_e32 v141, 0xffff0000, v106
	v_pk_fma_f32 v[24:25], v[136:137], v[140:141], v[24:25]
	v_lshlrev_b32_e32 v140, 16, v107
	v_and_b32_e32 v141, 0xffff0000, v107
	v_pk_fma_f32 v[26:27], v[138:139], v[140:141], v[26:27]
	global_load_dwordx4 v[92:95], v[50:51], off offset:2048
	global_load_dwordx4 v[96:99], v[50:51], off offset:2064
	global_load_dwordx4 v[100:103], v[50:51], off offset:2080
	global_load_dwordx4 v[104:107], v[50:51], off offset:2096
	global_load_dwordx4 v[108:111], v[34:35], off offset:3072
	global_load_dwordx4 v[112:115], v[34:35], off offset:3088
	global_load_dwordx4 v[116:119], v[34:35], off offset:3104
	global_load_dwordx4 v[120:123], v[34:35], off offset:3120
	global_load_dwordx4 v[124:127], v[34:35], off offset:3136
	global_load_dwordx4 v[128:131], v[34:35], off offset:3152
	global_load_dwordx4 v[132:135], v[34:35], off offset:3168
	global_load_dwordx4 v[136:139], v[34:35], off offset:3184
	s_waitcnt vmcnt(0)
	v_lshlrev_b32_e32 v140, 16, v92
	v_and_b32_e32 v141, 0xffff0000, v92
	v_pk_fma_f32 v[4:5], v[108:109], v[140:141], v[4:5]
	v_lshlrev_b32_e32 v140, 16, v93
	v_and_b32_e32 v141, 0xffff0000, v93
	v_pk_fma_f32 v[6:7], v[110:111], v[140:141], v[6:7]
	v_lshlrev_b32_e32 v140, 16, v94
	v_and_b32_e32 v141, 0xffff0000, v94
	v_pk_fma_f32 v[0:1], v[112:113], v[140:141], v[0:1]
	v_lshlrev_b32_e32 v140, 16, v95
	v_and_b32_e32 v141, 0xffff0000, v95
	v_pk_fma_f32 v[2:3], v[114:115], v[140:141], v[2:3]
	v_lshlrev_b32_e32 v140, 16, v96
	v_and_b32_e32 v141, 0xffff0000, v96
	v_pk_fma_f32 v[12:13], v[116:117], v[140:141], v[12:13]
	v_lshlrev_b32_e32 v140, 16, v97
	v_and_b32_e32 v141, 0xffff0000, v97
	v_pk_fma_f32 v[14:15], v[118:119], v[140:141], v[14:15]
	v_lshlrev_b32_e32 v140, 16, v98
	v_and_b32_e32 v141, 0xffff0000, v98
	v_pk_fma_f32 v[8:9], v[120:121], v[140:141], v[8:9]
	v_lshlrev_b32_e32 v140, 16, v99
	v_and_b32_e32 v141, 0xffff0000, v99
	v_pk_fma_f32 v[10:11], v[122:123], v[140:141], v[10:11]
	v_lshlrev_b32_e32 v140, 16, v100
	v_and_b32_e32 v141, 0xffff0000, v100
	v_pk_fma_f32 v[20:21], v[124:125], v[140:141], v[20:21]
	v_lshlrev_b32_e32 v140, 16, v101
	v_and_b32_e32 v141, 0xffff0000, v101
	v_pk_fma_f32 v[22:23], v[126:127], v[140:141], v[22:23]
	v_lshlrev_b32_e32 v140, 16, v102
	v_and_b32_e32 v141, 0xffff0000, v102
	v_pk_fma_f32 v[16:17], v[128:129], v[140:141], v[16:17]
	v_lshlrev_b32_e32 v140, 16, v103
	v_and_b32_e32 v141, 0xffff0000, v103
	v_pk_fma_f32 v[18:19], v[130:131], v[140:141], v[18:19]
	v_lshlrev_b32_e32 v140, 16, v104
	v_and_b32_e32 v141, 0xffff0000, v104
	v_pk_fma_f32 v[28:29], v[132:133], v[140:141], v[28:29]
	v_lshlrev_b32_e32 v140, 16, v105
	v_and_b32_e32 v141, 0xffff0000, v105
	v_pk_fma_f32 v[30:31], v[134:135], v[140:141], v[30:31]
	v_lshlrev_b32_e32 v140, 16, v106
	v_and_b32_e32 v141, 0xffff0000, v106
	v_pk_fma_f32 v[24:25], v[136:137], v[140:141], v[24:25]
	v_lshlrev_b32_e32 v140, 16, v107
	v_and_b32_e32 v141, 0xffff0000, v107
	v_pk_fma_f32 v[26:27], v[138:139], v[140:141], v[26:27]
	global_load_dwordx4 v[92:95], v[52:53], off offset:2048
	global_load_dwordx4 v[96:99], v[52:53], off offset:2064
	global_load_dwordx4 v[100:103], v[52:53], off offset:2080
	global_load_dwordx4 v[104:107], v[52:53], off offset:2096
	global_load_dwordx4 v[108:111], v[56:57], off offset:1024
	global_load_dwordx4 v[112:115], v[56:57], off offset:1040
	global_load_dwordx4 v[116:119], v[56:57], off offset:1056
	global_load_dwordx4 v[120:123], v[56:57], off offset:1072
	global_load_dwordx4 v[124:127], v[56:57], off offset:1088
	global_load_dwordx4 v[128:131], v[56:57], off offset:1104
	global_load_dwordx4 v[132:135], v[56:57], off offset:1120
	global_load_dwordx4 v[136:139], v[56:57], off offset:1136
	s_waitcnt vmcnt(0)
	v_lshlrev_b32_e32 v140, 16, v92
	v_and_b32_e32 v141, 0xffff0000, v92
	v_pk_fma_f32 v[4:5], v[108:109], v[140:141], v[4:5]
	v_lshlrev_b32_e32 v140, 16, v93
	v_and_b32_e32 v141, 0xffff0000, v93
	v_pk_fma_f32 v[6:7], v[110:111], v[140:141], v[6:7]
	v_lshlrev_b32_e32 v140, 16, v94
	v_and_b32_e32 v141, 0xffff0000, v94
	v_pk_fma_f32 v[0:1], v[112:113], v[140:141], v[0:1]
	v_lshlrev_b32_e32 v140, 16, v95
	v_and_b32_e32 v141, 0xffff0000, v95
	v_pk_fma_f32 v[2:3], v[114:115], v[140:141], v[2:3]
	v_lshlrev_b32_e32 v140, 16, v96
	v_and_b32_e32 v141, 0xffff0000, v96
	v_pk_fma_f32 v[12:13], v[116:117], v[140:141], v[12:13]
	v_lshlrev_b32_e32 v140, 16, v97
	v_and_b32_e32 v141, 0xffff0000, v97
	v_pk_fma_f32 v[14:15], v[118:119], v[140:141], v[14:15]
	v_lshlrev_b32_e32 v140, 16, v98
	v_and_b32_e32 v141, 0xffff0000, v98
	v_pk_fma_f32 v[8:9], v[120:121], v[140:141], v[8:9]
	v_lshlrev_b32_e32 v140, 16, v99
	v_and_b32_e32 v141, 0xffff0000, v99
	v_pk_fma_f32 v[10:11], v[122:123], v[140:141], v[10:11]
	v_lshlrev_b32_e32 v140, 16, v100
	v_and_b32_e32 v141, 0xffff0000, v100
	v_pk_fma_f32 v[20:21], v[124:125], v[140:141], v[20:21]
	v_lshlrev_b32_e32 v140, 16, v101
	v_and_b32_e32 v141, 0xffff0000, v101
	v_pk_fma_f32 v[22:23], v[126:127], v[140:141], v[22:23]
	v_lshlrev_b32_e32 v140, 16, v102
	v_and_b32_e32 v141, 0xffff0000, v102
	v_pk_fma_f32 v[16:17], v[128:129], v[140:141], v[16:17]
	v_lshlrev_b32_e32 v140, 16, v103
	v_and_b32_e32 v141, 0xffff0000, v103
	v_pk_fma_f32 v[18:19], v[130:131], v[140:141], v[18:19]
	v_lshlrev_b32_e32 v140, 16, v104
	v_and_b32_e32 v141, 0xffff0000, v104
	v_pk_fma_f32 v[28:29], v[132:133], v[140:141], v[28:29]
	v_lshlrev_b32_e32 v140, 16, v105
	v_and_b32_e32 v141, 0xffff0000, v105
	v_pk_fma_f32 v[30:31], v[134:135], v[140:141], v[30:31]
	v_lshlrev_b32_e32 v140, 16, v106
	v_and_b32_e32 v141, 0xffff0000, v106
	v_pk_fma_f32 v[24:25], v[136:137], v[140:141], v[24:25]
	v_lshlrev_b32_e32 v140, 16, v107
	v_and_b32_e32 v141, 0xffff0000, v107
	v_pk_fma_f32 v[26:27], v[138:139], v[140:141], v[26:27]
	global_load_dwordx4 v[92:95], v[54:55], off offset:2048
	global_load_dwordx4 v[96:99], v[54:55], off offset:2064
	global_load_dwordx4 v[100:103], v[54:55], off offset:2080
	global_load_dwordx4 v[104:107], v[54:55], off offset:2096
	global_load_dwordx4 v[108:111], v[56:57], off offset:3072
	global_load_dwordx4 v[112:115], v[56:57], off offset:3088
	global_load_dwordx4 v[116:119], v[56:57], off offset:3104
	global_load_dwordx4 v[120:123], v[56:57], off offset:3120
	global_load_dwordx4 v[124:127], v[56:57], off offset:3136
	global_load_dwordx4 v[128:131], v[56:57], off offset:3152
	global_load_dwordx4 v[132:135], v[56:57], off offset:3168
	global_load_dwordx4 v[136:139], v[56:57], off offset:3184
	s_waitcnt vmcnt(0)
	v_lshlrev_b32_e32 v140, 16, v92
	v_and_b32_e32 v141, 0xffff0000, v92
	v_pk_fma_f32 v[4:5], v[108:109], v[140:141], v[4:5]
	v_lshlrev_b32_e32 v140, 16, v93
	v_and_b32_e32 v141, 0xffff0000, v93
	v_pk_fma_f32 v[6:7], v[110:111], v[140:141], v[6:7]
	v_lshlrev_b32_e32 v140, 16, v94
	v_and_b32_e32 v141, 0xffff0000, v94
	v_pk_fma_f32 v[0:1], v[112:113], v[140:141], v[0:1]
	v_lshlrev_b32_e32 v140, 16, v95
	v_and_b32_e32 v141, 0xffff0000, v95
	v_pk_fma_f32 v[2:3], v[114:115], v[140:141], v[2:3]
	v_lshlrev_b32_e32 v140, 16, v96
	v_and_b32_e32 v141, 0xffff0000, v96
	v_pk_fma_f32 v[12:13], v[116:117], v[140:141], v[12:13]
	v_lshlrev_b32_e32 v140, 16, v97
	v_and_b32_e32 v141, 0xffff0000, v97
	v_pk_fma_f32 v[14:15], v[118:119], v[140:141], v[14:15]
	v_lshlrev_b32_e32 v140, 16, v98
	v_and_b32_e32 v141, 0xffff0000, v98
	v_pk_fma_f32 v[8:9], v[120:121], v[140:141], v[8:9]
	v_lshlrev_b32_e32 v140, 16, v99
	v_and_b32_e32 v141, 0xffff0000, v99
	v_pk_fma_f32 v[10:11], v[122:123], v[140:141], v[10:11]
	v_lshlrev_b32_e32 v140, 16, v100
	v_and_b32_e32 v141, 0xffff0000, v100
	v_pk_fma_f32 v[20:21], v[124:125], v[140:141], v[20:21]
	v_lshlrev_b32_e32 v140, 16, v101
	v_and_b32_e32 v141, 0xffff0000, v101
	v_pk_fma_f32 v[22:23], v[126:127], v[140:141], v[22:23]
	v_lshlrev_b32_e32 v140, 16, v102
	v_and_b32_e32 v141, 0xffff0000, v102
	v_pk_fma_f32 v[16:17], v[128:129], v[140:141], v[16:17]
	v_lshlrev_b32_e32 v140, 16, v103
	v_and_b32_e32 v141, 0xffff0000, v103
	v_pk_fma_f32 v[18:19], v[130:131], v[140:141], v[18:19]
	v_lshlrev_b32_e32 v140, 16, v104
	v_and_b32_e32 v141, 0xffff0000, v104
	v_pk_fma_f32 v[28:29], v[132:133], v[140:141], v[28:29]
	v_lshlrev_b32_e32 v140, 16, v105
	v_and_b32_e32 v141, 0xffff0000, v105
	v_pk_fma_f32 v[30:31], v[134:135], v[140:141], v[30:31]
	v_lshlrev_b32_e32 v140, 16, v106
	v_and_b32_e32 v141, 0xffff0000, v106
	v_pk_fma_f32 v[24:25], v[136:137], v[140:141], v[24:25]
	v_lshlrev_b32_e32 v140, 16, v107
	v_and_b32_e32 v141, 0xffff0000, v107
	v_pk_fma_f32 v[26:27], v[138:139], v[140:141], v[26:27]
	s_branch .Lssdb_tail
.Lssdb_slow:
	s_and_saveexec_b64 s[2:3], s[6:7]
	s_cbranch_execz .LBB0_937
	v_mad_i64_i32 v[10:11], s[0:1], v41, s93, v[32:33]
	global_load_dwordx4 v[10:13], v[10:11], off offset:2048
	s_nop 0
	global_load_dwordx4 v[14:17], v[34:35], off offset:1040
	global_load_dwordx4 v[18:21], v[34:35], off offset:1024
	s_waitcnt vmcnt(2)
	v_lshlrev_b32_e32 v22, 16, v10
	v_and_b32_e32 v23, 0xffff0000, v10
	v_lshlrev_b32_e32 v10, 16, v11
	v_and_b32_e32 v11, 0xffff0000, v11
	s_waitcnt vmcnt(0)
	v_pk_fma_f32 v[6:7], v[20:21], v[10:11], v[6:7]
	v_lshlrev_b32_e32 v10, 16, v12
	v_and_b32_e32 v11, 0xffff0000, v12
	v_pk_fma_f32 v[0:1], v[14:15], v[10:11], v[0:1]
	v_lshlrev_b32_e32 v10, 16, v13
	v_and_b32_e32 v11, 0xffff0000, v13
	v_pk_fma_f32 v[4:5], v[18:19], v[22:23], v[4:5]
	v_pk_fma_f32 v[2:3], v[16:17], v[10:11], v[2:3]

.Lssdb_tail:
	s_waitcnt vmcnt(2)
	v_mul_f32_e32 v32, 0xbfb8aa3b, v20
	v_exp_f32_e32 v32, v32
	s_lshl_b32 s33, s42, 6
	v_add_f32_e32 v32, 1.0, v32
	v_rcp_f32_e32 v32, v32
	s_nop 0
	v_mul_f32_e32 v20, v20, v32
	v_mul_f32_e32 v32, 0xbfb8aa3b, v21
	v_exp_f32_e32 v32, v32
	s_nop 0
	v_add_f32_e32 v32, 1.0, v32
	v_rcp_f32_e32 v32, v32
	s_nop 0
	v_mul_f32_e32 v21, v21, v32
	v_mul_f32_e32 v32, 0xbfb8aa3b, v22
	v_exp_f32_e32 v32, v32
	s_nop 0
	v_add_f32_e32 v32, 1.0, v32
	v_rcp_f32_e32 v32, v32
	s_nop 0
	v_mul_f32_e32 v22, v22, v32
	v_mul_f32_e32 v32, 0xbfb8aa3b, v23
	v_exp_f32_e32 v32, v32
	s_nop 0
	v_add_f32_e32 v32, 1.0, v32
	v_rcp_f32_e32 v32, v32
	s_nop 0
	v_mul_f32_e32 v23, v23, v32
	v_mul_f32_e32 v32, 0xbfb8aa3b, v16
	v_exp_f32_e32 v32, v32
	s_nop 0
	v_add_f32_e32 v32, 1.0, v32
	v_rcp_f32_e32 v32, v32
	s_nop 0
	v_mul_f32_e32 v16, v16, v32
	v_mul_f32_e32 v32, 0xbfb8aa3b, v17
	v_exp_f32_e32 v32, v32
	s_nop 0
	v_add_f32_e32 v32, 1.0, v32
	v_rcp_f32_e32 v32, v32
	s_nop 0
	v_mul_f32_e32 v17, v17, v32
	v_mul_f32_e32 v32, 0xbfb8aa3b, v18
	v_exp_f32_e32 v32, v32
	s_nop 0
	v_add_f32_e32 v32, 1.0, v32
	v_rcp_f32_e32 v32, v32
	s_nop 0
	v_mul_f32_e32 v18, v18, v32
	v_mul_f32_e32 v32, 0xbfb8aa3b, v19
	v_exp_f32_e32 v32, v32
	s_nop 0
	v_add_f32_e32 v32, 1.0, v32
	v_rcp_f32_e32 v32, v32
	s_nop 0
	v_mul_f32_e32 v19, v19, v32
	v_mul_f32_e32 v32, 0xbfb8aa3b, v12
	v_exp_f32_e32 v32, v32
	s_nop 0
	v_add_f32_e32 v32, 1.0, v32
	v_rcp_f32_e32 v32, v32
	s_nop 0
	v_mul_f32_e32 v12, v12, v32
	v_mul_f32_e32 v32, 0xbfb8aa3b, v13
	v_exp_f32_e32 v32, v32
	s_nop 0
	v_add_f32_e32 v32, 1.0, v32
	v_rcp_f32_e32 v32, v32
	s_nop 0
	v_mul_f32_e32 v13, v13, v32
	v_mul_f32_e32 v32, 0xbfb8aa3b, v14
	v_exp_f32_e32 v32, v32
	s_nop 0
	v_add_f32_e32 v32, 1.0, v32
	v_rcp_f32_e32 v32, v32
	s_nop 0
	v_mul_f32_e32 v14, v14, v32
	v_mul_f32_e32 v32, 0xbfb8aa3b, v15
	v_exp_f32_e32 v32, v32
	s_nop 0
	v_add_f32_e32 v32, 1.0, v32
	v_rcp_f32_e32 v32, v32
	s_nop 0
	v_mul_f32_e32 v15, v15, v32
	v_mul_f32_e32 v32, 0xbfb8aa3b, v8
	v_exp_f32_e32 v32, v32
	s_nop 0
	v_add_f32_e32 v32, 1.0, v32
	v_rcp_f32_e32 v32, v32
	s_nop 0
	v_mul_f32_e32 v8, v8, v32
	v_mul_f32_e32 v32, 0xbfb8aa3b, v9
	v_exp_f32_e32 v32, v32
	s_nop 0
	v_add_f32_e32 v32, 1.0, v32
	v_rcp_f32_e32 v32, v32
	s_nop 0
	v_mul_f32_e32 v9, v9, v32
	v_mul_f32_e32 v32, 0xbfb8aa3b, v10
	v_exp_f32_e32 v32, v32
	s_nop 0
	v_add_f32_e32 v32, 1.0, v32
	v_rcp_f32_e32 v32, v32
	s_nop 0
	v_mul_f32_e32 v10, v10, v32
	v_mul_f32_e32 v32, 0xbfb8aa3b, v11
	v_exp_f32_e32 v32, v32
	s_nop 0
	v_add_f32_e32 v32, 1.0, v32
	v_rcp_f32_e32 v32, v32
	s_nop 0
	v_mul_f32_e32 v11, v11, v32
	v_mul_f32_e32 v32, 0xbfb8aa3b, v4
	v_exp_f32_e32 v32, v32
	s_nop 0
	v_add_f32_e32 v32, 1.0, v32
	v_rcp_f32_e32 v32, v32
	s_nop 0
	v_mul_f32_e32 v4, v4, v32
	v_mul_f32_e32 v32, 0xbfb8aa3b, v5
	v_exp_f32_e32 v32, v32
	s_nop 0
	v_add_f32_e32 v32, 1.0, v32
	v_rcp_f32_e32 v32, v32
	s_nop 0
	v_mul_f32_e32 v5, v5, v32
	v_mul_f32_e32 v32, 0xbfb8aa3b, v6
	v_exp_f32_e32 v32, v32
	s_nop 0
	v_add_f32_e32 v32, 1.0, v32
	v_rcp_f32_e32 v32, v32
	s_nop 0
	v_mul_f32_e32 v6, v6, v32
	v_mul_f32_e32 v32, 0xbfb8aa3b, v7
	v_exp_f32_e32 v32, v32
	s_nop 0
	v_add_f32_e32 v32, 1.0, v32
	v_rcp_f32_e32 v32, v32
	s_nop 0
	v_mul_f32_e32 v7, v7, v32
	v_mul_f32_e32 v32, 0xbfb8aa3b, v0
	v_exp_f32_e32 v32, v32
	s_nop 0
	v_add_f32_e32 v32, 1.0, v32
	v_rcp_f32_e32 v32, v32
	s_nop 0
	v_mul_f32_e32 v32, v0, v32
	v_mul_f32_e32 v0, 0xbfb8aa3b, v1
	v_exp_f32_e32 v0, v0
	s_nop 0
	v_add_f32_e32 v0, 1.0, v0
	v_rcp_f32_e32 v0, v0
	s_nop 0
	v_mul_f32_e32 v33, v1, v0
	v_mul_f32_e32 v0, 0xbfb8aa3b, v2
	v_exp_f32_e32 v0, v0
	v_lshlrev_b32_e32 v1, 6, v39
	v_add_f32_e32 v0, 1.0, v0
	v_rcp_f32_e32 v0, v0
	s_nop 0
	v_mul_f32_e32 v34, v2, v0
	v_mul_f32_e32 v0, 0xbfb8aa3b, v3
	v_exp_f32_e32 v0, v0
	v_cvt_pk_bf16_f32 v2, v32, v33
	v_add_f32_e32 v0, 1.0, v0
	v_rcp_f32_e32 v0, v0
	s_nop 0
	v_mul_f32_e32 v3, v3, v0
	s_waitcnt vmcnt(0)
	v_mul_f32_e32 v0, 0xbfb8aa3b, v28
	v_exp_f32_e32 v0, v0
	v_cvt_pk_bf16_f32 v3, v34, v3
	v_add_f32_e32 v0, 1.0, v0
	v_rcp_f32_e32 v0, v0
	s_nop 0
	v_mul_f32_e32 v28, v28, v0
	v_mul_f32_e32 v0, 0xbfb8aa3b, v29
	v_exp_f32_e32 v0, v0
	s_nop 0
	v_add_f32_e32 v0, 1.0, v0
	v_rcp_f32_e32 v0, v0
	s_nop 0
	v_mul_f32_e32 v29, v29, v0
	v_mul_f32_e32 v0, 0xbfb8aa3b, v30
	v_exp_f32_e32 v0, v0
	s_nop 0
	v_add_f32_e32 v0, 1.0, v0
	v_rcp_f32_e32 v0, v0
	s_nop 0
	v_mul_f32_e32 v30, v30, v0
	v_mul_f32_e32 v0, 0xbfb8aa3b, v31
	v_exp_f32_e32 v0, v0
	s_nop 0
	v_add_f32_e32 v0, 1.0, v0
	v_rcp_f32_e32 v0, v0
	s_nop 0
	v_mul_f32_e32 v31, v31, v0
	v_mul_f32_e32 v0, 0xbfb8aa3b, v24
	v_exp_f32_e32 v0, v0
	s_nop 0
	v_add_f32_e32 v0, 1.0, v0
	v_rcp_f32_e32 v0, v0
	s_nop 0
	v_mul_f32_e32 v24, v24, v0
	v_mul_f32_e32 v0, 0xbfb8aa3b, v25
	v_exp_f32_e32 v0, v0
	s_nop 0
	v_add_f32_e32 v0, 1.0, v0
	v_rcp_f32_e32 v0, v0
	s_nop 0
	v_mul_f32_e32 v25, v25, v0
	v_mul_f32_e32 v0, 0xbfb8aa3b, v26
	v_exp_f32_e32 v0, v0
	s_nop 0
	v_add_f32_e32 v0, 1.0, v0
	v_rcp_f32_e32 v0, v0
	s_nop 0
	v_mul_f32_e32 v26, v26, v0
	v_mul_f32_e32 v0, 0xbfb8aa3b, v27
	v_exp_f32_e32 v0, v0
	s_nop 0
	v_add_f32_e32 v0, 1.0, v0
	v_rcp_f32_e32 v0, v0
	s_nop 0
	v_mul_f32_e32 v27, v27, v0
	v_lshl_add_u32 v0, v45, 13, s89
	v_add_u32_e32 v36, v0, v1
	v_cvt_pk_bf16_f32 v0, v4, v5
	v_cvt_pk_bf16_f32 v1, v6, v7
	ds_write_b128 v36, v[0:3]
	v_cvt_pk_bf16_f32 v0, v12, v13
	v_cvt_pk_bf16_f32 v1, v14, v15
	v_cvt_pk_bf16_f32 v2, v8, v9
	v_cvt_pk_bf16_f32 v3, v10, v11
	ds_write_b128 v36, v[0:3] offset:16
	v_cvt_pk_bf16_f32 v0, v20, v21
	v_cvt_pk_bf16_f32 v1, v22, v23
	v_cvt_pk_bf16_f32 v2, v16, v17
	v_cvt_pk_bf16_f32 v3, v18, v19
	ds_write_b128 v36, v[0:3] offset:32
	v_cvt_pk_bf16_f32 v0, v28, v29
	v_cvt_pk_bf16_f32 v1, v30, v31
	v_cvt_pk_bf16_f32 v2, v24, v25
	v_cvt_pk_bf16_f32 v3, v26, v27
	ds_write_b128 v36, v[0:3] offset:48
	v_or_b32_e32 v0, s33, v44
	v_lshlrev_b32_e32 v168, 2, v0
	v_lshlrev_b32_e32 v0, 1, v0
	v_mov_b32_e32 v1, v169
	v_lshl_add_u64 v[34:35], s[30:31], 0, v[0:1]
	global_load_dwordx4 v[0:3], v168, s[74:75] offset:16
	global_load_dwordx4 v[4:7], v168, s[74:75]
	v_lshl_add_u64 v[32:33], s[14:15], 0, v[168:169]
	s_and_saveexec_b64 s[2:3], s[6:7]
	s_cbranch_execnz .LBB0_1036
	s_or_b64 exec, exec, s[2:3]
	s_and_saveexec_b64 s[2:3], s[8:9]
	s_cbranch_execnz .LBB0_1037
